# nt policy also on the mixer phase's streaming loads and stores (GLA/SGU Z reads, OX/MIX writes)
# baseline (speedup 1.0000x reference)
; #define SGU_LOAD(ch) do { _Pragma("unroll") for (int i = 0; i < 4; ++i) pv[i] = *(const u32x4*)(Z + (size_t)((ch) * 128 + lrow + 32 * i) * ZW + ZSV + g * 128 + cs); } while (0)
; PHASE_FN void sgu_block(const Params& p, unsigned char* lds, int l, int g, int ch0, int nch) {
;     ...
;     const bf16_t* __restrict__ wsb = (const bf16_t*)(ws + WS_WSB) + (size_t)(l * 4 + g) * 128 * 128;
;     bf16_t* wl = (bf16_t*)(lds + L_SW);
;     const int lrow = tid >> 4, cs = (tid & 15) * 8;
; #pragma unroll
;     for (int i = 0; i < 4; ++i) *(u32x4*)(wl + (lrow + 32 * i) * SP + cs) = *(const u32x4*)(wsb + (size_t)(lrow + 32 * i) * 128 + cs);
;     const float* ngp = p.sgu_norm_g + (size_t)l * 512 + g * 128 + cs; const f32x4 g0 = *(const f32x4*)ngp, g1 = *(const f32x4*)(ngp + 4);
;     float bs[8];
; #pragma unroll
;     for (int pb = 0; pb < 8; ++pb) bs[pb] = p.b_s[(size_t)l * 512 + g * 128 + 16 * pb + lr];
;     const int ocol = g * 128 + 16 * wid + 4 * q4;
;     u32x4 pv[4];
;     ...
;     SGU_LOAD(ch0);
.LBB0_252:
	v_mov_b32_e32 v6, v206
	s_lshl_b32 s10, s9, 15
	s_add_i32 s10, s10, s4
	v_lshlrev_b32_e32 v0, 3, v6
	s_add_u32 s10, s91, s10
	v_readlane_b32 s11, v248, 34
	v_ashrrev_i32_e32 v24, 4, v6
	v_and_b32_e32 v40, 0x78, v0
	s_addc_u32 s11, s11, 0
	v_lshlrev_b32_e32 v152, 1, v40
	v_ashrrev_i32_e32 v25, 31, v24
	v_lshl_add_u64 v[0:1], s[10:11], 0, v[152:153]
	v_lshlrev_b64 v[2:3], 8, v[24:25]
	v_lshl_add_u64 v[4:5], v[0:1], 0, v[2:3]
	global_load_dwordx4 v[0:3], v[4:5], off nt
	s_movk_i32 s10, 0x110
	v_mul_lo_u32 v41, v24, s10
	v_add3_u32 v7, 0, v152, v41
	s_movk_i32 s10, 0x4000
	s_lshl_b32 s76, s9, 7
	v_and_b32_e32 v76, 15, v6
	v_lshlrev_b32_e32 v8, 2, v76
	v_readfirstlane_b32 s14, v6
	v_bfe_u32 v28, v6, 4, 2
	v_mov_b64_e32 v[20:21], s[60:61]
	v_and_b32_e32 v27, 64, v209
	v_xor_b32_e32 v25, 1, v209
	v_add_u32_e32 v27, 64, v27
	v_mul_u32_u24_e32 v89, 0x880, v28
	v_add_u32_e32 v90, s25, v24
	v_add_u32_e32 v91, s25, v76
	s_waitcnt vmcnt(0)
	ds_write_b128 v7, v[0:3]
	v_add_co_u32_e32 v0, vcc, s35, v4
	s_nop 1
	v_addc_co_u32_e32 v1, vcc, 0, v5, vcc
	global_load_dwordx4 v[0:3], v[0:1], off nt
	s_waitcnt vmcnt(0)
	ds_write_b128 v7, v[0:3] offset:8704
	v_add_co_u32_e32 v0, vcc, s10, v4
	s_movk_i32 s10, 0x6000
	s_nop 0
	v_addc_co_u32_e32 v1, vcc, 0, v5, vcc
	global_load_dwordx4 v[0:3], v[0:1], off nt
	s_waitcnt vmcnt(0)
	ds_write_b128 v7, v[0:3] offset:17408
	v_add_co_u32_e32 v0, vcc, s10, v4
	s_lshl_b64 s[10:11], s[76:77], 2
	s_nop 0
	v_addc_co_u32_e32 v1, vcc, 0, v5, vcc
	global_load_dwordx4 v[0:3], v[0:1], off nt
	s_add_u32 s12, s5, s10
	s_addc_u32 s13, s6, s11
	s_add_u32 s10, s7, s10
	v_lshlrev_b32_e32 v4, 2, v40
	s_addc_u32 s11, s8, s11
	s_waitcnt vmcnt(0)
	ds_write_b128 v7, v[0:3] offset:26112
	global_load_dwordx4 v[0:3], v4, s[12:13] nt
	s_nop 0
	global_load_dwordx4 v[4:7], v4, s[12:13] offset:16 nt
	s_nop 0
	global_load_dword v77, v8, s[10:11]
	global_load_dword v78, v8, s[10:11] offset:64
	global_load_dword v79, v8, s[10:11] offset:128
	global_load_dword v80, v8, s[10:11] offset:192
	global_load_dword v81, v8, s[10:11] offset:256
	global_load_dword v82, v8, s[10:11] offset:320
	global_load_dword v83, v8, s[10:11] offset:384
	global_load_dword v84, v8, s[10:11] offset:448
	v_readlane_b32 s11, v247, 35
	s_ashr_i32 s10, s14, 2
	s_and_b32 s10, s10, -16
	v_add_u32_e32 v22, s11, v24
	v_mad_i64_i32 v[8:9], s[12:13], v22, s1, v[20:21]
	s_lshl_b32 s12, s9, 8
	s_mov_b32 s13, s77
	v_lshl_add_u64 v[8:9], v[8:9], 0, s[12:13]
	v_add_u32_e32 v12, 32, v22
	v_lshl_add_u64 v[8:9], v[8:9], 0, v[152:153]
	s_movk_i32 s11, 0x1000
	v_mad_i64_i32 v[12:13], s[14:15], v12, s1, v[20:21]
	v_add_co_u32_e32 v8, vcc, s11, v8
	v_lshl_add_u64 v[12:13], v[12:13], 0, s[12:13]
	v_add_u32_e32 v16, 64, v22
	v_addc_co_u32_e32 v9, vcc, 0, v9, vcc
	v_lshl_add_u64 v[12:13], v[12:13], 0, v[152:153]
	v_mad_i64_i32 v[16:17], s[14:15], v16, s1, v[20:21]
	v_add_co_u32_e32 v12, vcc, s11, v12
	v_lshl_add_u64 v[16:17], v[16:17], 0, s[12:13]
	v_add_u32_e32 v22, 0x60, v22
	v_addc_co_u32_e32 v13, vcc, 0, v13, vcc
	v_lshl_add_u64 v[16:17], v[16:17], 0, v[152:153]
	v_mad_i64_i32 v[20:21], s[14:15], v22, s1, v[20:21]
	v_add_co_u32_e32 v16, vcc, s11, v16
	v_lshl_add_u64 v[20:21], v[20:21], 0, s[12:13]
	s_nop 0
	v_addc_co_u32_e32 v17, vcc, 0, v17, vcc
	v_lshl_add_u64 v[20:21], v[20:21], 0, v[152:153]
	v_add_co_u32_e32 v20, vcc, s11, v20
	global_load_dwordx4 v[8:11], v[8:9], off offset:512 nt
	s_nop 0
	v_addc_co_u32_e32 v21, vcc, 0, v21, vcc
	global_load_dwordx4 v[12:15], v[12:13], off offset:512 nt
	v_cmp_lt_i32_e32 vcc, v25, v27
	global_load_dwordx4 v[16:19], v[16:17], off offset:512 nt
	s_add_i32 s11, s10, s76
	global_load_dwordx4 v[20:23], v[20:21], off offset:512 nt
	v_cndmask_b32_e32 v25, v209, v25, vcc
	v_lshlrev_b32_e32 v85, 2, v25
	v_xor_b32_e32 v25, 2, v209
	v_cmp_lt_i32_e32 vcc, v25, v27
	v_lshl_or_b32 v26, v28, 2, s11
	s_lshl_b32 s76, s76, 1
	v_cndmask_b32_e32 v25, v209, v25, vcc
	v_lshlrev_b32_e32 v86, 2, v25
	v_xor_b32_e32 v25, 4, v209
	v_cmp_lt_i32_e32 vcc, v25, v27
	v_readlane_b32 s11, v246, 37
	s_mov_b32 s12, 0
	v_cndmask_b32_e32 v25, v209, v25, vcc
	v_lshlrev_b32_e32 v87, 2, v25
	v_xor_b32_e32 v25, 8, v209
	v_cmp_lt_i32_e32 vcc, v25, v27
	v_ashrrev_i32_e32 v27, 31, v26
	v_lshl_add_u64 v[42:43], v[26:27], 1, s[60:61]
	v_cndmask_b32_e32 v25, v209, v25, vcc
	v_lshlrev_b32_e32 v88, 2, v25
	v_lshl_add_u32 v25, v28, 4, 0
	v_mul_u32_u24_e32 v28, 0x110, v76
	v_add_u32_e32 v92, v25, v28
	v_lshlrev_b64 v[44:45], 1, v[26:27]
	s_mov_b32 s13, 0
	s_branch .LBB0_254
; __device__ __forceinline__ unsigned cvt_pk_bf16(float lo, float hi) { unsigned r; asm volatile("v_cvt_pk_bf16_f32 %0, %1, %2" : "=v"(r) : "v"(lo), "v"(hi)); return r; }
; __device__ __forceinline__ float bflo(unsigned w) { return __uint_as_float(w << 16); }
; __device__ __forceinline__ float bfhi(unsigned w) { return __uint_as_float(w & 0xffff0000u); }
; PHASE_FN void sgu_block(const Params& p, unsigned char* lds, int l, int g, int ch0, int nch) {
;     ...
;         u32x2 uw[8];
; #pragma unroll
;         for (int pb = 0; pb < 8; ++pb) uw[pb] = *(const u32x2*)(Z + (size_t)(tok0 + 16 * pb + lr) * ZW + ZSU + ocol);
;         asm volatile("s_waitcnt lgkmcnt(0)" ::: "memory"); __builtin_amdgcn_s_barrier(); asm volatile("" ::: "memory");
;         bf16x8 af[4];
; #pragma unroll
;         for (int ks = 0; ks < 4; ++ks)
; #pragma unroll
;             for (int i = 0; i < 8; ++i) af[ks][i] = (short)vt[(32 * ks + 8 * q4 + i) * SP + 16 * wid + lr];
; #pragma unroll
;         for (int pb = 0; pb < 8; ++pb) {
;             f32x4 a = (f32x4){0.f, 0.f, 0.f, 0.f};
; #pragma unroll
;             for (int ks = 0; ks < 4; ++ks) { const bf16x8 bf = *(const bf16x8*)(wl + (16 * pb + lr) * SP + 32 * ks + 8 * q4); a = __builtin_amdgcn_mfma_f32_16x16x32_bf16(af[ks], bf, a, 0, 0, 0); }
;             const f32x2 u0 = gelu_pk((f32x2){bflo(uw[pb].x), bfhi(uw[pb].x)}), u1 = gelu_pk((f32x2){bflo(uw[pb].y), bfhi(uw[pb].y)});
;             u32x2 w; w.x = cvt_pk_bf16((a[0] + bs[pb]) * u0.x, (a[1] + bs[pb]) * u0.y); w.y = cvt_pk_bf16((a[2] + bs[pb]) * u1.x, (a[3] + bs[pb]) * u1.y);
;             *(u32x2*)(MIX + (size_t)(tok0 + 16 * pb + lr) * D + 512 + ocol) = w;
.LBB0_253:
	v_add_u32_e32 v32, s12, v91
	v_add_u32_e32 v152, 0xffff0000, v32
	v_mad_u64_u32 v[24:25], s[14:15], v152, s1, v[42:43]
	v_add_u32_e32 v72, 0xffff0010, v32
	v_add_u32_e32 v68, 0xffff0020, v32
	v_add_u32_e32 v64, 0xffff0030, v32
	v_mad_u64_u32 v[26:27], s[14:15], v72, s1, v[42:43]
	v_mad_u64_u32 v[28:29], s[14:15], v68, s1, v[42:43]
	v_mad_u64_u32 v[30:31], s[14:15], v64, s1, v[42:43]
	global_load_dwordx2 v[102:103], v[24:25], off offset:3072 nt
	global_load_dwordx2 v[74:75], v[26:27], off offset:3072 nt
	global_load_dwordx2 v[70:71], v[28:29], off offset:3072 nt
	global_load_dwordx2 v[66:67], v[30:31], off offset:3072 nt
	v_add_u32_e32 v60, 0xffff0040, v32
	v_add_u32_e32 v56, 0xffff0050, v32
	v_add_u32_e32 v50, 0xffff0060, v32
	v_add_u32_e32 v46, 0xffff0070, v32
	v_mad_u64_u32 v[24:25], s[14:15], v60, s1, v[42:43]
	v_mad_u64_u32 v[26:27], s[14:15], v56, s1, v[42:43]
	v_mad_u64_u32 v[28:29], s[14:15], v50, s1, v[42:43]
	v_mad_u64_u32 v[30:31], s[14:15], v46, s1, v[42:43]
	s_lshl_b32 s14, s10, 1
	global_load_dwordx2 v[62:63], v[24:25], off offset:3072 nt
	global_load_dwordx2 v[58:59], v[26:27], off offset:3072 nt
	global_load_dwordx2 v[54:55], v[28:29], off offset:3072 nt
	global_load_dwordx2 v[48:49], v[30:31], off offset:3072 nt
	s_add_i32 s24, s24, s14
	v_lshlrev_b32_e32 v24, 1, v76
	s_waitcnt lgkmcnt(0)
	s_barrier
	v_add3_u32 v47, s24, v24, v89
	ds_read_u16 v24, v47 offset:544
	ds_read_u16 v25, v47 offset:816
	ds_read_u16 v26, v47 offset:1088
	ds_read_u16 v27, v47 offset:1632
	ds_read_u16 v32, v47 offset:1904
	ds_read_u16 v33, v47 offset:1360
	ds_read_u16 v34, v47
	ds_read_u16 v35, v47 offset:272
	ds_read_b128 v[28:31], v92
	s_waitcnt lgkmcnt(4)
	v_perm_b32 v27, v32, v27, s63
	s_waitcnt lgkmcnt(3)
	v_perm_b32 v26, v33, v26, s63
	v_perm_b32 v25, v25, v24, s63
	s_waitcnt lgkmcnt(1)
	v_perm_b32 v24, v35, v34, s63
	ds_read_u16 v51, v47 offset:8704
	ds_read_u16 v52, v47 offset:8976
	ds_read_u16 v53, v47 offset:9792
	ds_read_u16 v57, v47 offset:10064
	ds_read_u16 v61, v47 offset:10336
	ds_read_u16 v65, v47 offset:10608
	ds_read_u16 v69, v47 offset:9248
	ds_read_u16 v73, v47 offset:9520
	ds_read_b128 v[32:35], v92 offset:64
	s_waitcnt lgkmcnt(9)
	v_mfma_f32_16x16x32_bf16 v[36:39], v[24:27], v[28:31], 0
	s_waitcnt lgkmcnt(3)
	v_perm_b32 v31, v65, v61, s63
	v_perm_b32 v30, v57, v53, s63
	s_waitcnt lgkmcnt(1)
	v_perm_b32 v29, v73, v69, s63
	v_perm_b32 v28, v52, v51, s63
	ds_read_u16 v51, v47 offset:17408
	ds_read_u16 v52, v47 offset:17680
	ds_read_u16 v53, v47 offset:18496
	ds_read_u16 v57, v47 offset:18768
	ds_read_u16 v61, v47 offset:19040
	ds_read_u16 v65, v47 offset:19312
	ds_read_u16 v69, v47 offset:17952
	ds_read_u16 v73, v47 offset:18224
	s_waitcnt lgkmcnt(8)
	v_mfma_f32_16x16x32_bf16 v[36:39], v[28:31], v[32:35], v[36:39]
	ds_read_b128 v[94:97], v92 offset:128
	s_waitcnt lgkmcnt(3)
	v_perm_b32 v35, v65, v61, s63
	v_perm_b32 v34, v57, v53, s63
	s_waitcnt lgkmcnt(1)
	v_perm_b32 v33, v73, v69, s63
	v_perm_b32 v32, v52, v51, s63
	ds_read_u16 v51, v47 offset:26112
	ds_read_u16 v52, v47 offset:26384
	ds_read_u16 v53, v47 offset:27200
	ds_read_u16 v57, v47 offset:27472
	ds_read_u16 v61, v47 offset:27744
	ds_read_u16 v65, v47 offset:28016
	ds_read_u16 v69, v47 offset:26656
	ds_read_u16 v47, v47 offset:26928
	ds_read_b128 v[98:101], v92 offset:192
	s_waitcnt lgkmcnt(9)
	v_mfma_f32_16x16x32_bf16 v[94:97], v[32:35], v[94:97], v[36:39]
	s_waitcnt lgkmcnt(5)
	s_nop 1
	v_perm_b32 v38, v57, v53, s63
	v_perm_b32 v36, v52, v51, s63
	s_waitcnt lgkmcnt(3)
	v_perm_b32 v39, v65, v61, s63
	s_waitcnt lgkmcnt(1)
	v_perm_b32 v37, v47, v69, s63
	v_lshlrev_b64 v[108:109], 11, v[152:153]
	v_mov_b32_e32 v73, v153
	s_waitcnt lgkmcnt(0)
	v_mfma_f32_16x16x32_bf16 v[94:97], v[36:39], v[98:101], v[94:97]
	v_mov_b32_e32 v69, v153
	s_xor_b32 s13, s13, 1
	s_addk_i32 s12, 0x80
	s_nop 4
	v_add_f32_e32 v65, v77, v94
	s_add_i32 s11, s11, 1
	s_cmpk_lg_i32 s12, 0x200
	s_waitcnt vmcnt(7)
	v_lshlrev_b32_e32 v104, 16, v102
	v_and_b32_e32 v105, 0xffff0000, v102
	v_and_b32_e32 v53, 0x7fffffff, v105
	v_and_b32_e32 v52, 0x7fffffff, v104
	v_pk_fma_f32 v[52:53], v[52:53], s[78:79], 1.0 op_sel_hi:[1,0,0]
	v_pk_mul_f32 v[100:101], v[104:105], v[104:105]
	v_rcp_f32_e32 v106, v52
	v_rcp_f32_e32 v107, v53
	v_mov_b64_e32 v[52:53], s[66:67]
	v_pk_mul_f32 v[100:101], v[100:101], s[68:69] op_sel_hi:[1,0]
	v_lshlrev_b32_e32 v102, 16, v103
	v_pk_fma_f32 v[98:99], v[106:107], s[74:75], v[52:53] op_sel_hi:[1,0,0]
	v_exp_f32_e32 v100, v100
	v_pk_fma_f32 v[98:99], v[106:107], v[98:99], s[62:63] op_sel_hi:[1,1,0]
	v_exp_f32_e32 v101, v101
	v_pk_fma_f32 v[98:99], v[106:107], v[98:99], s[0:1] op_sel_hi:[1,1,0]
	v_and_b32_e32 v103, 0xffff0000, v103
	v_pk_fma_f32 v[98:99], v[106:107], v[98:99], s[90:91] op_sel_hi:[1,1,0]
	v_cmp_gt_f32_e32 vcc, 0, v104
	v_pk_mul_f32 v[98:99], v[106:107], v[98:99]
	v_and_b32_e32 v107, 0x7fffffff, v103
	v_and_b32_e32 v106, 0x7fffffff, v102
	v_pk_fma_f32 v[106:107], v[106:107], s[78:79], 1.0 op_sel_hi:[1,0,0]
	v_pk_mul_f32 v[98:99], v[100:101], v[98:99]
	v_rcp_f32_e32 v106, v106
	v_rcp_f32_e32 v107, v107
	v_pk_mul_f32 v[100:101], v[104:105], v[98:99]
	v_pk_fma_f32 v[98:99], v[104:105], v[98:99], v[104:105] neg_lo:[1,0,0] neg_hi:[1,0,0]
	s_nop 0
	v_cndmask_b32_e32 v47, v98, v100, vcc
	v_cmp_gt_f32_e32 vcc, 0, v105
	v_mul_f32_e32 v47, v47, v65
	v_add_f32_e32 v65, v77, v95
	v_cndmask_b32_e32 v51, v99, v101, vcc
	v_pk_mul_f32 v[100:101], v[102:103], v[102:103]
	v_pk_fma_f32 v[98:99], v[106:107], s[74:75], v[52:53] op_sel_hi:[1,0,0]
	v_pk_mul_f32 v[100:101], v[100:101], s[68:69] op_sel_hi:[1,0]
	v_pk_fma_f32 v[98:99], v[106:107], v[98:99], s[62:63] op_sel_hi:[1,1,0]
	v_exp_f32_e32 v100, v100
	v_exp_f32_e32 v101, v101
	v_pk_fma_f32 v[98:99], v[106:107], v[98:99], s[0:1] op_sel_hi:[1,1,0]
	v_cmp_gt_f32_e32 vcc, 0, v102
	v_pk_fma_f32 v[98:99], v[106:107], v[98:99], s[90:91] op_sel_hi:[1,1,0]
	v_mul_f32_e32 v51, v51, v65
	v_pk_mul_f32 v[98:99], v[106:107], v[98:99]
	v_cvt_pk_bf16_f32 v106, v47, v51
	v_add_f32_e32 v47, v77, v96
	v_pk_mul_f32 v[98:99], v[100:101], v[98:99]
	v_add_f32_e32 v51, v77, v97
	v_pk_mul_f32 v[100:101], v[102:103], v[98:99]
	v_pk_fma_f32 v[98:99], v[102:103], v[98:99], v[102:103] neg_lo:[1,0,0] neg_hi:[1,0,0]
	s_nop 0
	v_cndmask_b32_e32 v57, v98, v100, vcc
	v_cmp_gt_f32_e32 vcc, 0, v103
	v_mul_f32_e32 v47, v57, v47
	s_nop 0
	v_cndmask_b32_e32 v61, v99, v101, vcc
	v_mul_f32_e32 v51, v61, v51
	v_cvt_pk_bf16_f32 v107, v47, v51
	ds_read_b128 v[94:97], v92 offset:4352
	ds_read_b128 v[98:101], v92 offset:4416
	s_waitcnt lgkmcnt(1)
; __device__ __forceinline__ unsigned cvt_pk_bf16(float lo, float hi) { unsigned r; asm volatile("v_cvt_pk_bf16_f32 %0, %1, %2" : "=v"(r) : "v"(lo), "v"(hi)); return r; }
; __device__ __forceinline__ float bflo(unsigned w) { return __uint_as_float(w << 16); }
; __device__ __forceinline__ float bfhi(unsigned w) { return __uint_as_float(w & 0xffff0000u); }
; PHASE_FN void sgu_block(const Params& p, unsigned char* lds, int l, int g, int ch0, int nch) {
;     ...
;         for (int pb = 0; pb < 8; ++pb) {
;             f32x4 a = (f32x4){0.f, 0.f, 0.f, 0.f};
; #pragma unroll
;             for (int ks = 0; ks < 4; ++ks) { const bf16x8 bf = *(const bf16x8*)(wl + (16 * pb + lr) * SP + 32 * ks + 8 * q4); a = __builtin_amdgcn_mfma_f32_16x16x32_bf16(af[ks], bf, a, 0, 0, 0); }
;             const f32x2 u0 = gelu_pk((f32x2){bflo(uw[pb].x), bfhi(uw[pb].x)}), u1 = gelu_pk((f32x2){bflo(uw[pb].y), bfhi(uw[pb].y)});
;             u32x2 w; w.x = cvt_pk_bf16((a[0] + bs[pb]) * u0.x, (a[1] + bs[pb]) * u0.y); w.y = cvt_pk_bf16((a[2] + bs[pb]) * u1.x, (a[3] + bs[pb]) * u1.y);
;             *(u32x2*)(MIX + (size_t)(tok0 + 16 * pb + lr) * D + 512 + ocol) = w;
	v_mfma_f32_16x16x32_bf16 v[94:97], v[24:27], v[94:97], 0
	ds_read_b128 v[102:105], v92 offset:4480
	s_waitcnt lgkmcnt(1)
	v_mfma_f32_16x16x32_bf16 v[94:97], v[28:31], v[98:101], v[94:97]
	v_lshl_add_u64 v[98:99], s[86:87], 0, v[108:109]
	v_lshl_add_u64 v[108:109], v[98:99], 0, v[44:45]
	ds_read_b128 v[98:101], v92 offset:4544
	s_waitcnt lgkmcnt(1)
	v_mfma_f32_16x16x32_bf16 v[94:97], v[32:35], v[102:105], v[94:97]
	s_waitcnt vmcnt(6)
	v_lshlrev_b32_e32 v102, 16, v74
	v_and_b32_e32 v103, 0xffff0000, v74
	v_and_b32_e32 v105, 0x7fffffff, v103
	v_and_b32_e32 v104, 0x7fffffff, v102
	v_pk_fma_f32 v[104:105], v[104:105], s[78:79], 1.0 op_sel_hi:[1,0,0]
	s_waitcnt lgkmcnt(0)
	v_mfma_f32_16x16x32_bf16 v[94:97], v[36:39], v[98:101], v[94:97]
	v_rcp_f32_e32 v104, v104
	v_rcp_f32_e32 v105, v105
	v_pk_mul_f32 v[100:101], v[102:103], v[102:103]
	v_lshlrev_b32_e32 v74, 16, v75
	v_pk_mul_f32 v[100:101], v[100:101], s[68:69] op_sel_hi:[1,0]
	v_pk_fma_f32 v[98:99], v[104:105], s[74:75], v[52:53] op_sel_hi:[1,0,0]
	v_exp_f32_e32 v100, v100
	v_pk_fma_f32 v[98:99], v[104:105], v[98:99], s[62:63] op_sel_hi:[1,1,0]
	v_exp_f32_e32 v101, v101
	v_pk_fma_f32 v[98:99], v[104:105], v[98:99], s[0:1] op_sel_hi:[1,1,0]
	v_and_b32_e32 v75, 0xffff0000, v75
	v_pk_fma_f32 v[98:99], v[104:105], v[98:99], s[90:91] op_sel_hi:[1,1,0]
	v_add_co_u32_e32 v108, vcc, s33, v108
	v_pk_mul_f32 v[98:99], v[104:105], v[98:99]
	v_and_b32_e32 v105, 0x7fffffff, v75
	v_and_b32_e32 v104, 0x7fffffff, v74
	v_pk_fma_f32 v[104:105], v[104:105], s[78:79], 1.0 op_sel_hi:[1,0,0]
	v_addc_co_u32_e32 v109, vcc, 0, v109, vcc
	v_pk_mul_f32 v[98:99], v[100:101], v[98:99]
	v_rcp_f32_e32 v104, v104
	v_rcp_f32_e32 v105, v105
	v_pk_mul_f32 v[100:101], v[102:103], v[98:99]
	v_pk_fma_f32 v[98:99], v[102:103], v[98:99], v[102:103] neg_lo:[1,0,0] neg_hi:[1,0,0]
	v_cmp_gt_f32_e32 vcc, 0, v102
	v_add_f32_e32 v65, v78, v94
	global_store_dwordx2 v[108:109], v[106:107], off offset:1024 nt
	v_cndmask_b32_e32 v47, v98, v100, vcc
	v_cmp_gt_f32_e32 vcc, 0, v103
	v_mul_f32_e32 v47, v47, v65
	v_add_f32_e32 v65, v78, v95
	v_cndmask_b32_e32 v51, v99, v101, vcc
	v_pk_mul_f32 v[100:101], v[74:75], v[74:75]
	v_pk_fma_f32 v[98:99], v[104:105], s[74:75], v[52:53] op_sel_hi:[1,0,0]
	v_pk_mul_f32 v[100:101], v[100:101], s[68:69] op_sel_hi:[1,0]
	v_pk_fma_f32 v[98:99], v[104:105], v[98:99], s[62:63] op_sel_hi:[1,1,0]
	v_exp_f32_e32 v100, v100
	v_exp_f32_e32 v101, v101
	v_pk_fma_f32 v[98:99], v[104:105], v[98:99], s[0:1] op_sel_hi:[1,1,0]
	v_cmp_gt_f32_e32 vcc, 0, v74
	v_pk_fma_f32 v[98:99], v[104:105], v[98:99], s[90:91] op_sel_hi:[1,1,0]
	v_mul_f32_e32 v51, v51, v65
	v_pk_mul_f32 v[98:99], v[104:105], v[98:99]
	v_cvt_pk_bf16_f32 v102, v47, v51
	v_add_f32_e32 v47, v78, v96
	v_pk_mul_f32 v[98:99], v[100:101], v[98:99]
	v_add_f32_e32 v51, v78, v97
	v_pk_mul_f32 v[100:101], v[74:75], v[98:99]
	v_pk_fma_f32 v[98:99], v[74:75], v[98:99], v[74:75] neg_lo:[1,0,0] neg_hi:[1,0,0]
	v_lshlrev_b64 v[104:105], 11, v[72:73]
	v_cndmask_b32_e32 v57, v98, v100, vcc
	v_cmp_gt_f32_e32 vcc, 0, v75
	v_mul_f32_e32 v47, v57, v47
	s_nop 0
	v_cndmask_b32_e32 v61, v99, v101, vcc
	v_mul_f32_e32 v51, v61, v51
	v_cvt_pk_bf16_f32 v103, v47, v51
	ds_read_b128 v[94:97], v92 offset:8704
	ds_read_b128 v[98:101], v92 offset:8768
	s_waitcnt lgkmcnt(1)
	v_mfma_f32_16x16x32_bf16 v[94:97], v[24:27], v[94:97], 0
	ds_read_b128 v[72:75], v92 offset:8832
	s_waitcnt lgkmcnt(1)
	v_mfma_f32_16x16x32_bf16 v[94:97], v[28:31], v[98:101], v[94:97]
	v_lshl_add_u64 v[98:99], s[86:87], 0, v[104:105]
	v_lshl_add_u64 v[104:105], v[98:99], 0, v[44:45]
	ds_read_b128 v[98:101], v92 offset:8896
	s_waitcnt lgkmcnt(1)
	v_mfma_f32_16x16x32_bf16 v[72:75], v[32:35], v[72:75], v[94:97]
	v_add_co_u32_e32 v104, vcc, s33, v104
	s_waitcnt vmcnt(6)
	s_nop 0
	v_lshlrev_b32_e32 v94, 16, v70
	v_and_b32_e32 v95, 0xffff0000, v70
	v_and_b32_e32 v97, 0x7fffffff, v95
	v_and_b32_e32 v96, 0x7fffffff, v94
	v_pk_fma_f32 v[96:97], v[96:97], s[78:79], 1.0 op_sel_hi:[1,0,0]
	s_waitcnt lgkmcnt(0)
	v_mfma_f32_16x16x32_bf16 v[72:75], v[36:39], v[98:101], v[72:75]
	v_rcp_f32_e32 v96, v96
	v_rcp_f32_e32 v97, v97
	v_pk_mul_f32 v[100:101], v[94:95], v[94:95]
	v_lshlrev_b32_e32 v70, 16, v71
	v_pk_mul_f32 v[100:101], v[100:101], s[68:69] op_sel_hi:[1,0]
	v_pk_fma_f32 v[98:99], v[96:97], s[74:75], v[52:53] op_sel_hi:[1,0,0]
	v_exp_f32_e32 v100, v100
	v_pk_fma_f32 v[98:99], v[96:97], v[98:99], s[62:63] op_sel_hi:[1,1,0]
	v_exp_f32_e32 v101, v101
	v_pk_fma_f32 v[98:99], v[96:97], v[98:99], s[0:1] op_sel_hi:[1,1,0]
	v_and_b32_e32 v71, 0xffff0000, v71
	v_pk_fma_f32 v[98:99], v[96:97], v[98:99], s[90:91] op_sel_hi:[1,1,0]
	v_addc_co_u32_e32 v105, vcc, 0, v105, vcc
	v_pk_mul_f32 v[96:97], v[96:97], v[98:99]
	v_cmp_gt_f32_e32 vcc, 0, v94
	v_pk_mul_f32 v[96:97], v[100:101], v[96:97]
	v_and_b32_e32 v101, 0x7fffffff, v71
	v_and_b32_e32 v100, 0x7fffffff, v70
	v_pk_fma_f32 v[100:101], v[100:101], s[78:79], 1.0 op_sel_hi:[1,0,0]
	v_pk_mul_f32 v[98:99], v[94:95], v[96:97]
	v_rcp_f32_e32 v100, v100
	v_rcp_f32_e32 v101, v101
	v_pk_fma_f32 v[96:97], v[94:95], v[96:97], v[94:95] neg_lo:[1,0,0] neg_hi:[1,0,0]
	v_add_f32_e32 v65, v79, v72
	v_cndmask_b32_e32 v47, v96, v98, vcc
	v_cmp_gt_f32_e32 vcc, 0, v95
	v_pk_fma_f32 v[94:95], v[100:101], s[74:75], v[52:53] op_sel_hi:[1,0,0]
	v_mul_f32_e32 v47, v47, v65
	v_cndmask_b32_e32 v51, v97, v99, vcc
	v_pk_mul_f32 v[96:97], v[70:71], v[70:71]
	v_pk_fma_f32 v[94:95], v[100:101], v[94:95], s[62:63] op_sel_hi:[1,1,0]
	v_pk_mul_f32 v[96:97], v[96:97], s[68:69] op_sel_hi:[1,0]
	v_pk_fma_f32 v[94:95], v[100:101], v[94:95], s[0:1] op_sel_hi:[1,1,0]
	v_exp_f32_e32 v96, v96
	v_exp_f32_e32 v97, v97
	v_pk_fma_f32 v[94:95], v[100:101], v[94:95], s[90:91] op_sel_hi:[1,1,0]
	v_cmp_gt_f32_e32 vcc, 0, v70
	v_pk_mul_f32 v[94:95], v[100:101], v[94:95]
	v_add_f32_e32 v65, v79, v73
	v_pk_mul_f32 v[94:95], v[96:97], v[94:95]
	v_mul_f32_e32 v51, v51, v65
	v_pk_mul_f32 v[96:97], v[70:71], v[94:95]
	v_pk_fma_f32 v[94:95], v[70:71], v[94:95], v[70:71] neg_lo:[1,0,0] neg_hi:[1,0,0]
	global_store_dwordx2 v[104:105], v[102:103], off offset:1024 nt
	v_cndmask_b32_e32 v57, v94, v96, vcc
	v_cmp_gt_f32_e32 vcc, 0, v71
	v_cvt_pk_bf16_f32 v102, v47, v51
	v_add_f32_e32 v47, v79, v74
	v_add_f32_e32 v51, v79, v75
	v_cndmask_b32_e32 v61, v95, v97, vcc
	v_mul_f32_e32 v47, v57, v47
	v_mul_f32_e32 v51, v61, v51
	v_cvt_pk_bf16_f32 v103, v47, v51
	ds_read_b128 v[70:73], v92 offset:13056
	ds_read_b128 v[94:97], v92 offset:13120
	s_waitcnt lgkmcnt(1)
; __device__ __forceinline__ unsigned cvt_pk_bf16(float lo, float hi) { unsigned r; asm volatile("v_cvt_pk_bf16_f32 %0, %1, %2" : "=v"(r) : "v"(lo), "v"(hi)); return r; }
; __device__ __forceinline__ float bflo(unsigned w) { return __uint_as_float(w << 16); }
; __device__ __forceinline__ float bfhi(unsigned w) { return __uint_as_float(w & 0xffff0000u); }
; PHASE_FN void sgu_block(const Params& p, unsigned char* lds, int l, int g, int ch0, int nch) {
;     ...
;         for (int pb = 0; pb < 8; ++pb) {
;             f32x4 a = (f32x4){0.f, 0.f, 0.f, 0.f};
; #pragma unroll
;             for (int ks = 0; ks < 4; ++ks) { const bf16x8 bf = *(const bf16x8*)(wl + (16 * pb + lr) * SP + 32 * ks + 8 * q4); a = __builtin_amdgcn_mfma_f32_16x16x32_bf16(af[ks], bf, a, 0, 0, 0); }
;             const f32x2 u0 = gelu_pk((f32x2){bflo(uw[pb].x), bfhi(uw[pb].x)}), u1 = gelu_pk((f32x2){bflo(uw[pb].y), bfhi(uw[pb].y)});
;             u32x2 w; w.x = cvt_pk_bf16((a[0] + bs[pb]) * u0.x, (a[1] + bs[pb]) * u0.y); w.y = cvt_pk_bf16((a[2] + bs[pb]) * u1.x, (a[3] + bs[pb]) * u1.y);
;             *(u32x2*)(MIX + (size_t)(tok0 + 16 * pb + lr) * D + 512 + ocol) = w;
	v_mfma_f32_16x16x32_bf16 v[70:73], v[24:27], v[70:73], 0
	ds_read_b128 v[98:101], v92 offset:13184
	v_lshlrev_b64 v[74:75], 11, v[68:69]
	s_waitcnt lgkmcnt(1)
	v_mfma_f32_16x16x32_bf16 v[68:71], v[28:31], v[94:97], v[70:73]
	s_waitcnt vmcnt(6)
	v_lshlrev_b32_e32 v96, 16, v66
	v_and_b32_e32 v97, 0xffff0000, v66
	v_lshlrev_b32_e32 v66, 16, v67
	v_lshl_add_u64 v[72:73], s[86:87], 0, v[74:75]
	v_lshl_add_u64 v[94:95], v[72:73], 0, v[44:45]
	ds_read_b128 v[72:75], v92 offset:13248
	s_waitcnt lgkmcnt(1)
	v_mfma_f32_16x16x32_bf16 v[68:71], v[32:35], v[98:101], v[68:71]
	v_and_b32_e32 v99, 0x7fffffff, v97
	v_and_b32_e32 v98, 0x7fffffff, v96
	v_pk_fma_f32 v[98:99], v[98:99], s[78:79], 1.0 op_sel_hi:[1,0,0]
	s_waitcnt lgkmcnt(0)
	v_mfma_f32_16x16x32_bf16 v[68:71], v[36:39], v[72:75], v[68:71]
	v_rcp_f32_e32 v98, v98
	v_rcp_f32_e32 v99, v99
	v_pk_mul_f32 v[74:75], v[96:97], v[96:97]
	v_add_co_u32_e32 v94, vcc, s33, v94
	v_pk_fma_f32 v[72:73], v[98:99], s[74:75], v[52:53] op_sel_hi:[1,0,0]
	v_pk_mul_f32 v[74:75], v[74:75], s[68:69] op_sel_hi:[1,0]
	v_pk_fma_f32 v[72:73], v[98:99], v[72:73], s[62:63] op_sel_hi:[1,1,0]
	v_exp_f32_e32 v74, v74
	v_exp_f32_e32 v75, v75
	v_addc_co_u32_e32 v95, vcc, 0, v95, vcc
	v_pk_fma_f32 v[72:73], v[98:99], v[72:73], s[0:1] op_sel_hi:[1,1,0]
	v_and_b32_e32 v67, 0xffff0000, v67
	global_store_dwordx2 v[94:95], v[102:103], off offset:1024 nt
	v_pk_fma_f32 v[72:73], v[98:99], v[72:73], s[90:91] op_sel_hi:[1,1,0]
	v_and_b32_e32 v95, 0x7fffffff, v67
	v_and_b32_e32 v94, 0x7fffffff, v66
	v_pk_mul_f32 v[72:73], v[98:99], v[72:73]
	v_pk_fma_f32 v[94:95], v[94:95], s[78:79], 1.0 op_sel_hi:[1,0,0]
	v_pk_mul_f32 v[72:73], v[74:75], v[72:73]
	v_rcp_f32_e32 v94, v94
	v_rcp_f32_e32 v95, v95
	v_pk_mul_f32 v[74:75], v[96:97], v[72:73]
	v_pk_fma_f32 v[72:73], v[96:97], v[72:73], v[96:97] neg_lo:[1,0,0] neg_hi:[1,0,0]
	v_cmp_gt_f32_e32 vcc, 0, v96
	v_add_f32_e32 v65, v80, v68
	s_nop 0
	v_cndmask_b32_e32 v47, v72, v74, vcc
	v_cmp_gt_f32_e32 vcc, 0, v97
	v_mul_f32_e32 v47, v47, v65
	v_add_f32_e32 v65, v80, v69
	v_cndmask_b32_e32 v51, v73, v75, vcc
	v_pk_mul_f32 v[74:75], v[66:67], v[66:67]
	v_pk_fma_f32 v[72:73], v[94:95], s[74:75], v[52:53] op_sel_hi:[1,0,0]
	v_pk_mul_f32 v[74:75], v[74:75], s[68:69] op_sel_hi:[1,0]
	v_pk_fma_f32 v[72:73], v[94:95], v[72:73], s[62:63] op_sel_hi:[1,1,0]
	v_exp_f32_e32 v74, v74
	v_exp_f32_e32 v75, v75
	v_pk_fma_f32 v[72:73], v[94:95], v[72:73], s[0:1] op_sel_hi:[1,1,0]
	v_cmp_gt_f32_e32 vcc, 0, v66
	v_pk_fma_f32 v[72:73], v[94:95], v[72:73], s[90:91] op_sel_hi:[1,1,0]
	v_mul_f32_e32 v51, v51, v65
	v_pk_mul_f32 v[72:73], v[94:95], v[72:73]
	v_mov_b32_e32 v65, v153
	v_pk_mul_f32 v[72:73], v[74:75], v[72:73]
	v_lshlrev_b64 v[98:99], 11, v[64:65]
	v_pk_mul_f32 v[74:75], v[66:67], v[72:73]
	v_pk_fma_f32 v[72:73], v[66:67], v[72:73], v[66:67] neg_lo:[1,0,0] neg_hi:[1,0,0]
	s_nop 0
	v_cndmask_b32_e32 v57, v72, v74, vcc
	v_cmp_gt_f32_e32 vcc, 0, v67
	v_cvt_pk_bf16_f32 v74, v47, v51
	v_add_f32_e32 v47, v80, v70
	v_add_f32_e32 v51, v80, v71
	v_cndmask_b32_e32 v61, v73, v75, vcc
	v_mul_f32_e32 v47, v57, v47
	v_mul_f32_e32 v51, v61, v51
	v_cvt_pk_bf16_f32 v75, v47, v51
	ds_read_b128 v[66:69], v92 offset:17408
	ds_read_b128 v[70:73], v92 offset:17472
	s_waitcnt lgkmcnt(1)
	v_mfma_f32_16x16x32_bf16 v[66:69], v[24:27], v[66:69], 0
	ds_read_b128 v[94:97], v92 offset:17536
	s_waitcnt lgkmcnt(1)
	v_mfma_f32_16x16x32_bf16 v[64:67], v[28:31], v[70:73], v[66:69]
	s_nop 4
	v_lshl_add_u64 v[68:69], s[86:87], 0, v[98:99]
	v_lshl_add_u64 v[72:73], v[68:69], 0, v[44:45]
	ds_read_b128 v[68:71], v92 offset:17600
	s_waitcnt lgkmcnt(1)
	v_mfma_f32_16x16x32_bf16 v[64:67], v[32:35], v[94:97], v[64:67]
	s_waitcnt vmcnt(6)
	v_lshlrev_b32_e32 v94, 16, v62
	v_and_b32_e32 v95, 0xffff0000, v62
	v_and_b32_e32 v97, 0x7fffffff, v95
	v_and_b32_e32 v96, 0x7fffffff, v94
	v_pk_fma_f32 v[96:97], v[96:97], s[78:79], 1.0 op_sel_hi:[1,0,0]
	s_waitcnt lgkmcnt(0)
	v_mfma_f32_16x16x32_bf16 v[64:67], v[36:39], v[68:71], v[64:67]
	v_rcp_f32_e32 v96, v96
	v_rcp_f32_e32 v97, v97
	v_pk_mul_f32 v[70:71], v[94:95], v[94:95]
	v_add_co_u32_e32 v72, vcc, s33, v72
	v_pk_fma_f32 v[68:69], v[96:97], s[74:75], v[52:53] op_sel_hi:[1,0,0]
	v_pk_mul_f32 v[70:71], v[70:71], s[68:69] op_sel_hi:[1,0]
	v_pk_fma_f32 v[68:69], v[96:97], v[68:69], s[62:63] op_sel_hi:[1,1,0]
	v_exp_f32_e32 v70, v70
	v_exp_f32_e32 v71, v71
	v_addc_co_u32_e32 v73, vcc, 0, v73, vcc
	v_pk_fma_f32 v[68:69], v[96:97], v[68:69], s[0:1] op_sel_hi:[1,1,0]
	v_lshlrev_b32_e32 v62, 16, v63
	v_and_b32_e32 v63, 0xffff0000, v63
	global_store_dwordx2 v[72:73], v[74:75], off offset:1024 nt
	v_pk_fma_f32 v[68:69], v[96:97], v[68:69], s[90:91] op_sel_hi:[1,1,0]
	v_and_b32_e32 v73, 0x7fffffff, v63
	v_and_b32_e32 v72, 0x7fffffff, v62
	v_pk_mul_f32 v[68:69], v[96:97], v[68:69]
	v_pk_fma_f32 v[72:73], v[72:73], s[78:79], 1.0 op_sel_hi:[1,0,0]
	v_pk_mul_f32 v[68:69], v[70:71], v[68:69]
	v_rcp_f32_e32 v72, v72
	v_rcp_f32_e32 v73, v73
	v_pk_mul_f32 v[70:71], v[94:95], v[68:69]
	v_pk_fma_f32 v[68:69], v[94:95], v[68:69], v[94:95] neg_lo:[1,0,0] neg_hi:[1,0,0]
	v_cmp_gt_f32_e32 vcc, 0, v94
	s_nop 1
	v_cndmask_b32_e32 v47, v68, v70, vcc
	v_cmp_gt_f32_e32 vcc, 0, v95
	s_nop 1
	v_cndmask_b32_e32 v51, v69, v71, vcc
	v_pk_mul_f32 v[70:71], v[62:63], v[62:63]
	v_pk_fma_f32 v[68:69], v[72:73], s[74:75], v[52:53] op_sel_hi:[1,0,0]
	v_pk_mul_f32 v[70:71], v[70:71], s[68:69] op_sel_hi:[1,0]
	v_pk_fma_f32 v[68:69], v[72:73], v[68:69], s[62:63] op_sel_hi:[1,1,0]
	v_exp_f32_e32 v70, v70
	v_exp_f32_e32 v71, v71
	v_pk_fma_f32 v[68:69], v[72:73], v[68:69], s[0:1] op_sel_hi:[1,1,0]
	v_cmp_gt_f32_e32 vcc, 0, v62
	v_pk_fma_f32 v[68:69], v[72:73], v[68:69], s[90:91] op_sel_hi:[1,1,0]
	s_nop 0
	v_pk_mul_f32 v[68:69], v[72:73], v[68:69]
	s_nop 0
	v_pk_mul_f32 v[68:69], v[70:71], v[68:69]
	s_nop 0
	v_pk_mul_f32 v[70:71], v[62:63], v[68:69]
	v_pk_fma_f32 v[68:69], v[62:63], v[68:69], v[62:63] neg_lo:[1,0,0] neg_hi:[1,0,0]
	v_add_f32_e32 v62, v81, v64
	v_mul_f32_e32 v47, v47, v62
	v_add_f32_e32 v62, v81, v65
	v_cndmask_b32_e32 v57, v68, v70, vcc
	v_cmp_gt_f32_e32 vcc, 0, v63
	v_mul_f32_e32 v51, v51, v62
	v_cvt_pk_bf16_f32 v74, v47, v51
	v_add_f32_e32 v47, v81, v66
	v_cndmask_b32_e32 v61, v69, v71, vcc
	v_add_f32_e32 v51, v81, v67
	v_mul_f32_e32 v47, v57, v47
	v_mul_f32_e32 v51, v61, v51
	v_cvt_pk_bf16_f32 v75, v47, v51
	ds_read_b128 v[62:65], v92 offset:21760
	ds_read_b128 v[66:69], v92 offset:21824
	s_waitcnt lgkmcnt(1)
; __device__ __forceinline__ unsigned cvt_pk_bf16(float lo, float hi) { unsigned r; asm volatile("v_cvt_pk_bf16_f32 %0, %1, %2" : "=v"(r) : "v"(lo), "v"(hi)); return r; }
; __device__ __forceinline__ float bflo(unsigned w) { return __uint_as_float(w << 16); }
; __device__ __forceinline__ float bfhi(unsigned w) { return __uint_as_float(w & 0xffff0000u); }
; PHASE_FN void sgu_block(const Params& p, unsigned char* lds, int l, int g, int ch0, int nch) {
;     ...
;         for (int pb = 0; pb < 8; ++pb) {
;             f32x4 a = (f32x4){0.f, 0.f, 0.f, 0.f};
; #pragma unroll
;             for (int ks = 0; ks < 4; ++ks) { const bf16x8 bf = *(const bf16x8*)(wl + (16 * pb + lr) * SP + 32 * ks + 8 * q4); a = __builtin_amdgcn_mfma_f32_16x16x32_bf16(af[ks], bf, a, 0, 0, 0); }
;             const f32x2 u0 = gelu_pk((f32x2){bflo(uw[pb].x), bfhi(uw[pb].x)}), u1 = gelu_pk((f32x2){bflo(uw[pb].y), bfhi(uw[pb].y)});
;             u32x2 w; w.x = cvt_pk_bf16((a[0] + bs[pb]) * u0.x, (a[1] + bs[pb]) * u0.y); w.y = cvt_pk_bf16((a[2] + bs[pb]) * u1.x, (a[3] + bs[pb]) * u1.y);
;             *(u32x2*)(MIX + (size_t)(tok0 + 16 * pb + lr) * D + 512 + ocol) = w;
	v_mfma_f32_16x16x32_bf16 v[62:65], v[24:27], v[62:65], 0
	v_mov_b32_e32 v61, v153
	ds_read_b128 v[70:73], v92 offset:21888
	v_lshlrev_b64 v[94:95], 11, v[60:61]
	s_waitcnt lgkmcnt(1)
	v_mfma_f32_16x16x32_bf16 v[60:63], v[28:31], v[66:69], v[62:65]
	s_nop 2
	v_lshl_add_u64 v[64:65], s[86:87], 0, v[94:95]
	v_lshl_add_u64 v[68:69], v[64:65], 0, v[44:45]
	ds_read_b128 v[64:67], v92 offset:21952
	s_waitcnt lgkmcnt(1)
	v_mfma_f32_16x16x32_bf16 v[60:63], v[32:35], v[70:73], v[60:63]
	s_waitcnt vmcnt(6)
	v_lshlrev_b32_e32 v70, 16, v58
	v_and_b32_e32 v71, 0xffff0000, v58
	v_and_b32_e32 v73, 0x7fffffff, v71
	v_and_b32_e32 v72, 0x7fffffff, v70
	v_pk_fma_f32 v[72:73], v[72:73], s[78:79], 1.0 op_sel_hi:[1,0,0]
	s_waitcnt lgkmcnt(0)
	v_mfma_f32_16x16x32_bf16 v[60:63], v[36:39], v[64:67], v[60:63]
	v_rcp_f32_e32 v72, v72
	v_rcp_f32_e32 v73, v73
	v_pk_mul_f32 v[66:67], v[70:71], v[70:71]
	v_add_co_u32_e32 v68, vcc, s33, v68
	v_pk_fma_f32 v[64:65], v[72:73], s[74:75], v[52:53] op_sel_hi:[1,0,0]
	v_pk_mul_f32 v[66:67], v[66:67], s[68:69] op_sel_hi:[1,0]
	v_pk_fma_f32 v[64:65], v[72:73], v[64:65], s[62:63] op_sel_hi:[1,1,0]
	v_exp_f32_e32 v66, v66
	v_exp_f32_e32 v67, v67
	v_addc_co_u32_e32 v69, vcc, 0, v69, vcc
	v_pk_fma_f32 v[64:65], v[72:73], v[64:65], s[0:1] op_sel_hi:[1,1,0]
	v_lshlrev_b32_e32 v58, 16, v59
	v_and_b32_e32 v59, 0xffff0000, v59
	global_store_dwordx2 v[68:69], v[74:75], off offset:1024 nt
	v_pk_fma_f32 v[64:65], v[72:73], v[64:65], s[90:91] op_sel_hi:[1,1,0]
	v_and_b32_e32 v69, 0x7fffffff, v59
	v_and_b32_e32 v68, 0x7fffffff, v58
	v_pk_mul_f32 v[64:65], v[72:73], v[64:65]
	v_pk_fma_f32 v[68:69], v[68:69], s[78:79], 1.0 op_sel_hi:[1,0,0]
	v_pk_mul_f32 v[64:65], v[66:67], v[64:65]
	v_rcp_f32_e32 v68, v68
	v_rcp_f32_e32 v69, v69
	v_pk_mul_f32 v[66:67], v[70:71], v[64:65]
	v_pk_fma_f32 v[64:65], v[70:71], v[64:65], v[70:71] neg_lo:[1,0,0] neg_hi:[1,0,0]
	v_cmp_gt_f32_e32 vcc, 0, v70
	s_nop 1
	v_cndmask_b32_e32 v47, v64, v66, vcc
	v_cmp_gt_f32_e32 vcc, 0, v71
	s_nop 1
	v_cndmask_b32_e32 v51, v65, v67, vcc
	v_pk_mul_f32 v[66:67], v[58:59], v[58:59]
	v_pk_fma_f32 v[64:65], v[68:69], s[74:75], v[52:53] op_sel_hi:[1,0,0]
	v_pk_mul_f32 v[66:67], v[66:67], s[68:69] op_sel_hi:[1,0]
	v_pk_fma_f32 v[64:65], v[68:69], v[64:65], s[62:63] op_sel_hi:[1,1,0]
	v_exp_f32_e32 v66, v66
	v_exp_f32_e32 v67, v67
	v_pk_fma_f32 v[64:65], v[68:69], v[64:65], s[0:1] op_sel_hi:[1,1,0]
	v_cmp_gt_f32_e32 vcc, 0, v58
	v_pk_fma_f32 v[64:65], v[68:69], v[64:65], s[90:91] op_sel_hi:[1,1,0]
	s_nop 0
	v_pk_mul_f32 v[64:65], v[68:69], v[64:65]
	s_nop 0
	v_pk_mul_f32 v[64:65], v[66:67], v[64:65]
	s_nop 0
	v_pk_mul_f32 v[66:67], v[58:59], v[64:65]
	v_pk_fma_f32 v[64:65], v[58:59], v[64:65], v[58:59] neg_lo:[1,0,0] neg_hi:[1,0,0]
	s_nop 0
	v_cndmask_b32_e32 v57, v64, v66, vcc
	v_cmp_gt_f32_e32 vcc, 0, v59
	v_add_f32_e32 v59, v82, v60
	v_mul_f32_e32 v47, v47, v59
	v_add_f32_e32 v59, v82, v61
	v_mul_f32_e32 v51, v51, v59
	v_cndmask_b32_e32 v58, v65, v67, vcc
	v_cvt_pk_bf16_f32 v70, v47, v51
	v_add_f32_e32 v47, v82, v62
	v_add_f32_e32 v51, v82, v63
	v_mul_f32_e32 v47, v57, v47
	v_mul_f32_e32 v51, v58, v51
	v_cvt_pk_bf16_f32 v71, v47, v51
	ds_read_b128 v[58:61], v92 offset:26112
	ds_read_b128 v[62:65], v92 offset:26176
	s_waitcnt lgkmcnt(1)
	v_mfma_f32_16x16x32_bf16 v[58:61], v[24:27], v[58:61], 0
	v_mov_b32_e32 v57, v153
	ds_read_b128 v[66:69], v92 offset:26240
	v_lshlrev_b64 v[72:73], 11, v[56:57]
	s_waitcnt lgkmcnt(1)
	v_mfma_f32_16x16x32_bf16 v[56:59], v[28:31], v[62:65], v[58:61]
	s_nop 2
	v_lshl_add_u64 v[60:61], s[86:87], 0, v[72:73]
	v_lshl_add_u64 v[64:65], v[60:61], 0, v[44:45]
	ds_read_b128 v[60:63], v92 offset:26304
	s_waitcnt lgkmcnt(1)
	v_mfma_f32_16x16x32_bf16 v[56:59], v[32:35], v[66:69], v[56:59]
	s_waitcnt vmcnt(6)
	v_lshlrev_b32_e32 v66, 16, v54
	v_and_b32_e32 v67, 0xffff0000, v54
	v_and_b32_e32 v69, 0x7fffffff, v67
	v_and_b32_e32 v68, 0x7fffffff, v66
	v_pk_fma_f32 v[68:69], v[68:69], s[78:79], 1.0 op_sel_hi:[1,0,0]
	s_waitcnt lgkmcnt(0)
	v_mfma_f32_16x16x32_bf16 v[56:59], v[36:39], v[60:63], v[56:59]
	v_rcp_f32_e32 v68, v68
	v_rcp_f32_e32 v69, v69
	v_pk_mul_f32 v[62:63], v[66:67], v[66:67]
	v_add_co_u32_e32 v64, vcc, s33, v64
	v_pk_fma_f32 v[60:61], v[68:69], s[74:75], v[52:53] op_sel_hi:[1,0,0]
	v_pk_mul_f32 v[62:63], v[62:63], s[68:69] op_sel_hi:[1,0]
	v_pk_fma_f32 v[60:61], v[68:69], v[60:61], s[62:63] op_sel_hi:[1,1,0]
	v_exp_f32_e32 v62, v62
	v_exp_f32_e32 v63, v63
	v_addc_co_u32_e32 v65, vcc, 0, v65, vcc
	v_pk_fma_f32 v[60:61], v[68:69], v[60:61], s[0:1] op_sel_hi:[1,1,0]
	v_lshlrev_b32_e32 v54, 16, v55
	v_and_b32_e32 v55, 0xffff0000, v55
	global_store_dwordx2 v[64:65], v[70:71], off offset:1024 nt
	v_pk_fma_f32 v[60:61], v[68:69], v[60:61], s[90:91] op_sel_hi:[1,1,0]
	v_and_b32_e32 v65, 0x7fffffff, v55
	v_and_b32_e32 v64, 0x7fffffff, v54
	v_pk_mul_f32 v[60:61], v[68:69], v[60:61]
	v_pk_fma_f32 v[64:65], v[64:65], s[78:79], 1.0 op_sel_hi:[1,0,0]
	v_pk_mul_f32 v[60:61], v[62:63], v[60:61]
	v_rcp_f32_e32 v64, v64
	v_rcp_f32_e32 v65, v65
	v_pk_mul_f32 v[62:63], v[66:67], v[60:61]
	v_pk_fma_f32 v[60:61], v[66:67], v[60:61], v[66:67] neg_lo:[1,0,0] neg_hi:[1,0,0]
	v_cmp_gt_f32_e32 vcc, 0, v66
	v_add_f32_e32 v56, v83, v56
	s_nop 0
	v_cndmask_b32_e32 v47, v60, v62, vcc
	v_cmp_gt_f32_e32 vcc, 0, v67
	v_mul_f32_e32 v47, v47, v56
	v_add_f32_e32 v56, v83, v57
	v_cndmask_b32_e32 v51, v61, v63, vcc
	v_pk_mul_f32 v[62:63], v[54:55], v[54:55]
	v_pk_fma_f32 v[60:61], v[64:65], s[74:75], v[52:53] op_sel_hi:[1,0,0]
	v_pk_mul_f32 v[62:63], v[62:63], s[68:69] op_sel_hi:[1,0]
	v_pk_fma_f32 v[60:61], v[64:65], v[60:61], s[62:63] op_sel_hi:[1,1,0]
	v_exp_f32_e32 v62, v62
	v_exp_f32_e32 v63, v63
	v_pk_fma_f32 v[60:61], v[64:65], v[60:61], s[0:1] op_sel_hi:[1,1,0]
	v_cmp_gt_f32_e32 vcc, 0, v54
	v_pk_fma_f32 v[60:61], v[64:65], v[60:61], s[90:91] op_sel_hi:[1,1,0]
	v_mul_f32_e32 v51, v51, v56
	v_pk_mul_f32 v[60:61], v[64:65], v[60:61]
	s_nop 0
	v_pk_mul_f32 v[60:61], v[62:63], v[60:61]
	s_nop 0
	v_pk_mul_f32 v[62:63], v[54:55], v[60:61]
	v_pk_fma_f32 v[60:61], v[54:55], v[60:61], v[54:55] neg_lo:[1,0,0] neg_hi:[1,0,0]
	s_nop 0
	v_cndmask_b32_e32 v54, v60, v62, vcc
	v_cmp_gt_f32_e32 vcc, 0, v55
	v_cvt_pk_bf16_f32 v62, v47, v51
	v_add_f32_e32 v47, v83, v58
	v_add_f32_e32 v51, v83, v59
	v_cndmask_b32_e32 v55, v61, v63, vcc
	v_mul_f32_e32 v47, v54, v47
	v_mul_f32_e32 v51, v55, v51
	v_cvt_pk_bf16_f32 v63, v47, v51
	ds_read_b128 v[54:57], v92 offset:30464
	ds_read_b128 v[58:61], v92 offset:30528
	s_waitcnt lgkmcnt(1)
; __device__ __forceinline__ unsigned cvt_pk_bf16(float lo, float hi) { unsigned r; asm volatile("v_cvt_pk_bf16_f32 %0, %1, %2" : "=v"(r) : "v"(lo), "v"(hi)); return r; }
; __device__ __forceinline__ float bflo(unsigned w) { return __uint_as_float(w << 16); }
; __device__ __forceinline__ float bfhi(unsigned w) { return __uint_as_float(w & 0xffff0000u); }
; PHASE_FN void sgu_block(const Params& p, unsigned char* lds, int l, int g, int ch0, int nch) {
;     ...
;         for (int i = 0; i < 4; ++i) { const u32x4 w = pv[i];
;             float v[8];
;             { const f32x2 a = gelu_pk((f32x2){bflo(w.x), bfhi(w.x)}), b2 = gelu_pk((f32x2){bflo(w.y), bfhi(w.y)}), c = gelu_pk((f32x2){bflo(w.z), bfhi(w.z)}), d = gelu_pk((f32x2){bflo(w.w), bfhi(w.w)});
;               v[0] = a.x; v[1] = a.y; v[2] = b2.x; v[3] = b2.y; v[4] = c.x; v[5] = c.y; v[6] = d.x; v[7] = d.y; }
;     ...
;         for (int pb = 0; pb < 8; ++pb) {
;             f32x4 a = (f32x4){0.f, 0.f, 0.f, 0.f};
; #pragma unroll
;             for (int ks = 0; ks < 4; ++ks) { const bf16x8 bf = *(const bf16x8*)(wl + (16 * pb + lr) * SP + 32 * ks + 8 * q4); a = __builtin_amdgcn_mfma_f32_16x16x32_bf16(af[ks], bf, a, 0, 0, 0); }
;             const f32x2 u0 = gelu_pk((f32x2){bflo(uw[pb].x), bfhi(uw[pb].x)}), u1 = gelu_pk((f32x2){bflo(uw[pb].y), bfhi(uw[pb].y)});
;             u32x2 w; w.x = cvt_pk_bf16((a[0] + bs[pb]) * u0.x, (a[1] + bs[pb]) * u0.y); w.y = cvt_pk_bf16((a[2] + bs[pb]) * u1.x, (a[3] + bs[pb]) * u1.y);
;             *(u32x2*)(MIX + (size_t)(tok0 + 16 * pb + lr) * D + 512 + ocol) = w;
	v_mfma_f32_16x16x32_bf16 v[24:27], v[24:27], v[54:57], 0
	ds_read_b128 v[54:57], v92 offset:30592
	v_mov_b32_e32 v51, v153
	v_lshlrev_b64 v[50:51], 11, v[50:51]
	s_waitcnt lgkmcnt(1)
	v_mfma_f32_16x16x32_bf16 v[24:27], v[28:31], v[58:61], v[24:27]
	v_lshl_add_u64 v[28:29], s[86:87], 0, v[50:51]
	v_lshl_add_u64 v[50:51], v[28:29], 0, v[44:45]
	ds_read_b128 v[28:31], v92 offset:30656
	s_waitcnt lgkmcnt(1)
	v_mfma_f32_16x16x32_bf16 v[24:27], v[32:35], v[54:57], v[24:27]
	s_waitcnt vmcnt(6)
	v_lshlrev_b32_e32 v32, 16, v48
	v_and_b32_e32 v33, 0xffff0000, v48
	v_and_b32_e32 v35, 0x7fffffff, v33
	v_and_b32_e32 v34, 0x7fffffff, v32
	v_pk_fma_f32 v[34:35], v[34:35], s[78:79], 1.0 op_sel_hi:[1,0,0]
	s_waitcnt lgkmcnt(0)
	v_mfma_f32_16x16x32_bf16 v[24:27], v[36:39], v[28:31], v[24:27]
	v_rcp_f32_e32 v34, v34
	v_rcp_f32_e32 v35, v35
	v_pk_mul_f32 v[30:31], v[32:33], v[32:33]
	v_add_co_u32_e32 v50, vcc, s33, v50
	v_pk_fma_f32 v[28:29], v[34:35], s[74:75], v[52:53] op_sel_hi:[1,0,0]
	v_pk_mul_f32 v[30:31], v[30:31], s[68:69] op_sel_hi:[1,0]
	v_pk_fma_f32 v[28:29], v[34:35], v[28:29], s[62:63] op_sel_hi:[1,1,0]
	v_exp_f32_e32 v30, v30
	v_pk_fma_f32 v[28:29], v[34:35], v[28:29], s[0:1] op_sel_hi:[1,1,0]
	v_exp_f32_e32 v31, v31
	v_pk_fma_f32 v[28:29], v[34:35], v[28:29], s[90:91] op_sel_hi:[1,1,0]
	v_addc_co_u32_e32 v51, vcc, 0, v51, vcc
	v_pk_mul_f32 v[28:29], v[34:35], v[28:29]
	v_lshlrev_b32_e32 v34, 16, v49
	v_and_b32_e32 v35, 0xffff0000, v49
	v_and_b32_e32 v37, 0x7fffffff, v35
	v_and_b32_e32 v36, 0x7fffffff, v34
	v_pk_fma_f32 v[36:37], v[36:37], s[78:79], 1.0 op_sel_hi:[1,0,0]
	v_pk_mul_f32 v[28:29], v[30:31], v[28:29]
	v_rcp_f32_e32 v36, v36
	v_rcp_f32_e32 v37, v37
	v_pk_mul_f32 v[30:31], v[32:33], v[28:29]
	v_pk_fma_f32 v[28:29], v[32:33], v[28:29], v[32:33] neg_lo:[1,0,0] neg_hi:[1,0,0]
	v_cmp_gt_f32_e32 vcc, 0, v32
	v_add_f32_e32 v24, v84, v24
	v_add_f32_e32 v25, v84, v25
	v_cndmask_b32_e32 v32, v28, v30, vcc
	v_cmp_gt_f32_e32 vcc, 0, v33
	v_mul_f32_e32 v24, v32, v24
	global_store_dwordx2 v[50:51], v[62:63], off offset:1024 nt
	v_cndmask_b32_e32 v33, v29, v31, vcc
	v_pk_mul_f32 v[30:31], v[34:35], v[34:35]
	v_pk_fma_f32 v[28:29], v[36:37], s[74:75], v[52:53] op_sel_hi:[1,0,0]
	v_pk_mul_f32 v[30:31], v[30:31], s[68:69] op_sel_hi:[1,0]
	v_pk_fma_f32 v[28:29], v[36:37], v[28:29], s[62:63] op_sel_hi:[1,1,0]
	v_exp_f32_e32 v30, v30
	v_exp_f32_e32 v31, v31
	v_pk_fma_f32 v[28:29], v[36:37], v[28:29], s[0:1] op_sel_hi:[1,1,0]
	v_cmp_gt_f32_e32 vcc, 0, v34
	v_pk_fma_f32 v[28:29], v[36:37], v[28:29], s[90:91] op_sel_hi:[1,1,0]
	v_mul_f32_e32 v25, v33, v25
	v_pk_mul_f32 v[28:29], v[36:37], v[28:29]
	v_cvt_pk_bf16_f32 v24, v24, v25
	v_add_f32_e32 v25, v84, v26
	v_pk_mul_f32 v[28:29], v[30:31], v[28:29]
	v_add_f32_e32 v26, v84, v27
	v_pk_mul_f32 v[30:31], v[34:35], v[28:29]
	v_pk_fma_f32 v[28:29], v[34:35], v[28:29], v[34:35] neg_lo:[1,0,0] neg_hi:[1,0,0]
	v_mov_b32_e32 v47, v153
	v_cndmask_b32_e32 v28, v28, v30, vcc
	v_cmp_gt_f32_e32 vcc, 0, v35
	v_mul_f32_e32 v25, v28, v25
	s_nop 0
	v_cndmask_b32_e32 v29, v29, v31, vcc
	v_mul_f32_e32 v26, v29, v26
	v_cvt_pk_bf16_f32 v25, v25, v26
	v_lshlrev_b64 v[26:27], 11, v[46:47]
	v_lshl_add_u64 v[26:27], s[86:87], 0, v[26:27]
	v_lshl_add_u64 v[26:27], v[26:27], 0, v[44:45]
	v_add_co_u32_e32 v26, vcc, 0x24c00000, v26
	s_nop 1
	v_addc_co_u32_e32 v27, vcc, 0, v27, vcc
	global_store_dwordx2 v[26:27], v[24:25], off offset:1024 nt
	s_cbranch_scc0 .LBB0_251
.LBB0_254:
	s_waitcnt vmcnt(3)
	v_lshlrev_b32_e32 v26, 16, v8
	v_and_b32_e32 v27, 0xffff0000, v8
	v_and_b32_e32 v25, 0x7fffffff, v27
	v_and_b32_e32 v24, 0x7fffffff, v26
	v_pk_fma_f32 v[24:25], v[24:25], s[78:79], 1.0 op_sel_hi:[1,0,0]
	v_cmp_gt_f32_e32 vcc, 0, v26
	v_rcp_f32_e32 v28, v24
	v_rcp_f32_e32 v29, v25
	v_mov_b64_e32 v[24:25], s[66:67]
	s_cmp_eq_u32 s13, 0
	s_mov_b32 s14, 0x8800
	v_pk_fma_f32 v[30:31], v[28:29], s[74:75], v[24:25] op_sel_hi:[1,0,0]
	s_cselect_b32 s14, s14, 0x11000
	v_pk_fma_f32 v[30:31], v[28:29], v[30:31], s[62:63] op_sel_hi:[1,1,0]
	s_add_i32 s24, s14, 0
	v_pk_fma_f32 v[30:31], v[28:29], v[30:31], s[0:1] op_sel_hi:[1,1,0]
	v_lshlrev_b32_e32 v152, 1, v40
	v_pk_fma_f32 v[30:31], v[28:29], v[30:31], s[90:91] op_sel_hi:[1,1,0]
	s_cmp_ge_u32 s11, s81
	v_pk_mul_f32 v[28:29], v[28:29], v[30:31]
	v_pk_mul_f32 v[30:31], v[26:27], v[26:27]
	s_nop 0
	v_pk_mul_f32 v[30:31], v[30:31], s[68:69] op_sel_hi:[1,0]
	s_nop 0
	v_exp_f32_e32 v30, v30
	v_exp_f32_e32 v31, v31
	s_nop 0
	v_pk_mul_f32 v[28:29], v[30:31], v[28:29]
	s_nop 0
	v_pk_mul_f32 v[30:31], v[26:27], v[28:29]
	v_pk_fma_f32 v[28:29], v[26:27], v[28:29], v[26:27] neg_lo:[1,0,0] neg_hi:[1,0,0]
	v_lshlrev_b32_e32 v26, 16, v9
	v_cndmask_b32_e32 v36, v28, v30, vcc
	v_cmp_gt_f32_e32 vcc, 0, v27
	v_and_b32_e32 v27, 0xffff0000, v9
	v_and_b32_e32 v28, 0x7fffffff, v26
	v_cndmask_b32_e32 v37, v29, v31, vcc
	v_and_b32_e32 v29, 0x7fffffff, v27
	v_pk_fma_f32 v[28:29], v[28:29], s[78:79], 1.0 op_sel_hi:[1,0,0]
	v_cmp_gt_f32_e32 vcc, 0, v27
	v_rcp_f32_e32 v28, v28
	v_rcp_f32_e32 v29, v29
	v_cmp_gt_f32_e64 s[40:41], 0, v26
	v_mul_f32_e32 v32, v37, v37
	v_fmac_f32_e32 v32, v36, v36
	v_pk_fma_f32 v[30:31], v[28:29], s[74:75], v[24:25] op_sel_hi:[1,0,0]
	s_nop 0
	v_pk_fma_f32 v[30:31], v[28:29], v[30:31], s[62:63] op_sel_hi:[1,1,0]
	s_nop 0
	v_pk_fma_f32 v[30:31], v[28:29], v[30:31], s[0:1] op_sel_hi:[1,1,0]
	s_nop 0
	v_pk_fma_f32 v[30:31], v[28:29], v[30:31], s[90:91] op_sel_hi:[1,1,0]
	s_nop 0
	v_pk_mul_f32 v[28:29], v[28:29], v[30:31]
	v_pk_mul_f32 v[30:31], v[26:27], v[26:27]
	s_nop 0
	v_pk_mul_f32 v[30:31], v[30:31], s[68:69] op_sel_hi:[1,0]
	s_nop 0
	v_exp_f32_e32 v30, v30
	v_exp_f32_e32 v31, v31
	s_nop 0
; __device__ __forceinline__ unsigned cvt_pk_bf16(float lo, float hi) { unsigned r; asm volatile("v_cvt_pk_bf16_f32 %0, %1, %2" : "=v"(r) : "v"(lo), "v"(hi)); return r; }
; __device__ __forceinline__ float bflo(unsigned w) { return __uint_as_float(w << 16); }
; __device__ __forceinline__ float bfhi(unsigned w) { return __uint_as_float(w & 0xffff0000u); }
; PHASE_FN void sgu_block(const Params& p, unsigned char* lds, int l, int g, int ch0, int nch) {
;     ...
;         for (int i = 0; i < 4; ++i) { const u32x4 w = pv[i];
;             float v[8];
;             { const f32x2 a = gelu_pk((f32x2){bflo(w.x), bfhi(w.x)}), b2 = gelu_pk((f32x2){bflo(w.y), bfhi(w.y)}), c = gelu_pk((f32x2){bflo(w.z), bfhi(w.z)}), d = gelu_pk((f32x2){bflo(w.w), bfhi(w.w)});
;               v[0] = a.x; v[1] = a.y; v[2] = b2.x; v[3] = b2.y; v[4] = c.x; v[5] = c.y; v[6] = d.x; v[7] = d.y; }
;             float ss = 0.f;
; #pragma unroll
;             for (int k = 0; k < 8; ++k) ss += v[k] * v[k];
;             ss += __shfl_xor(ss, 1); ss += __shfl_xor(ss, 2); ss += __shfl_xor(ss, 4); ss += __shfl_xor(ss, 8);
;             const float rs = rsqrtf(ss * (1.0f / 128.0f) + EPS);
;             u32x4 o; o.x = cvt_pk_bf16(v[0] * rs * g0[0], v[1] * rs * g0[1]); o.y = cvt_pk_bf16(v[2] * rs * g0[2], v[3] * rs * g0[3]);
;             o.z = cvt_pk_bf16(v[4] * rs * g1[0], v[5] * rs * g1[1]); o.w = cvt_pk_bf16(v[6] * rs * g1[2], v[7] * rs * g1[3]);
;             *(u32x4*)(vt + (lrow + 32 * i) * SP + cs) = o; }
	v_pk_mul_f32 v[28:29], v[30:31], v[28:29]
	s_nop 0
	v_pk_mul_f32 v[30:31], v[28:29], v[26:27]
	v_pk_fma_f32 v[28:29], v[28:29], v[26:27], v[26:27] neg_lo:[1,0,0] neg_hi:[1,0,0]
	s_nop 0
	v_cndmask_b32_e32 v27, v29, v31, vcc
	v_cndmask_b32_e64 v26, v28, v30, s[40:41]
	v_pk_mul_f32 v[28:29], v[26:27], v[26:27]
	s_nop 0
	v_add_f32_e32 v28, v28, v32
	v_add_f32_e32 v34, v29, v28
	v_and_b32_e32 v29, 0xffff0000, v10
	v_lshlrev_b32_e32 v28, 16, v10
	v_and_b32_e32 v31, 0x7fffffff, v29
	v_and_b32_e32 v30, 0x7fffffff, v28
	v_pk_fma_f32 v[30:31], v[30:31], s[78:79], 1.0 op_sel_hi:[1,0,0]
	v_cmp_gt_f32_e32 vcc, 0, v29
	v_rcp_f32_e32 v30, v30
	v_rcp_f32_e32 v31, v31
	v_cmp_gt_f32_e64 s[40:41], 0, v28
	v_pk_fma_f32 v[32:33], v[30:31], s[74:75], v[24:25] op_sel_hi:[1,0,0]
	s_nop 0
	v_pk_fma_f32 v[32:33], v[30:31], v[32:33], s[62:63] op_sel_hi:[1,1,0]
	s_nop 0
	v_pk_fma_f32 v[32:33], v[30:31], v[32:33], s[0:1] op_sel_hi:[1,1,0]
	s_nop 0
	v_pk_fma_f32 v[32:33], v[30:31], v[32:33], s[90:91] op_sel_hi:[1,1,0]
	s_nop 0
	v_pk_mul_f32 v[30:31], v[30:31], v[32:33]
	v_pk_mul_f32 v[32:33], v[28:29], v[28:29]
	s_nop 0
	v_pk_mul_f32 v[32:33], v[32:33], s[68:69] op_sel_hi:[1,0]
	s_nop 0
	v_exp_f32_e32 v32, v32
	v_exp_f32_e32 v33, v33
	s_nop 0
	v_pk_mul_f32 v[30:31], v[32:33], v[30:31]
	s_nop 0
	v_pk_mul_f32 v[32:33], v[30:31], v[28:29]
	v_pk_fma_f32 v[30:31], v[30:31], v[28:29], v[28:29] neg_lo:[1,0,0] neg_hi:[1,0,0]
	s_nop 0
	v_cndmask_b32_e32 v29, v31, v33, vcc
	v_cndmask_b32_e64 v28, v30, v32, s[40:41]
	v_pk_mul_f32 v[30:31], v[28:29], v[28:29]
	s_nop 0
	v_add_f32_e32 v30, v30, v34
	v_add_f32_e32 v38, v31, v30
	v_and_b32_e32 v31, 0xffff0000, v11
	v_lshlrev_b32_e32 v30, 16, v11
	v_and_b32_e32 v33, 0x7fffffff, v31
	v_and_b32_e32 v32, 0x7fffffff, v30
	v_pk_fma_f32 v[32:33], v[32:33], s[78:79], 1.0 op_sel_hi:[1,0,0]
	v_cmp_gt_f32_e32 vcc, 0, v31
	v_rcp_f32_e32 v32, v32
	v_rcp_f32_e32 v33, v33
	v_cmp_gt_f32_e64 s[40:41], 0, v30
	v_pk_fma_f32 v[34:35], v[32:33], s[74:75], v[24:25] op_sel_hi:[1,0,0]
	s_nop 0
	v_pk_fma_f32 v[34:35], v[32:33], v[34:35], s[62:63] op_sel_hi:[1,1,0]
	s_nop 0
	v_pk_fma_f32 v[34:35], v[32:33], v[34:35], s[0:1] op_sel_hi:[1,1,0]
	s_nop 0
	v_pk_fma_f32 v[34:35], v[32:33], v[34:35], s[90:91] op_sel_hi:[1,1,0]
	s_nop 0
	v_pk_mul_f32 v[32:33], v[32:33], v[34:35]
	v_pk_mul_f32 v[34:35], v[30:31], v[30:31]
	s_nop 0
	v_pk_mul_f32 v[34:35], v[34:35], s[68:69] op_sel_hi:[1,0]
	s_nop 0
	v_exp_f32_e32 v34, v34
	v_exp_f32_e32 v35, v35
	s_nop 0
	v_pk_mul_f32 v[32:33], v[34:35], v[32:33]
	s_nop 0
	v_pk_mul_f32 v[34:35], v[32:33], v[30:31]
	v_pk_fma_f32 v[32:33], v[32:33], v[30:31], v[30:31] neg_lo:[1,0,0] neg_hi:[1,0,0]
	s_nop 0
	v_cndmask_b32_e32 v35, v33, v35, vcc
	v_cndmask_b32_e64 v34, v32, v34, s[40:41]
	v_pk_mul_f32 v[30:31], v[34:35], v[34:35]
	s_nop 0
	v_add_f32_e32 v30, v30, v38
	v_add_f32_e32 v30, v31, v30
	ds_bpermute_b32 v31, v85, v30
	s_waitcnt lgkmcnt(0)
	v_add_f32_e32 v30, v30, v31
	ds_bpermute_b32 v31, v86, v30
	s_waitcnt lgkmcnt(0)
	v_add_f32_e32 v30, v30, v31
	ds_bpermute_b32 v31, v87, v30
	s_waitcnt lgkmcnt(0)
	v_add_f32_e32 v30, v30, v31
	ds_bpermute_b32 v31, v88, v30
	s_waitcnt lgkmcnt(0)
	v_add_f32_e32 v30, v30, v31
	v_fmamk_f32 v30, v30, 0x3c000000, v208
	v_cmp_gt_f32_e32 vcc, s75, v30
	v_mul_f32_e32 v31, 0x4b800000, v30
	s_nop 0
	v_cndmask_b32_e32 v30, v30, v31, vcc
	v_rsq_f32_e32 v30, v30
	s_nop 0
	v_mul_f32_e32 v31, 0x45800000, v30
	v_cndmask_b32_e32 v33, v30, v31, vcc
	v_mul_f32_e32 v30, v36, v33
	v_mul_f32_e32 v31, v37, v33
	v_mul_f32_e32 v26, v26, v33
	v_mul_f32_e32 v27, v27, v33
	v_mul_f32_e32 v30, v0, v30
	v_mul_f32_e32 v31, v1, v31
	v_mul_f32_e32 v26, v2, v26
	v_mul_f32_e32 v27, v3, v27
	v_cvt_pk_bf16_f32 v30, v30, v31
	v_cvt_pk_bf16_f32 v31, v26, v27
	v_mul_f32_e32 v26, v28, v33
	v_mul_f32_e32 v27, v29, v33
	v_mul_f32_e32 v26, v4, v26
	v_mul_f32_e32 v27, v5, v27
	v_cvt_pk_bf16_f32 v32, v26, v27
	v_mul_f32_e32 v26, v34, v33
	v_mul_f32_e32 v27, v35, v33
	v_mul_f32_e32 v26, v6, v26
	v_mul_f32_e32 v27, v7, v27
	v_cvt_pk_bf16_f32 v33, v26, v27
	v_add3_u32 v28, s24, v152, v41
	s_waitcnt vmcnt(2)
	v_lshlrev_b32_e32 v26, 16, v12
	v_and_b32_e32 v27, 0xffff0000, v12
	ds_write_b128 v28, v[30:33]
	v_and_b32_e32 v31, 0x7fffffff, v27
	v_and_b32_e32 v30, 0x7fffffff, v26
	v_pk_fma_f32 v[30:31], v[30:31], s[78:79], 1.0 op_sel_hi:[1,0,0]
	v_cmp_gt_f32_e32 vcc, 0, v26
	v_rcp_f32_e32 v30, v30
	v_rcp_f32_e32 v31, v31
	s_nop 0
	v_pk_fma_f32 v[32:33], v[30:31], s[74:75], v[24:25] op_sel_hi:[1,0,0]
	s_nop 0
	v_pk_fma_f32 v[32:33], v[30:31], v[32:33], s[62:63] op_sel_hi:[1,1,0]
	s_nop 0
	v_pk_fma_f32 v[32:33], v[30:31], v[32:33], s[0:1] op_sel_hi:[1,1,0]
	s_nop 0
	v_pk_fma_f32 v[32:33], v[30:31], v[32:33], s[90:91] op_sel_hi:[1,1,0]
	s_nop 0
	v_pk_mul_f32 v[30:31], v[30:31], v[32:33]
	v_pk_mul_f32 v[32:33], v[26:27], v[26:27]
	s_nop 0
	v_pk_mul_f32 v[32:33], v[32:33], s[68:69] op_sel_hi:[1,0]
	s_nop 0
	v_exp_f32_e32 v32, v32
	v_exp_f32_e32 v33, v33
	s_nop 0
	v_pk_mul_f32 v[30:31], v[32:33], v[30:31]
	s_nop 0
	v_pk_mul_f32 v[32:33], v[26:27], v[30:31]
	v_pk_fma_f32 v[30:31], v[26:27], v[30:31], v[26:27] neg_lo:[1,0,0] neg_hi:[1,0,0]
	v_lshlrev_b32_e32 v26, 16, v13
	v_cndmask_b32_e32 v29, v30, v32, vcc
	v_cmp_gt_f32_e32 vcc, 0, v27
	v_and_b32_e32 v27, 0xffff0000, v13
	v_and_b32_e32 v30, 0x7fffffff, v26
	v_cndmask_b32_e32 v38, v31, v33, vcc
	v_and_b32_e32 v31, 0x7fffffff, v27
	v_pk_fma_f32 v[30:31], v[30:31], s[78:79], 1.0 op_sel_hi:[1,0,0]
	v_cmp_gt_f32_e32 vcc, 0, v27
	v_rcp_f32_e32 v30, v30
	v_rcp_f32_e32 v31, v31
	v_cmp_gt_f32_e64 s[40:41], 0, v26
	v_mul_f32_e32 v34, v38, v38
	v_fmac_f32_e32 v34, v29, v29
	v_pk_fma_f32 v[32:33], v[30:31], s[74:75], v[24:25] op_sel_hi:[1,0,0]
; __device__ __forceinline__ unsigned cvt_pk_bf16(float lo, float hi) { unsigned r; asm volatile("v_cvt_pk_bf16_f32 %0, %1, %2" : "=v"(r) : "v"(lo), "v"(hi)); return r; }
; __device__ __forceinline__ float bflo(unsigned w) { return __uint_as_float(w << 16); }
; __device__ __forceinline__ float bfhi(unsigned w) { return __uint_as_float(w & 0xffff0000u); }
; PHASE_FN void sgu_block(const Params& p, unsigned char* lds, int l, int g, int ch0, int nch) {
;     ...
;         for (int i = 0; i < 4; ++i) { const u32x4 w = pv[i];
;             float v[8];
;             { const f32x2 a = gelu_pk((f32x2){bflo(w.x), bfhi(w.x)}), b2 = gelu_pk((f32x2){bflo(w.y), bfhi(w.y)}), c = gelu_pk((f32x2){bflo(w.z), bfhi(w.z)}), d = gelu_pk((f32x2){bflo(w.w), bfhi(w.w)});
;               v[0] = a.x; v[1] = a.y; v[2] = b2.x; v[3] = b2.y; v[4] = c.x; v[5] = c.y; v[6] = d.x; v[7] = d.y; }
;             float ss = 0.f;
; #pragma unroll
;             for (int k = 0; k < 8; ++k) ss += v[k] * v[k];
;             ss += __shfl_xor(ss, 1); ss += __shfl_xor(ss, 2); ss += __shfl_xor(ss, 4); ss += __shfl_xor(ss, 8);
;             const float rs = rsqrtf(ss * (1.0f / 128.0f) + EPS);
;             u32x4 o; o.x = cvt_pk_bf16(v[0] * rs * g0[0], v[1] * rs * g0[1]); o.y = cvt_pk_bf16(v[2] * rs * g0[2], v[3] * rs * g0[3]);
;             o.z = cvt_pk_bf16(v[4] * rs * g1[0], v[5] * rs * g1[1]); o.w = cvt_pk_bf16(v[6] * rs * g1[2], v[7] * rs * g1[3]);
	s_nop 0
	v_pk_fma_f32 v[32:33], v[30:31], v[32:33], s[62:63] op_sel_hi:[1,1,0]
	s_nop 0
	v_pk_fma_f32 v[32:33], v[30:31], v[32:33], s[0:1] op_sel_hi:[1,1,0]
	s_nop 0
	v_pk_fma_f32 v[32:33], v[30:31], v[32:33], s[90:91] op_sel_hi:[1,1,0]
	s_nop 0
	v_pk_mul_f32 v[30:31], v[30:31], v[32:33]
	v_pk_mul_f32 v[32:33], v[26:27], v[26:27]
	s_nop 0
	v_pk_mul_f32 v[32:33], v[32:33], s[68:69] op_sel_hi:[1,0]
	s_nop 0
	v_exp_f32_e32 v32, v32
	v_exp_f32_e32 v33, v33
	s_nop 0
	v_pk_mul_f32 v[30:31], v[32:33], v[30:31]
	s_nop 0
	v_pk_mul_f32 v[32:33], v[30:31], v[26:27]
	v_pk_fma_f32 v[30:31], v[30:31], v[26:27], v[26:27] neg_lo:[1,0,0] neg_hi:[1,0,0]
	s_nop 0
	v_cndmask_b32_e32 v27, v31, v33, vcc
	v_cndmask_b32_e64 v26, v30, v32, s[40:41]
	v_pk_mul_f32 v[30:31], v[26:27], v[26:27]
	s_nop 0
	v_add_f32_e32 v30, v30, v34
	v_add_f32_e32 v36, v31, v30
	v_and_b32_e32 v31, 0xffff0000, v14
	v_lshlrev_b32_e32 v30, 16, v14
	v_and_b32_e32 v33, 0x7fffffff, v31
	v_and_b32_e32 v32, 0x7fffffff, v30
	v_pk_fma_f32 v[32:33], v[32:33], s[78:79], 1.0 op_sel_hi:[1,0,0]
	v_cmp_gt_f32_e32 vcc, 0, v31
	v_rcp_f32_e32 v32, v32
	v_rcp_f32_e32 v33, v33
	v_cmp_gt_f32_e64 s[40:41], 0, v30
	v_pk_fma_f32 v[34:35], v[32:33], s[74:75], v[24:25] op_sel_hi:[1,0,0]
	s_nop 0
	v_pk_fma_f32 v[34:35], v[32:33], v[34:35], s[62:63] op_sel_hi:[1,1,0]
	s_nop 0
	v_pk_fma_f32 v[34:35], v[32:33], v[34:35], s[0:1] op_sel_hi:[1,1,0]
	s_nop 0
	v_pk_fma_f32 v[34:35], v[32:33], v[34:35], s[90:91] op_sel_hi:[1,1,0]
	s_nop 0
	v_pk_mul_f32 v[32:33], v[32:33], v[34:35]
	v_pk_mul_f32 v[34:35], v[30:31], v[30:31]
	s_nop 0
	v_pk_mul_f32 v[34:35], v[34:35], s[68:69] op_sel_hi:[1,0]
	s_nop 0
	v_exp_f32_e32 v34, v34
	v_exp_f32_e32 v35, v35
	s_nop 0
	v_pk_mul_f32 v[32:33], v[34:35], v[32:33]
	s_nop 0
	v_pk_mul_f32 v[34:35], v[32:33], v[30:31]
	v_pk_fma_f32 v[32:33], v[32:33], v[30:31], v[30:31] neg_lo:[1,0,0] neg_hi:[1,0,0]
	s_nop 0
	v_cndmask_b32_e32 v33, v33, v35, vcc
	v_cndmask_b32_e64 v32, v32, v34, s[40:41]
	v_pk_mul_f32 v[30:31], v[32:33], v[32:33]
	s_nop 0
	v_add_f32_e32 v30, v30, v36
	v_add_f32_e32 v39, v31, v30
	v_and_b32_e32 v31, 0xffff0000, v15
	v_lshlrev_b32_e32 v30, 16, v15
	v_and_b32_e32 v35, 0x7fffffff, v31
	v_and_b32_e32 v34, 0x7fffffff, v30
	v_pk_fma_f32 v[34:35], v[34:35], s[78:79], 1.0 op_sel_hi:[1,0,0]
	v_cmp_gt_f32_e32 vcc, 0, v31
	v_rcp_f32_e32 v34, v34
	v_rcp_f32_e32 v35, v35
	v_cmp_gt_f32_e64 s[40:41], 0, v30
	v_pk_fma_f32 v[36:37], v[34:35], s[74:75], v[24:25] op_sel_hi:[1,0,0]
	s_nop 0
	v_pk_fma_f32 v[36:37], v[34:35], v[36:37], s[62:63] op_sel_hi:[1,1,0]
	s_nop 0
	v_pk_fma_f32 v[36:37], v[34:35], v[36:37], s[0:1] op_sel_hi:[1,1,0]
	s_nop 0
	v_pk_fma_f32 v[36:37], v[34:35], v[36:37], s[90:91] op_sel_hi:[1,1,0]
	s_nop 0
	v_pk_mul_f32 v[34:35], v[34:35], v[36:37]
	v_pk_mul_f32 v[36:37], v[30:31], v[30:31]
	s_nop 0
	v_pk_mul_f32 v[36:37], v[36:37], s[68:69] op_sel_hi:[1,0]
	s_nop 0
	v_exp_f32_e32 v36, v36
	v_exp_f32_e32 v37, v37
	s_nop 0
	v_pk_mul_f32 v[34:35], v[36:37], v[34:35]
	s_nop 0
	v_pk_mul_f32 v[36:37], v[34:35], v[30:31]
	v_pk_fma_f32 v[34:35], v[34:35], v[30:31], v[30:31] neg_lo:[1,0,0] neg_hi:[1,0,0]
	s_nop 0
	v_cndmask_b32_e32 v35, v35, v37, vcc
	v_cndmask_b32_e64 v34, v34, v36, s[40:41]
	v_pk_mul_f32 v[30:31], v[34:35], v[34:35]
	s_nop 0
	v_add_f32_e32 v30, v30, v39
	v_add_f32_e32 v30, v31, v30
	ds_bpermute_b32 v31, v85, v30
	s_waitcnt lgkmcnt(0)
	v_add_f32_e32 v30, v30, v31
	ds_bpermute_b32 v31, v86, v30
	s_waitcnt lgkmcnt(0)
	v_add_f32_e32 v30, v30, v31
	ds_bpermute_b32 v31, v87, v30
	s_waitcnt lgkmcnt(0)
	v_add_f32_e32 v30, v30, v31
	ds_bpermute_b32 v31, v88, v30
	s_waitcnt lgkmcnt(0)
	v_add_f32_e32 v30, v30, v31
	v_fmamk_f32 v30, v30, 0x3c000000, v208
	v_cmp_gt_f32_e32 vcc, s75, v30
	v_mul_f32_e32 v31, 0x4b800000, v30
	s_nop 0
	v_cndmask_b32_e32 v30, v30, v31, vcc
	v_rsq_f32_e32 v30, v30
	s_nop 0
	v_mul_f32_e32 v31, 0x45800000, v30
	v_cndmask_b32_e32 v36, v30, v31, vcc
	v_mul_f32_e32 v30, v38, v36
	v_mul_f32_e32 v26, v26, v36
	v_mul_f32_e32 v27, v27, v36
	v_mul_f32_e32 v29, v29, v36
	v_mul_f32_e32 v30, v1, v30
	v_mul_f32_e32 v26, v2, v26
	v_mul_f32_e32 v27, v3, v27
	v_mul_f32_e32 v29, v0, v29
	v_cvt_pk_bf16_f32 v30, v29, v30
	v_cvt_pk_bf16_f32 v31, v26, v27
	v_mul_f32_e32 v26, v32, v36
	v_mul_f32_e32 v27, v33, v36
	v_mul_f32_e32 v26, v4, v26
	v_mul_f32_e32 v27, v5, v27
	v_cvt_pk_bf16_f32 v32, v26, v27
	v_mul_f32_e32 v26, v34, v36
	v_mul_f32_e32 v27, v35, v36
	v_mul_f32_e32 v26, v6, v26
	v_mul_f32_e32 v27, v7, v27
	v_cvt_pk_bf16_f32 v33, v26, v27
	s_waitcnt vmcnt(1)
; __device__ __forceinline__ unsigned cvt_pk_bf16(float lo, float hi) { unsigned r; asm volatile("v_cvt_pk_bf16_f32 %0, %1, %2" : "=v"(r) : "v"(lo), "v"(hi)); return r; }
; __device__ __forceinline__ float bflo(unsigned w) { return __uint_as_float(w << 16); }
; __device__ __forceinline__ float bfhi(unsigned w) { return __uint_as_float(w & 0xffff0000u); }
; PHASE_FN void sgu_block(const Params& p, unsigned char* lds, int l, int g, int ch0, int nch) {
;     ...
;         for (int i = 0; i < 4; ++i) { const u32x4 w = pv[i];
;             float v[8];
;             { const f32x2 a = gelu_pk((f32x2){bflo(w.x), bfhi(w.x)}), b2 = gelu_pk((f32x2){bflo(w.y), bfhi(w.y)}), c = gelu_pk((f32x2){bflo(w.z), bfhi(w.z)}), d = gelu_pk((f32x2){bflo(w.w), bfhi(w.w)});
;               v[0] = a.x; v[1] = a.y; v[2] = b2.x; v[3] = b2.y; v[4] = c.x; v[5] = c.y; v[6] = d.x; v[7] = d.y; }
;             float ss = 0.f;
; #pragma unroll
;             for (int k = 0; k < 8; ++k) ss += v[k] * v[k];
;             ss += __shfl_xor(ss, 1); ss += __shfl_xor(ss, 2); ss += __shfl_xor(ss, 4); ss += __shfl_xor(ss, 8);
;             const float rs = rsqrtf(ss * (1.0f / 128.0f) + EPS);
;             u32x4 o; o.x = cvt_pk_bf16(v[0] * rs * g0[0], v[1] * rs * g0[1]); o.y = cvt_pk_bf16(v[2] * rs * g0[2], v[3] * rs * g0[3]);
;             o.z = cvt_pk_bf16(v[4] * rs * g1[0], v[5] * rs * g1[1]); o.w = cvt_pk_bf16(v[6] * rs * g1[2], v[7] * rs * g1[3]);
;             *(u32x4*)(vt + (lrow + 32 * i) * SP + cs) = o; }
	v_lshlrev_b32_e32 v26, 16, v16
	v_and_b32_e32 v27, 0xffff0000, v16
	ds_write_b128 v28, v[30:33] offset:8704
	v_and_b32_e32 v31, 0x7fffffff, v27
	v_and_b32_e32 v30, 0x7fffffff, v26
	v_pk_fma_f32 v[30:31], v[30:31], s[78:79], 1.0 op_sel_hi:[1,0,0]
	v_cmp_gt_f32_e32 vcc, 0, v26
	v_rcp_f32_e32 v30, v30
	v_rcp_f32_e32 v31, v31
	s_nop 0
	v_pk_fma_f32 v[32:33], v[30:31], s[74:75], v[24:25] op_sel_hi:[1,0,0]
	s_nop 0
	v_pk_fma_f32 v[32:33], v[30:31], v[32:33], s[62:63] op_sel_hi:[1,1,0]
	s_nop 0
	v_pk_fma_f32 v[32:33], v[30:31], v[32:33], s[0:1] op_sel_hi:[1,1,0]
	s_nop 0
	v_pk_fma_f32 v[32:33], v[30:31], v[32:33], s[90:91] op_sel_hi:[1,1,0]
	s_nop 0
	v_pk_mul_f32 v[30:31], v[30:31], v[32:33]
	v_pk_mul_f32 v[32:33], v[26:27], v[26:27]
	s_nop 0
	v_pk_mul_f32 v[32:33], v[32:33], s[68:69] op_sel_hi:[1,0]
	s_nop 0
	v_exp_f32_e32 v32, v32
	v_exp_f32_e32 v33, v33
	s_nop 0
	v_pk_mul_f32 v[30:31], v[32:33], v[30:31]
	s_nop 0
	v_pk_mul_f32 v[32:33], v[26:27], v[30:31]
	v_pk_fma_f32 v[30:31], v[26:27], v[30:31], v[26:27] neg_lo:[1,0,0] neg_hi:[1,0,0]
	v_lshlrev_b32_e32 v26, 16, v17
	v_cndmask_b32_e32 v29, v30, v32, vcc
	v_cmp_gt_f32_e32 vcc, 0, v27
	v_and_b32_e32 v27, 0xffff0000, v17
	v_and_b32_e32 v30, 0x7fffffff, v26
	v_cndmask_b32_e32 v38, v31, v33, vcc
	v_and_b32_e32 v31, 0x7fffffff, v27
	v_pk_fma_f32 v[30:31], v[30:31], s[78:79], 1.0 op_sel_hi:[1,0,0]
	v_cmp_gt_f32_e32 vcc, 0, v27
	v_rcp_f32_e32 v30, v30
	v_rcp_f32_e32 v31, v31
	v_cmp_gt_f32_e64 s[40:41], 0, v26
	v_mul_f32_e32 v34, v38, v38
	v_fmac_f32_e32 v34, v29, v29
	v_pk_fma_f32 v[32:33], v[30:31], s[74:75], v[24:25] op_sel_hi:[1,0,0]
	s_nop 0
	v_pk_fma_f32 v[32:33], v[30:31], v[32:33], s[62:63] op_sel_hi:[1,1,0]
	s_nop 0
	v_pk_fma_f32 v[32:33], v[30:31], v[32:33], s[0:1] op_sel_hi:[1,1,0]
	s_nop 0
	v_pk_fma_f32 v[32:33], v[30:31], v[32:33], s[90:91] op_sel_hi:[1,1,0]
	s_nop 0
	v_pk_mul_f32 v[30:31], v[30:31], v[32:33]
	v_pk_mul_f32 v[32:33], v[26:27], v[26:27]
	s_nop 0
	v_pk_mul_f32 v[32:33], v[32:33], s[68:69] op_sel_hi:[1,0]
	s_nop 0
	v_exp_f32_e32 v32, v32
	v_exp_f32_e32 v33, v33
	s_nop 0
	v_pk_mul_f32 v[30:31], v[32:33], v[30:31]
	s_nop 0
	v_pk_mul_f32 v[32:33], v[30:31], v[26:27]
	v_pk_fma_f32 v[30:31], v[30:31], v[26:27], v[26:27] neg_lo:[1,0,0] neg_hi:[1,0,0]
	s_nop 0
	v_cndmask_b32_e32 v27, v31, v33, vcc
	v_cndmask_b32_e64 v26, v30, v32, s[40:41]
	v_pk_mul_f32 v[30:31], v[26:27], v[26:27]
	s_nop 0
	v_add_f32_e32 v30, v30, v34
	v_add_f32_e32 v36, v31, v30
	v_and_b32_e32 v31, 0xffff0000, v18
	v_lshlrev_b32_e32 v30, 16, v18
	v_and_b32_e32 v33, 0x7fffffff, v31
	v_and_b32_e32 v32, 0x7fffffff, v30
	v_pk_fma_f32 v[32:33], v[32:33], s[78:79], 1.0 op_sel_hi:[1,0,0]
	v_cmp_gt_f32_e32 vcc, 0, v31
	v_rcp_f32_e32 v32, v32
	v_rcp_f32_e32 v33, v33
	v_cmp_gt_f32_e64 s[40:41], 0, v30
	v_pk_fma_f32 v[34:35], v[32:33], s[74:75], v[24:25] op_sel_hi:[1,0,0]
	s_nop 0
	v_pk_fma_f32 v[34:35], v[32:33], v[34:35], s[62:63] op_sel_hi:[1,1,0]
	s_nop 0
	v_pk_fma_f32 v[34:35], v[32:33], v[34:35], s[0:1] op_sel_hi:[1,1,0]
	s_nop 0
	v_pk_fma_f32 v[34:35], v[32:33], v[34:35], s[90:91] op_sel_hi:[1,1,0]
	s_nop 0
	v_pk_mul_f32 v[32:33], v[32:33], v[34:35]
	v_pk_mul_f32 v[34:35], v[30:31], v[30:31]
	s_nop 0
	v_pk_mul_f32 v[34:35], v[34:35], s[68:69] op_sel_hi:[1,0]
	s_nop 0
	v_exp_f32_e32 v34, v34
	v_exp_f32_e32 v35, v35
	s_nop 0
	v_pk_mul_f32 v[32:33], v[34:35], v[32:33]
	s_nop 0
	v_pk_mul_f32 v[34:35], v[32:33], v[30:31]
	v_pk_fma_f32 v[32:33], v[32:33], v[30:31], v[30:31] neg_lo:[1,0,0] neg_hi:[1,0,0]
	s_nop 0
	v_cndmask_b32_e32 v33, v33, v35, vcc
	v_cndmask_b32_e64 v32, v32, v34, s[40:41]
	v_pk_mul_f32 v[30:31], v[32:33], v[32:33]
	s_nop 0
	v_add_f32_e32 v30, v30, v36
	v_add_f32_e32 v39, v31, v30
	v_and_b32_e32 v31, 0xffff0000, v19
	v_lshlrev_b32_e32 v30, 16, v19
	v_and_b32_e32 v35, 0x7fffffff, v31
	v_and_b32_e32 v34, 0x7fffffff, v30
	v_pk_fma_f32 v[34:35], v[34:35], s[78:79], 1.0 op_sel_hi:[1,0,0]
	v_cmp_gt_f32_e32 vcc, 0, v31
	v_rcp_f32_e32 v34, v34
	v_rcp_f32_e32 v35, v35
	v_cmp_gt_f32_e64 s[40:41], 0, v30
	v_pk_fma_f32 v[36:37], v[34:35], s[74:75], v[24:25] op_sel_hi:[1,0,0]
	s_nop 0
	v_pk_fma_f32 v[36:37], v[34:35], v[36:37], s[62:63] op_sel_hi:[1,1,0]
	s_nop 0
	v_pk_fma_f32 v[36:37], v[34:35], v[36:37], s[0:1] op_sel_hi:[1,1,0]
	s_nop 0
	v_pk_fma_f32 v[36:37], v[34:35], v[36:37], s[90:91] op_sel_hi:[1,1,0]
	s_nop 0
	v_pk_mul_f32 v[34:35], v[34:35], v[36:37]
	v_pk_mul_f32 v[36:37], v[30:31], v[30:31]
	s_nop 0
	v_pk_mul_f32 v[36:37], v[36:37], s[68:69] op_sel_hi:[1,0]
	s_nop 0
	v_exp_f32_e32 v36, v36
	v_exp_f32_e32 v37, v37
	s_nop 0
	v_pk_mul_f32 v[34:35], v[36:37], v[34:35]
	s_nop 0
	v_pk_mul_f32 v[36:37], v[34:35], v[30:31]
	v_pk_fma_f32 v[34:35], v[34:35], v[30:31], v[30:31] neg_lo:[1,0,0] neg_hi:[1,0,0]
	s_nop 0
	v_cndmask_b32_e32 v35, v35, v37, vcc
	v_cndmask_b32_e64 v34, v34, v36, s[40:41]
	v_pk_mul_f32 v[30:31], v[34:35], v[34:35]
	s_nop 0
	v_add_f32_e32 v30, v30, v39
	v_add_f32_e32 v30, v31, v30
	ds_bpermute_b32 v31, v85, v30
	s_waitcnt lgkmcnt(0)
	v_add_f32_e32 v30, v30, v31
	ds_bpermute_b32 v31, v86, v30
	s_waitcnt lgkmcnt(0)
	v_add_f32_e32 v30, v30, v31
	ds_bpermute_b32 v31, v87, v30
	s_waitcnt lgkmcnt(0)
	v_add_f32_e32 v30, v30, v31
	ds_bpermute_b32 v31, v88, v30
	s_waitcnt lgkmcnt(0)
; __device__ __forceinline__ unsigned cvt_pk_bf16(float lo, float hi) { unsigned r; asm volatile("v_cvt_pk_bf16_f32 %0, %1, %2" : "=v"(r) : "v"(lo), "v"(hi)); return r; }
; __device__ __forceinline__ float bflo(unsigned w) { return __uint_as_float(w << 16); }
; __device__ __forceinline__ float bfhi(unsigned w) { return __uint_as_float(w & 0xffff0000u); }
; PHASE_FN void sgu_block(const Params& p, unsigned char* lds, int l, int g, int ch0, int nch) {
;     ...
;         for (int i = 0; i < 4; ++i) { const u32x4 w = pv[i];
;             float v[8];
;             { const f32x2 a = gelu_pk((f32x2){bflo(w.x), bfhi(w.x)}), b2 = gelu_pk((f32x2){bflo(w.y), bfhi(w.y)}), c = gelu_pk((f32x2){bflo(w.z), bfhi(w.z)}), d = gelu_pk((f32x2){bflo(w.w), bfhi(w.w)});
;               v[0] = a.x; v[1] = a.y; v[2] = b2.x; v[3] = b2.y; v[4] = c.x; v[5] = c.y; v[6] = d.x; v[7] = d.y; }
;             float ss = 0.f;
; #pragma unroll
;             for (int k = 0; k < 8; ++k) ss += v[k] * v[k];
;             ss += __shfl_xor(ss, 1); ss += __shfl_xor(ss, 2); ss += __shfl_xor(ss, 4); ss += __shfl_xor(ss, 8);
;             const float rs = rsqrtf(ss * (1.0f / 128.0f) + EPS);
;             u32x4 o; o.x = cvt_pk_bf16(v[0] * rs * g0[0], v[1] * rs * g0[1]); o.y = cvt_pk_bf16(v[2] * rs * g0[2], v[3] * rs * g0[3]);
;             o.z = cvt_pk_bf16(v[4] * rs * g1[0], v[5] * rs * g1[1]); o.w = cvt_pk_bf16(v[6] * rs * g1[2], v[7] * rs * g1[3]);
;             *(u32x4*)(vt + (lrow + 32 * i) * SP + cs) = o; }
	v_add_f32_e32 v30, v30, v31
	v_fmamk_f32 v30, v30, 0x3c000000, v208
	v_cmp_gt_f32_e32 vcc, s75, v30
	v_mul_f32_e32 v31, 0x4b800000, v30
	s_nop 0
	v_cndmask_b32_e32 v30, v30, v31, vcc
	v_rsq_f32_e32 v30, v30
	s_nop 0
	v_mul_f32_e32 v31, 0x45800000, v30
	v_cndmask_b32_e32 v36, v30, v31, vcc
	v_mul_f32_e32 v30, v38, v36
	v_mul_f32_e32 v26, v26, v36
	v_mul_f32_e32 v27, v27, v36
	v_mul_f32_e32 v29, v29, v36
	v_mul_f32_e32 v30, v1, v30
	v_mul_f32_e32 v26, v2, v26
	v_mul_f32_e32 v27, v3, v27
	v_mul_f32_e32 v29, v0, v29
	v_cvt_pk_bf16_f32 v30, v29, v30
	v_cvt_pk_bf16_f32 v31, v26, v27
	v_mul_f32_e32 v26, v32, v36
	v_mul_f32_e32 v27, v33, v36
	v_mul_f32_e32 v26, v4, v26
	v_mul_f32_e32 v27, v5, v27
	v_cvt_pk_bf16_f32 v32, v26, v27
	v_mul_f32_e32 v26, v34, v36
	v_mul_f32_e32 v27, v35, v36
	v_mul_f32_e32 v26, v6, v26
	v_mul_f32_e32 v27, v7, v27
	v_cvt_pk_bf16_f32 v33, v26, v27
	s_waitcnt vmcnt(0)
	v_lshlrev_b32_e32 v26, 16, v20
	v_and_b32_e32 v27, 0xffff0000, v20
	ds_write_b128 v28, v[30:33] offset:17408
	v_and_b32_e32 v31, 0x7fffffff, v27
	v_and_b32_e32 v30, 0x7fffffff, v26
	v_pk_fma_f32 v[30:31], v[30:31], s[78:79], 1.0 op_sel_hi:[1,0,0]
	v_cmp_gt_f32_e32 vcc, 0, v26
	v_rcp_f32_e32 v30, v30
	v_rcp_f32_e32 v31, v31
	s_nop 0
	v_pk_fma_f32 v[32:33], v[30:31], s[74:75], v[24:25] op_sel_hi:[1,0,0]
	s_nop 0
	v_pk_fma_f32 v[32:33], v[30:31], v[32:33], s[62:63] op_sel_hi:[1,1,0]
	s_nop 0
	v_pk_fma_f32 v[32:33], v[30:31], v[32:33], s[0:1] op_sel_hi:[1,1,0]
	s_nop 0
	v_pk_fma_f32 v[32:33], v[30:31], v[32:33], s[90:91] op_sel_hi:[1,1,0]
	s_nop 0
	v_pk_mul_f32 v[30:31], v[30:31], v[32:33]
	v_pk_mul_f32 v[32:33], v[26:27], v[26:27]
	s_nop 0
	v_pk_mul_f32 v[32:33], v[32:33], s[68:69] op_sel_hi:[1,0]
	s_nop 0
	v_exp_f32_e32 v32, v32
	v_exp_f32_e32 v33, v33
	s_nop 0
	v_pk_mul_f32 v[30:31], v[32:33], v[30:31]
	s_nop 0
	v_pk_mul_f32 v[32:33], v[26:27], v[30:31]
	v_pk_fma_f32 v[30:31], v[26:27], v[30:31], v[26:27] neg_lo:[1,0,0] neg_hi:[1,0,0]
	v_lshlrev_b32_e32 v26, 16, v21
	v_cndmask_b32_e32 v29, v30, v32, vcc
	v_cmp_gt_f32_e32 vcc, 0, v27
	v_and_b32_e32 v27, 0xffff0000, v21
	v_and_b32_e32 v30, 0x7fffffff, v26
	v_cndmask_b32_e32 v36, v31, v33, vcc
	v_and_b32_e32 v31, 0x7fffffff, v27
	v_pk_fma_f32 v[30:31], v[30:31], s[78:79], 1.0 op_sel_hi:[1,0,0]
	v_cmp_gt_f32_e32 vcc, 0, v27
	v_rcp_f32_e32 v30, v30
	v_rcp_f32_e32 v31, v31
	v_cmp_gt_f32_e64 s[40:41], 0, v26
	v_mul_f32_e32 v34, v36, v36
	v_fmac_f32_e32 v34, v29, v29
	v_pk_fma_f32 v[32:33], v[30:31], s[74:75], v[24:25] op_sel_hi:[1,0,0]
	s_nop 0
	v_pk_fma_f32 v[32:33], v[30:31], v[32:33], s[62:63] op_sel_hi:[1,1,0]
	s_nop 0
	v_pk_fma_f32 v[32:33], v[30:31], v[32:33], s[0:1] op_sel_hi:[1,1,0]
	s_nop 0
	v_pk_fma_f32 v[32:33], v[30:31], v[32:33], s[90:91] op_sel_hi:[1,1,0]
	s_nop 0
	v_pk_mul_f32 v[30:31], v[30:31], v[32:33]
	v_pk_mul_f32 v[32:33], v[26:27], v[26:27]
	s_nop 0
	v_pk_mul_f32 v[32:33], v[32:33], s[68:69] op_sel_hi:[1,0]
	s_nop 0
	v_exp_f32_e32 v32, v32
	v_exp_f32_e32 v33, v33
	s_nop 0
	v_pk_mul_f32 v[30:31], v[32:33], v[30:31]
	s_nop 0
	v_pk_mul_f32 v[32:33], v[30:31], v[26:27]
	v_pk_fma_f32 v[30:31], v[30:31], v[26:27], v[26:27] neg_lo:[1,0,0] neg_hi:[1,0,0]
	s_nop 0
	v_cndmask_b32_e32 v27, v31, v33, vcc
	v_cndmask_b32_e64 v26, v30, v32, s[40:41]
	v_pk_mul_f32 v[30:31], v[26:27], v[26:27]
	s_nop 0
	v_add_f32_e32 v30, v30, v34
	v_add_f32_e32 v37, v31, v30
	v_and_b32_e32 v31, 0xffff0000, v22
	v_lshlrev_b32_e32 v30, 16, v22
	v_and_b32_e32 v33, 0x7fffffff, v31
	v_and_b32_e32 v32, 0x7fffffff, v30
	v_pk_fma_f32 v[32:33], v[32:33], s[78:79], 1.0 op_sel_hi:[1,0,0]
	v_cmp_gt_f32_e32 vcc, 0, v31
	v_rcp_f32_e32 v32, v32
	v_rcp_f32_e32 v33, v33
	v_cmp_gt_f32_e64 s[40:41], 0, v30
	v_pk_fma_f32 v[34:35], v[32:33], s[74:75], v[24:25] op_sel_hi:[1,0,0]
	s_nop 0
	v_pk_fma_f32 v[34:35], v[32:33], v[34:35], s[62:63] op_sel_hi:[1,1,0]
	s_nop 0
	v_pk_fma_f32 v[34:35], v[32:33], v[34:35], s[0:1] op_sel_hi:[1,1,0]
	s_nop 0
	v_pk_fma_f32 v[34:35], v[32:33], v[34:35], s[90:91] op_sel_hi:[1,1,0]
	s_nop 0
	v_pk_mul_f32 v[32:33], v[32:33], v[34:35]
	v_pk_mul_f32 v[34:35], v[30:31], v[30:31]
	s_nop 0
	v_pk_mul_f32 v[34:35], v[34:35], s[68:69] op_sel_hi:[1,0]
	s_nop 0
	v_exp_f32_e32 v34, v34
	v_exp_f32_e32 v35, v35
	s_nop 0
	v_pk_mul_f32 v[32:33], v[34:35], v[32:33]
	s_nop 0
	v_pk_mul_f32 v[34:35], v[32:33], v[30:31]
	v_pk_fma_f32 v[32:33], v[32:33], v[30:31], v[30:31] neg_lo:[1,0,0] neg_hi:[1,0,0]
	s_nop 0
	v_cndmask_b32_e32 v31, v33, v35, vcc
	v_cndmask_b32_e64 v30, v32, v34, s[40:41]
	v_pk_mul_f32 v[32:33], v[30:31], v[30:31]
	s_nop 0
	v_add_f32_e32 v32, v32, v37
	v_add_f32_e32 v37, v33, v32
	v_and_b32_e32 v33, 0xffff0000, v23
	v_lshlrev_b32_e32 v32, 16, v23
	v_and_b32_e32 v35, 0x7fffffff, v33
	v_and_b32_e32 v34, 0x7fffffff, v32
	v_pk_fma_f32 v[34:35], v[34:35], s[78:79], 1.0 op_sel_hi:[1,0,0]
	v_cmp_gt_f32_e32 vcc, 0, v33
	v_rcp_f32_e32 v34, v34
	v_rcp_f32_e32 v35, v35
	v_cmp_gt_f32_e64 s[40:41], 0, v32
	v_pk_fma_f32 v[24:25], v[34:35], s[74:75], v[24:25] op_sel_hi:[1,0,0]
	s_nop 0
	v_pk_fma_f32 v[24:25], v[34:35], v[24:25], s[62:63] op_sel_hi:[1,1,0]
	s_nop 0
	v_pk_fma_f32 v[24:25], v[34:35], v[24:25], s[0:1] op_sel_hi:[1,1,0]
	s_nop 0
	v_pk_fma_f32 v[24:25], v[34:35], v[24:25], s[90:91] op_sel_hi:[1,1,0]
	s_nop 0
	v_pk_mul_f32 v[24:25], v[34:35], v[24:25]
	v_pk_mul_f32 v[34:35], v[32:33], v[32:33]
	s_nop 0
	v_pk_mul_f32 v[34:35], v[34:35], s[68:69] op_sel_hi:[1,0]
	s_nop 0
	v_exp_f32_e32 v34, v34
	v_exp_f32_e32 v35, v35
	s_nop 0
	v_pk_mul_f32 v[24:25], v[34:35], v[24:25]
	s_nop 0
	v_pk_mul_f32 v[34:35], v[24:25], v[32:33]
	v_pk_fma_f32 v[24:25], v[24:25], v[32:33], v[32:33] neg_lo:[1,0,0] neg_hi:[1,0,0]
	s_nop 0
	v_cndmask_b32_e32 v33, v25, v35, vcc
	v_cndmask_b32_e64 v32, v24, v34, s[40:41]
	v_pk_mul_f32 v[24:25], v[32:33], v[32:33]
	s_nop 0
	v_add_f32_e32 v24, v24, v37
	v_add_f32_e32 v24, v25, v24
	ds_bpermute_b32 v25, v85, v24
	s_waitcnt lgkmcnt(0)
; __device__ __forceinline__ unsigned cvt_pk_bf16(float lo, float hi) { unsigned r; asm volatile("v_cvt_pk_bf16_f32 %0, %1, %2" : "=v"(r) : "v"(lo), "v"(hi)); return r; }
; __device__ __forceinline__ float bflo(unsigned w) { return __uint_as_float(w << 16); }
; __device__ __forceinline__ float bfhi(unsigned w) { return __uint_as_float(w & 0xffff0000u); }
; #define SGU_LOAD(ch) do { _Pragma("unroll") for (int i = 0; i < 4; ++i) pv[i] = *(const u32x4*)(Z + (size_t)((ch) * 128 + lrow + 32 * i) * ZW + ZSV + g * 128 + cs); } while (0)
; PHASE_FN void sgu_block(const Params& p, unsigned char* lds, int l, int g, int ch0, int nch) {
;     ...
;         for (int i = 0; i < 4; ++i) { const u32x4 w = pv[i];
;             float v[8];
;             { const f32x2 a = gelu_pk((f32x2){bflo(w.x), bfhi(w.x)}), b2 = gelu_pk((f32x2){bflo(w.y), bfhi(w.y)}), c = gelu_pk((f32x2){bflo(w.z), bfhi(w.z)}), d = gelu_pk((f32x2){bflo(w.w), bfhi(w.w)});
;               v[0] = a.x; v[1] = a.y; v[2] = b2.x; v[3] = b2.y; v[4] = c.x; v[5] = c.y; v[6] = d.x; v[7] = d.y; }
;             float ss = 0.f;
; #pragma unroll
;             for (int k = 0; k < 8; ++k) ss += v[k] * v[k];
;             ss += __shfl_xor(ss, 1); ss += __shfl_xor(ss, 2); ss += __shfl_xor(ss, 4); ss += __shfl_xor(ss, 8);
;             const float rs = rsqrtf(ss * (1.0f / 128.0f) + EPS);
;             u32x4 o; o.x = cvt_pk_bf16(v[0] * rs * g0[0], v[1] * rs * g0[1]); o.y = cvt_pk_bf16(v[2] * rs * g0[2], v[3] * rs * g0[3]);
;             o.z = cvt_pk_bf16(v[4] * rs * g1[0], v[5] * rs * g1[1]); o.w = cvt_pk_bf16(v[6] * rs * g1[2], v[7] * rs * g1[3]);
;             *(u32x4*)(vt + (lrow + 32 * i) * SP + cs) = o; }
;         if (ch + 1 < ch0 + nch) SGU_LOAD(ch + 1);
	v_add_f32_e32 v24, v24, v25
	ds_bpermute_b32 v25, v86, v24
	s_waitcnt lgkmcnt(0)
	v_add_f32_e32 v24, v24, v25
	ds_bpermute_b32 v25, v87, v24
	s_waitcnt lgkmcnt(0)
	v_add_f32_e32 v24, v24, v25
	ds_bpermute_b32 v25, v88, v24
	s_waitcnt lgkmcnt(0)
	v_add_f32_e32 v24, v24, v25
	v_fmamk_f32 v24, v24, 0x3c000000, v208
	v_cmp_gt_f32_e32 vcc, s75, v24
	v_mul_f32_e32 v25, 0x4b800000, v24
	s_nop 0
	v_cndmask_b32_e32 v24, v24, v25, vcc
	v_rsq_f32_e32 v24, v24
	s_nop 0
	v_mul_f32_e32 v25, 0x45800000, v24
	v_cndmask_b32_e32 v34, v24, v25, vcc
	v_mul_f32_e32 v24, v29, v34
	v_mul_f32_e32 v25, v36, v34
	v_mul_f32_e32 v24, v0, v24
	v_mul_f32_e32 v25, v1, v25
	v_cvt_pk_bf16_f32 v24, v24, v25
	v_mul_f32_e32 v25, v26, v34
	v_mul_f32_e32 v26, v27, v34
	v_mul_f32_e32 v25, v2, v25
	v_mul_f32_e32 v26, v3, v26
	v_cvt_pk_bf16_f32 v25, v25, v26
	v_mul_f32_e32 v26, v30, v34
	v_mul_f32_e32 v27, v31, v34
	v_mul_f32_e32 v26, v4, v26
	v_mul_f32_e32 v27, v5, v27
	v_cvt_pk_bf16_f32 v26, v26, v27
	v_mul_f32_e32 v27, v32, v34
	v_mul_f32_e32 v27, v6, v27
	v_mul_f32_e32 v29, v33, v34
	v_mul_f32_e32 v29, v7, v29
	v_cvt_pk_bf16_f32 v27, v27, v29
	ds_write_b128 v28, v[24:27] offset:26112
	s_cbranch_scc1 .LBB0_253
	v_add_u32_e32 v20, s12, v90
	v_add_u32_e32 v8, 0xffff0080, v20
	v_mov_b64_e32 v[16:17], s[60:61]
	v_mad_i64_i32 v[8:9], s[14:15], v8, s1, v[16:17]
	v_lshl_add_u64 v[8:9], v[8:9], 0, s[76:77]
	v_add_u32_e32 v10, 0xffff00a0, v20
	v_lshl_add_u64 v[8:9], v[8:9], 0, v[152:153]
	v_mad_i64_i32 v[10:11], s[14:15], v10, s1, v[16:17]
	v_add_co_u32_e32 v8, vcc, 0x1000, v8
	v_lshl_add_u64 v[10:11], v[10:11], 0, s[76:77]
	v_add_u32_e32 v18, 0xffff00c0, v20
	v_addc_co_u32_e32 v9, vcc, 0, v9, vcc
	v_lshl_add_u64 v[10:11], v[10:11], 0, v[152:153]
	v_mad_i64_i32 v[18:19], s[14:15], v18, s1, v[16:17]
	v_add_co_u32_e32 v12, vcc, 0x1000, v10
	v_lshl_add_u64 v[18:19], v[18:19], 0, s[76:77]
	v_add_u32_e32 v20, 0xffff00e0, v20
	v_addc_co_u32_e32 v13, vcc, 0, v11, vcc
	v_lshl_add_u64 v[18:19], v[18:19], 0, v[152:153]
	v_mad_i64_i32 v[16:17], s[14:15], v20, s1, v[16:17]
	v_add_co_u32_e32 v18, vcc, 0x1000, v18
	v_lshl_add_u64 v[16:17], v[16:17], 0, s[76:77]
	s_nop 0
	v_addc_co_u32_e32 v19, vcc, 0, v19, vcc
	v_lshl_add_u64 v[16:17], v[16:17], 0, v[152:153]
	v_add_co_u32_e32 v20, vcc, 0x1000, v16
	global_load_dwordx4 v[8:11], v[8:9], off offset:512 nt
	s_nop 0
	global_load_dwordx4 v[12:15], v[12:13], off offset:512 nt
	v_addc_co_u32_e32 v21, vcc, 0, v17, vcc
	global_load_dwordx4 v[16:19], v[18:19], off offset:512 nt
	s_nop 0
	global_load_dwordx4 v[20:23], v[20:21], off offset:512 nt
	s_branch .LBB0_253

; #define GLA_BAR() do { asm volatile("s_waitcnt lgkmcnt(0)" ::: "memory"); __builtin_amdgcn_s_barrier(); asm volatile("" ::: "memory"); } while (0)
; __device__ __forceinline__ void gla_mma(const Params& p, unsigned char* lds, int l, int item, int tid) {
;     ...
;     const int wid = __builtin_amdgcn_readfirstlane(tid >> 6), lane = tid & 63, lr = lane & 15, q4 = lane >> 4;
;     const int b = item >> 3, h = (item >> 1) & 3, dir = item & 1;
;     const bf16_t* Z = (const bf16_t*)(ws + WS_Z); bf16_t* OX = (bf16_t*)(ws + WS_OX); bf16_t* MIX = (bf16_t*)(ws + WS_MIX);
;     const bf16_t* qin = (const bf16_t*)(lds + L_QIN); const bf16_t* kin = (const bf16_t*)(lds + L_KIN); const bf16_t* qout = (const bf16_t*)(lds + L_QOUT); const bf16_t* koutT = (const bf16_t*)(lds + L_KOUTT);
;     const float* decs = (const float*)(lds + L_DEC); float* red = (float*)(lds + L_RED); const bf16_t* vraw = (const bf16_t*)(lds + L_VRAW);
;     const int vq = wid & 3;
;     const int ocol = h * 128 + 32 * vq + 8 * q4;
;     f32x4 ng[2];
; #pragma unroll
;     for (int vb = 0; vb < 2; ++vb) ng[vb] = *(const f32x4*)(p.gla_norm_g + (size_t)l * 512 + ocol + 4 * vb);
;     f32x4 accS[2][4];
; #pragma unroll
;     for (int vb = 0; vb < 2; ++vb)
; #pragma unroll
;         for (int i = 0; i < 4; ++i) accS[vb][i] = (f32x4){0.f, 0.f, 0.f, 0.f};
;     GLA_BAR();
.LBB0_257:
	s_andn2_b64 vcc, exec, s[24:25]
	s_cbranch_vccnz .LBB0_353
	v_mov_b32_e32 v106, v206
	s_movk_i32 s4, 0xff
	v_and_b32_e32 v108, 15, v106
	v_cmp_lt_i32_e32 vcc, s4, v106
	v_bfe_u32 v107, v106, 4, 2
	v_and_b32_e32 v112, 3, v106
	v_lshlrev_b32_e32 v111, 2, v108
	s_and_saveexec_b64 s[4:5], vcc
	s_xor_b64 s[24:25], exec, s[4:5]
	s_cbranch_execz .LBB0_282
	v_readfirstlane_b32 s4, v106
	s_bfe_u32 s6, s4, 0x20006
	v_lshlrev_b32_e32 v9, 3, v107
	v_readlane_b32 s4, v247, 38
	v_readlane_b32 s36, v248, 0
	v_readlane_b32 s50, v248, 14
	v_or_b32_e32 v0, s4, v9
	v_readlane_b32 s4, v246, 56
	v_readlane_b32 s51, v248, 15
	s_lshl_b32 s4, s4, 11
	s_mov_b64 s[26:27], s[50:51]
	v_lshl_or_b32 v8, s6, 5, v0
	v_readlane_b32 s5, v246, 57
	s_add_u32 s4, s26, s4
	s_addc_u32 s5, s27, 0
	v_lshlrev_b32_e32 v4, 2, v8
	s_nop 1
	global_load_dwordx4 v[0:3], v4, s[4:5] offset:16 nt
	s_nop 0
	global_load_dwordx4 v[4:7], v4, s[4:5] nt
	s_lshl_b32 s4, s6, 6
	v_lshlrev_b32_e32 v11, 2, v106
	s_add_i32 s4, s4, 0
	v_and_b32_e32 v11, 48, v11
	v_lshlrev_b32_e32 v12, 1, v112
	v_add3_u32 v11, s4, v11, v12
	v_readlane_b32 s4, v247, 36
	v_mul_u32_u24_e32 v143, 0x240, v107
	v_lshlrev_b32_e32 v152, 1, v8
	v_readlane_b32 s5, v247, 37
	v_lshl_add_u32 v14, v143, 1, 0
	v_lshlrev_b32_e32 v10, 2, v107
	s_waitcnt lgkmcnt(0)
	v_lshl_add_u64 v[136:137], s[4:5], 0, v[152:153]
	s_movk_i32 s4, 0xfb90
	v_mad_i32_i24 v144, v107, s4, v14
	s_lshl_b32 s4, s6, 8
	v_readlane_b32 s6, v246, 26
	v_readlane_b32 s7, v246, 27
	v_cmp_ge_u32_e32 vcc, v108, v10
	s_movk_i32 s5, 0x420
	v_lshl_add_u64 v[138:139], s[6:7], 0, v[152:153]
	v_cndmask_b32_e64 v28, 0, 1, vcc
	v_cmp_gt_u32_e32 vcc, v108, v10
	v_readlane_b32 s6, v247, 42
	v_readlane_b32 s7, v247, 43
	v_cndmask_b32_e64 v29, 0, 1, vcc
	v_readlane_b32 s42, v248, 6
	v_cndmask_b32_e64 v28, v29, v28, s[6:7]
	v_readlane_b32 s43, v248, 7
	v_mad_u32_u24 v19, v107, s5, v210
	v_mad_u32_u24 v20, v107, s5, v211
	v_mad_u32_u24 v21, v107, s5, v212
	v_mad_u32_u24 v22, v107, s5, v213
	v_mad_u32_u24 v23, v107, s5, v214
	v_mad_u32_u24 v24, v107, s5, v215
	v_and_b32_e32 v28, 1, v28
	v_readlane_b32 s5, v247, 52
	v_readlane_b32 s44, v248, 8
	v_readlane_b32 s45, v248, 9
	v_cmp_eq_u32_e64 s[42:43], 1, v28
	v_or_b32_e32 v28, s5, v10
	v_cmp_gt_u32_e64 s[44:45], v108, v28
	v_or_b32_e32 v28, 2, v10
	v_cmp_ge_u32_e32 vcc, v108, v28
	v_or_b32_e32 v16, 32, v10
	v_or_b32_e32 v10, 3, v10
	v_cndmask_b32_e64 v29, 0, 1, vcc
	v_cmp_gt_u32_e32 vcc, v108, v28
	v_readlane_b32 s46, v248, 10
	v_readlane_b32 s47, v248, 11
	v_cndmask_b32_e64 v28, 0, 1, vcc
	v_cndmask_b32_e64 v28, v28, v29, s[6:7]
	v_and_b32_e32 v28, 1, v28
	v_cmp_ge_u32_e32 vcc, v108, v10
	v_bfe_u32 v12, v106, 2, 2
	v_cmp_eq_u32_e64 s[46:47], 1, v28
	v_cndmask_b32_e64 v28, 0, 1, vcc
	v_cmp_gt_u32_e32 vcc, v108, v10
	v_mul_u32_u24_e32 v12, 0x48, v12
	v_and_b32_e32 v13, 12, v111
	v_cndmask_b32_e64 v10, 0, 1, vcc
	v_add_lshl_u32 v12, v13, v12, 1
	v_cndmask_b32_e64 v10, v10, v28, s[6:7]
	v_readlane_b32 s48, v248, 12
	v_readlane_b32 s49, v248, 13
	s_waitcnt lgkmcnt(0)
	s_barrier
	v_bitop3_b32 v15, v106, 63, 15 bitop3:0x6c
	v_add_u32_e32 v145, v14, v12
	v_bitop3_b32 v14, v106, 31, 15 bitop3:0x6c
	v_or_b32_e32 v25, 32, v108
	v_bitop3_b32 v26, v106, 15, v106 bitop3:0xc
	v_or_b32_e32 v27, 48, v108
	v_and_b32_e32 v10, 1, v10
	v_add_u32_e32 v146, 0, v12
	s_movk_i32 s5, 0x240
	v_mov_b32_e32 v52, v153
	v_mov_b32_e32 v53, v153
	v_mov_b32_e32 v54, v153
	v_mov_b32_e32 v55, v153
	v_readlane_b32 s40, v248, 4
	v_readlane_b32 s41, v248, 5
	v_readlane_b32 s50, v246, 43
	v_sub_u32_e32 v9, v144, v9
	v_mul_u32_u24_e32 v17, 0x108, v16
	v_mul_u32_u24_e32 v18, 0x420, v107
	v_or_b32_e32 v13, 16, v108
	v_cmp_eq_u32_e64 s[48:49], 1, v10
	v_mad_u32_u24 v147, v107, s5, v146
	v_mul_u32_u24_e32 v10, 0x90, v16
	s_movk_i32 s5, 0x90
	v_mul_u32_u24_e32 v12, 0x90, v108
	v_cndmask_b32_e64 v149, v15, v108, s[6:7]
	v_bitop3_b32 v15, v106, 47, 15 bitop3:0x6c
	v_cndmask_b32_e64 v151, v14, v25, s[6:7]
	v_cndmask_b32_e64 v162, v26, v27, s[6:7]
	v_add_u32_e32 v170, v11, v24
	v_mov_b64_e32 v[66:67], v[54:55]
	v_mov_b64_e32 v[44:45], v[52:53]
	v_mov_b64_e32 v[24:25], v[52:53]
	v_mov_b64_e32 v[70:71], v[54:55]
	v_mov_b64_e32 v[62:63], v[54:55]
	v_mov_b64_e32 v[40:41], v[52:53]
	v_mov_b64_e32 v[28:29], v[52:53]
	v_readlane_b32 s51, v246, 44
	v_add_u32_e32 v142, 0, v111
	v_cmp_eq_u32_e64 s[40:41], 0, v107
	v_mad_u32_u24 v148, v16, s5, v146
	v_cndmask_b32_e64 v150, v15, v13, s[6:7]
	s_movk_i32 s5, 0xffe0
	v_add_u32_e32 v163, v11, v18
	v_add_u32_e32 v164, v11, v17
	v_add_u32_e32 v165, v11, v19
	v_add_u32_e32 v166, v11, v20
	v_add_u32_e32 v167, v11, v21
	v_add_u32_e32 v168, v11, v22
	v_add_u32_e32 v169, v11, v23
	v_lshlrev_b32_e32 v152, 1, v8
	v_add_u32_e32 v171, v146, v10
	v_add_u32_e32 v172, v9, v12
	v_mov_b64_e32 v[64:65], v[52:53]
	v_mov_b64_e32 v[46:47], v[54:55]
	v_mov_b64_e32 v[26:27], v[54:55]
	v_mov_b64_e32 v[68:69], v[52:53]
	v_mov_b64_e32 v[60:61], v[52:53]
	v_mov_b64_e32 v[42:43], v[54:55]
	v_mov_b64_e32 v[30:31], v[54:55]
	v_readlane_b32 s37, v248, 1
	v_readlane_b32 s38, v248, 2
	v_readlane_b32 s39, v248, 3
	s_branch .LBB0_262

; __device__ __forceinline__ void gla_mma(const Params& p, unsigned char* lds, int l, int item, int tid) {
;     ...
;         const int tok0 = b * SEQ + CHUNK(s < 0 ? 0 : s) * 64;
;     ...
;         if (s == 32) __syncthreads();
;         f32x4 accO[2][4]; u32x4 gw[4];
;         if (s >= 0) {
;             u32x4 ox[4];
;             bf16x8 vfrag[2][2];
; #pragma unroll
;             for (int vb = 0; vb < 2; ++vb)
; #pragma unroll
;                 for (int pp = 0; pp < 2; ++pp)
; #pragma unroll
;                     for (int i = 0; i < 8; ++i) { const int pos = 32 * pp + 4 * q4 + (i & 3) + ((i >> 2) << 4); vfrag[vb][pp][i] = (short)vraw[pos * VP + 32 * vq + 8 * (lr >> 2) + 4 * vb + (lr & 3)]; }
;             bf16x8 qf[4][2], kf[4][2];
; #pragma unroll
;             for (int cb = 0; cb < 4; ++cb) { qf[cb][0] = gla_tr_frag(qin, 8 * q4, 8 * q4 + 4, 16 * cb, lr); qf[cb][1] = gla_tr_frag(qin, 32 + 8 * q4, 36 + 8 * q4, 16 * cb, lr);
;                 kf[cb][0] = gla_tr_frag(kin, 8 * q4, 8 * q4 + 4, 16 * cb, lr); kf[cb][1] = gla_tr_frag(kin, 32 + 8 * q4, 36 + 8 * q4, 16 * cb, lr); }
;             bf16x8 P0[4], P1[2];
;             {
;                 f32x4 sc[4][4];
; #pragma unroll
;                 for (int cb = 0; cb < 4; ++cb)
; #pragma unroll
;                     for (int jb = 0; jb < 4; ++jb) {
;                         if (jb > cb) { sc[jb][cb] = (f32x4){0.f, 0.f, 0.f, 0.f}; continue; }
;                         f32x4 a = (f32x4){0.f, 0.f, 0.f, 0.f};
;                         a = __builtin_amdgcn_mfma_f32_16x16x32_bf16(kf[jb][0], qf[cb][0], a, 0, 0, 0);
;                         sc[jb][cb] = a;
;                     }
; #pragma unroll
;                 for (int cb = 0; cb < 4; ++cb)
; #pragma unroll
;                     for (int jb = 0; jb <= cb; ++jb) sc[jb][cb] = __builtin_amdgcn_mfma_f32_16x16x32_bf16(kf[jb][1], qf[cb][1], sc[jb][cb], 0, 0, 0);
;             __builtin_amdgcn_sched_barrier(0);
;             if (s >= 32) {
; #pragma unroll
;                 for (int cb = 0; cb < 4; ++cb) { const size_t tk = (size_t)TOK(16 * cb + lr); ox[cb] = *(const u32x4*)(OX + tk * 512 + ocol); gw[cb] = *(const u32x4*)(Z + tk * ZW + ZG + ocol); }
.LBB0_264:
	s_add_i32 s7, s5, 31
	s_max_i32 s6, s7, 0
	v_readlane_b32 s8, v247, 42
	s_sub_i32 s10, 63, s6
	v_readlane_b32 s9, v247, 43
	s_and_b64 s[8:9], s[8:9], exec
	s_cselect_b32 s6, s6, s10
	s_lshl_b32 s6, s6, 6
	v_readlane_b32 s8, v247, 57
	s_add_i32 s6, s6, s8
	s_cmp_lt_i32 s7, 0
	v_or_b32_e32 v140, s6, v150
	s_cbranch_scc1 .LBB0_279
	s_waitcnt vmcnt(0)
	ds_read_b64_tr_b16 v[72:73], v145 offset:9216
	ds_read_b64_tr_b16 v[74:75], v145 offset:9792
	ds_read_b64_tr_b16 v[76:77], v145
	ds_read_b64_tr_b16 v[80:81], v145 offset:32
	ds_read_b64_tr_b16 v[84:85], v145 offset:64
	ds_read_b64_tr_b16 v[88:89], v145 offset:96
	ds_read_b64_tr_b16 v[78:79], v145 offset:576
	ds_read_b64_tr_b16 v[82:83], v145 offset:608
	ds_read_b64_tr_b16 v[86:87], v145 offset:640
	ds_read_b64_tr_b16 v[90:91], v145 offset:672
	ds_read_b64_tr_b16 v[92:93], v145 offset:9248
	ds_read_b64_tr_b16 v[96:97], v145 offset:9280
	ds_read_b64_tr_b16 v[100:101], v145 offset:9312
	ds_read_b64_tr_b16 v[94:95], v145 offset:9824
	ds_read_b64_tr_b16 v[98:99], v145 offset:9856
	ds_read_b64_tr_b16 v[102:103], v145 offset:9888
	s_waitcnt lgkmcnt(9)
	v_mfma_f32_16x16x32_bf16 v[76:79], v[72:75], v[76:79], 0
	ds_read_b64_tr_b16 v[126:127], v145 offset:13824
	ds_read_b64_tr_b16 v[128:129], v145 offset:14400
	s_waitcnt lgkmcnt(10)
	v_mfma_f32_16x16x32_bf16 v[104:107], v[72:75], v[80:83], 0
	s_waitcnt lgkmcnt(9)
	v_mfma_f32_16x16x32_bf16 v[112:115], v[72:75], v[84:87], 0
	s_waitcnt lgkmcnt(8)
	v_mfma_f32_16x16x32_bf16 v[130:133], v[72:75], v[88:91], 0
	ds_read_b64_tr_b16 v[72:73], v145 offset:4608
	ds_read_b64_tr_b16 v[120:121], v145 offset:4640
	ds_read_b64_tr_b16 v[174:175], v145 offset:4672
	ds_read_b64_tr_b16 v[182:183], v145 offset:4704
	ds_read_b64_tr_b16 v[74:75], v145 offset:5184
	ds_read_b64_tr_b16 v[122:123], v145 offset:5216
	ds_read_b64_tr_b16 v[176:177], v145 offset:5248
	ds_read_b64_tr_b16 v[184:185], v145 offset:5280
	ds_read_b64_tr_b16 v[190:191], v145 offset:13856
	ds_read_b64_tr_b16 v[194:195], v145 offset:13888
	ds_read_b64_tr_b16 v[198:199], v145 offset:13920
	s_waitcnt lgkmcnt(14)
	v_mfma_f32_16x16x32_bf16 v[80:83], v[92:95], v[80:83], 0
	ds_read_b64_tr_b16 v[192:193], v145 offset:14432
	ds_read_b64_tr_b16 v[196:197], v145 offset:14464
	ds_read_b64_tr_b16 v[200:201], v145 offset:14496
	v_mfma_f32_16x16x32_bf16 v[116:119], v[92:95], v[84:87], 0
	v_mfma_f32_16x16x32_bf16 v[84:87], v[96:99], v[84:87], 0
	v_mfma_f32_16x16x32_bf16 v[178:181], v[92:95], v[88:91], 0
	v_mfma_f32_16x16x32_bf16 v[186:189], v[96:99], v[88:91], 0
	s_waitcnt lgkmcnt(14)
	v_mfma_f32_16x16x32_bf16 v[100:103], v[100:103], v[88:91], 0
	s_waitcnt lgkmcnt(9)
	v_mfma_f32_16x16x32_bf16 v[108:111], v[126:129], v[72:75], v[76:79]
	s_waitcnt lgkmcnt(8)
	v_mfma_f32_16x16x32_bf16 v[96:99], v[126:129], v[120:123], v[104:107]
	s_waitcnt lgkmcnt(2)
	v_mfma_f32_16x16x32_bf16 v[104:107], v[190:193], v[120:123], v[80:83]
	v_mfma_f32_16x16x32_bf16 v[92:95], v[126:129], v[174:177], v[112:115]
	v_mfma_f32_16x16x32_bf16 v[80:83], v[190:193], v[174:177], v[116:119]
	s_nop 2
	ds_read_u16 v119, v167 offset:56576
	ds_read_u16 v116, v167 offset:56584
	ds_read_u16 v120, v168 offset:56576
	ds_read_u16 v117, v168 offset:56584
	ds_read_u16 v121, v169 offset:56576
	ds_read_u16 v118, v169 offset:56584
	ds_read_u16 v122, v170 offset:56576
	ds_read_u16 v124, v170 offset:56584
	s_waitcnt lgkmcnt(9)
	v_mfma_f32_16x16x32_bf16 v[72:75], v[194:197], v[174:177], v[84:87]
	v_mfma_f32_16x16x32_bf16 v[76:79], v[126:129], v[182:185], v[130:133]
	ds_read_u16 v114, v163 offset:56576
	ds_read_u16 v112, v163 offset:56584
	s_nop 0
	ds_read_u16 v131, v163 offset:56840
	ds_read_u16 v133, v163 offset:57104
	ds_read_u16 v135, v163 offset:57368
	ds_read_u16 v113, v163 offset:57376
	ds_read_u16 v115, v163 offset:57112
	ds_read_u16 v129, v163 offset:56848
	v_mfma_f32_16x16x32_bf16 v[88:91], v[190:193], v[182:185], v[178:181]
	ds_read_u16 v176, v163 offset:60800
	s_nop 1
	ds_read_u16 v178, v163 offset:61064
	ds_read_u16 v179, v163 offset:61328
	ds_read_u16 v180, v163 offset:61592
	ds_read_u16 v173, v163 offset:61600
	ds_read_u16 v175, v163 offset:61336
	ds_read_u16 v174, v163 offset:61072
	ds_read_u16 v177, v163 offset:60808
	ds_read_u16 v123, v164 offset:56576
	ds_read_u16 v125, v164 offset:56584
	ds_read_u16 v130, v163 offset:65288
	ds_read_u16 v132, v165 offset:56576
	ds_read_u16 v126, v165 offset:56584
	ds_read_u16 v134, v166 offset:56576
	ds_read_u16 v128, v166 offset:56584
	ds_read_u16 v127, v163 offset:65296
	v_mfma_f32_16x16x32_bf16 v[84:87], v[194:197], v[182:185], v[186:189]
	s_waitcnt lgkmcnt(14)
	v_mfma_f32_16x16x32_bf16 v[100:103], v[198:201], v[182:185], v[100:103]
	s_cmp_lt_u32 s7, 32
	v_ashrrev_i32_e32 v141, 31, v140
	s_cbranch_scc1 .LBB0_267
	v_or_b32_e32 v8, s6, v149
	v_ashrrev_i32_e32 v9, 31, v8
	v_mov_b64_e32 v[48:49], s[86:87]
	v_lshlrev_b64 v[10:11], 10, v[8:9]
	v_mad_i64_i32 v[8:9], s[8:9], v8, s1, v[48:49]
	v_lshl_add_u64 v[8:9], v[8:9], 0, v[152:153]
	v_add_co_u32_e32 v12, vcc, 0xec00000, v8
	v_mad_i64_i32 v[18:19], s[8:9], v140, s1, v[48:49]
	v_or_b32_e32 v32, s6, v151
	v_addc_co_u32_e32 v13, vcc, 0, v9, vcc
	v_lshl_add_u64 v[18:19], v[18:19], 0, v[152:153]
	v_ashrrev_i32_e32 v33, 31, v32
	v_add_co_u32_e32 v20, vcc, 0xec00000, v18
	v_lshlrev_b64 v[34:35], 10, v[32:33]
	v_mad_i64_i32 v[32:33], s[8:9], v32, s1, v[48:49]
	v_addc_co_u32_e32 v21, vcc, 0, v19, vcc
	v_lshl_add_u64 v[32:33], v[32:33], 0, v[152:153]
	v_or_b32_e32 v50, s6, v162
	v_add_co_u32_e32 v36, vcc, 0xec00000, v32
	v_mad_i64_i32 v[48:49], s[8:9], v50, s1, v[48:49]
	s_nop 0
	v_addc_co_u32_e32 v37, vcc, 0, v33, vcc
	v_ashrrev_i32_e32 v51, 31, v50
	v_lshl_add_u64 v[48:49], v[48:49], 0, v[152:153]
	v_lshlrev_b64 v[16:17], 10, v[140:141]
	v_lshlrev_b64 v[56:57], 10, v[50:51]
	v_add_co_u32_e32 v58, vcc, 0xec00000, v48
	v_lshl_add_u64 v[10:11], v[136:137], 0, v[10:11]
	v_lshl_add_u64 v[16:17], v[136:137], 0, v[16:17]
	v_lshl_add_u64 v[34:35], v[136:137], 0, v[34:35]
	v_lshl_add_u64 v[56:57], v[136:137], 0, v[56:57]
	v_addc_co_u32_e32 v59, vcc, 0, v49, vcc
	global_load_dwordx4 v[8:11], v[10:11], off nt
	s_nop 0
	global_load_dwordx4 v[12:15], v[12:13], off offset:2048 nt
	s_nop 0
	global_load_dwordx4 v[16:19], v[16:17], off nt
	s_nop 0
	global_load_dwordx4 v[20:23], v[20:21], off offset:2048 nt
	s_nop 0
	global_load_dwordx4 v[32:35], v[34:35], off nt
	s_nop 0
	global_load_dwordx4 v[36:39], v[36:37], off offset:2048 nt
	s_nop 0
	global_load_dwordx4 v[48:51], v[56:57], off nt
	s_nop 0
	global_load_dwordx4 v[56:59], v[58:59], off offset:2048 nt

; __device__ __forceinline__ unsigned cvt_pk_bf16(float lo, float hi) { unsigned r; asm volatile("v_cvt_pk_bf16_f32 %0, %1, %2" : "=v"(r) : "v"(lo), "v"(hi)); return r; }
; __device__ __forceinline__ float bflo(unsigned w) { return __uint_as_float(w << 16); }
; __device__ __forceinline__ float bfhi(unsigned w) { return __uint_as_float(w & 0xffff0000u); }
; #define GLA_BAR() do { asm volatile("s_waitcnt lgkmcnt(0)" ::: "memory"); __builtin_amdgcn_s_barrier(); asm volatile("" ::: "memory"); } while (0)
; __device__ __forceinline__ void gla_mma(const Params& p, unsigned char* lds, int l, int item, int tid) {
;     ...
;             if (s < 32) {
; #pragma unroll
;                 for (int cb = 0; cb < 4; ++cb) { const f32x4 o0 = accO[0][cb], o1 = accO[1][cb]; *(u32x4*)(OX + (size_t)TOK(16 * cb + lr) * 512 + ocol) = (u32x4){cvt_pk_bf16(o0[0], o0[1]), cvt_pk_bf16(o0[2], o0[3]), cvt_pk_bf16(o1[0], o1[1]), cvt_pk_bf16(o1[2], o1[3])}; }
;             } else {
; #pragma unroll
;                 for (int cb = 0; cb < 4; ++cb) { float ss = 0.f;
; #pragma unroll
;                     for (int vb = 0; vb < 2; ++vb) { const unsigned xa = vb ? ox[cb].z : ox[cb].x, xb2 = vb ? ox[cb].w : ox[cb].y; accO[vb][cb] += (f32x4){bflo(xa), bfhi(xa), bflo(xb2), bfhi(xb2)}; const f32x4 o = accO[vb][cb]; ss += (o[0] * o[0] + o[1] * o[1]) + (o[2] * o[2] + o[3] * o[3]); }
;                     ss += __shfl_xor(ss, 16); ss += __shfl_xor(ss, 32);
;                     if (q4 == 0) red[vq * 64 + 16 * cb + lr] = ss; }
;             }
;         }
;         GLA_BAR();
;         if (s >= 32) {
; #pragma unroll
;             for (int cb = 0; cb < 4; ++cb) { const float ss = (red[16 * cb + lr] + red[64 + 16 * cb + lr]) + (red[128 + 16 * cb + lr] + red[192 + 16 * cb + lr]);
;                 const float rs = rsqrtf(ss * (1.0f / 128.0f) + EPS); const size_t tk = (size_t)TOK(16 * cb + lr);
;                 const f32x4 o0 = accO[0][cb] * rs * ng[0], o1 = accO[1][cb] * rs * ng[1]; const u32x4 g4 = gw[cb];
;                 u32x4 w; w.x = cvt_pk_bf16(o0[0] * bflo(g4.x), o0[1] * bfhi(g4.x)); w.y = cvt_pk_bf16(o0[2] * bflo(g4.y), o0[3] * bfhi(g4.y)); w.z = cvt_pk_bf16(o1[0] * bflo(g4.z), o1[1] * bfhi(g4.z)); w.w = cvt_pk_bf16(o1[2] * bflo(g4.w), o1[3] * bfhi(g4.w));
.LBB0_277:
	s_and_b64 vcc, exec, s[26:27]
	s_cbranch_vccz .LBB0_279
	v_or_b32_e32 v76, s6, v149
	v_ashrrev_i32_e32 v77, 31, v76
	v_lshlrev_b64 v[76:77], 10, v[76:77]
	v_lshl_add_u64 v[76:77], v[136:137], 0, v[76:77]
	v_cvt_pk_bf16_f32 v72, v96, v97
	v_cvt_pk_bf16_f32 v73, v98, v99
	v_cvt_pk_bf16_f32 v74, v108, v109
	v_cvt_pk_bf16_f32 v75, v110, v111
	global_store_dwordx4 v[76:77], v[72:75], off nt
	v_lshlrev_b64 v[76:77], 10, v[140:141]
	v_lshl_add_u64 v[76:77], v[136:137], 0, v[76:77]
	v_cvt_pk_bf16_f32 v72, v104, v105
	v_cvt_pk_bf16_f32 v73, v106, v107
	v_cvt_pk_bf16_f32 v74, v112, v113
	v_cvt_pk_bf16_f32 v75, v114, v115
	global_store_dwordx4 v[76:77], v[72:75], off nt
	v_or_b32_e32 v76, s6, v151
	v_ashrrev_i32_e32 v77, 31, v76
	v_lshlrev_b64 v[76:77], 10, v[76:77]
	v_lshl_add_u64 v[76:77], v[136:137], 0, v[76:77]
	v_cvt_pk_bf16_f32 v72, v120, v121
	v_cvt_pk_bf16_f32 v73, v122, v123
	v_cvt_pk_bf16_f32 v74, v128, v129
	v_cvt_pk_bf16_f32 v75, v130, v131
	global_store_dwordx4 v[76:77], v[72:75], off nt
	v_or_b32_e32 v76, s6, v162
	v_ashrrev_i32_e32 v77, 31, v76
	v_lshlrev_b64 v[76:77], 10, v[76:77]
	v_cvt_pk_bf16_f32 v72, v124, v125
	v_cvt_pk_bf16_f32 v73, v126, v127
	v_cvt_pk_bf16_f32 v74, v132, v133
	v_cvt_pk_bf16_f32 v75, v134, v135
	v_lshl_add_u64 v[76:77], v[136:137], 0, v[76:77]
	global_store_dwordx4 v[76:77], v[72:75], off nt
	v_mov_b64_e32 v[116:117], v[132:133]
	v_mov_b64_e32 v[92:93], v[128:129]
	v_mov_b64_e32 v[84:85], v[112:113]
	v_mov_b64_e32 v[76:77], v[108:109]
	v_mov_b64_e32 v[100:101], v[124:125]
	v_mov_b64_e32 v[88:89], v[120:121]
	v_mov_b64_e32 v[80:81], v[104:105]
	v_mov_b64_e32 v[72:73], v[96:97]
	v_mov_b64_e32 v[118:119], v[134:135]
	v_mov_b64_e32 v[94:95], v[130:131]
	v_mov_b64_e32 v[86:87], v[114:115]
	v_mov_b64_e32 v[78:79], v[110:111]
	v_mov_b64_e32 v[102:103], v[126:127]
	v_mov_b64_e32 v[90:91], v[122:123]
	v_mov_b64_e32 v[82:83], v[106:107]
	v_mov_b64_e32 v[74:75], v[98:99]
.LBB0_279:
	s_waitcnt lgkmcnt(0)
	s_barrier
	s_cmp_lt_i32 s7, 32
	s_cbranch_scc1 .LBB0_260
	ds_read2st64_b32 v[96:97], v142 offset0:145 offset1:146
	ds_read2st64_b32 v[98:99], v142 offset0:147 offset1:148
	v_ashrrev_i32_e32 v141, 31, v140
	s_waitcnt lgkmcnt(0)
	v_mov_b32_e32 v104, v96
	v_mov_b32_e32 v105, v98
	v_mov_b32_e32 v98, v97
	v_pk_add_f32 v[96:97], v[104:105], v[98:99]
	s_nop 0
	v_add_f32_e32 v96, v96, v97
	v_fmamk_f32 v96, v96, 0x3c000000, v208
	v_mul_f32_e32 v97, 0x4b800000, v96
	v_cmp_gt_f32_e32 vcc, s75, v96
	s_nop 1
	v_cndmask_b32_e32 v96, v96, v97, vcc
	v_rsq_f32_e32 v96, v96
	s_nop 0
	v_mul_f32_e32 v97, 0x45800000, v96
	v_cndmask_b32_e32 v96, v96, v97, vcc
	v_pk_mul_f32 v[98:99], v[72:73], v[96:97] op_sel_hi:[1,0]
	v_pk_mul_f32 v[104:105], v[74:75], v[96:97] op_sel_hi:[1,0]
	v_pk_mul_f32 v[106:107], v[76:77], v[96:97] op_sel_hi:[1,0]
	v_pk_mul_f32 v[96:97], v[78:79], v[96:97] op_sel_hi:[1,0]
	s_waitcnt vmcnt(0)
	v_pk_mul_f32 v[98:99], v[4:5], v[98:99]
	v_pk_mul_f32 v[108:109], v[2:3], v[96:97]
	v_lshlrev_b32_e32 v96, 16, v12
	v_and_b32_e32 v97, 0xffff0000, v12
	v_mul_f32_e32 v96, v98, v96
	v_mul_f32_e32 v97, v99, v97
	v_pk_mul_f32 v[104:105], v[6:7], v[104:105]
	v_cvt_pk_bf16_f32 v96, v96, v97
	v_lshlrev_b32_e32 v97, 16, v13
	v_and_b32_e32 v98, 0xffff0000, v13
	v_mul_f32_e32 v97, v104, v97
	v_mul_f32_e32 v98, v105, v98
	v_pk_mul_f32 v[106:107], v[0:1], v[106:107]
	v_cvt_pk_bf16_f32 v97, v97, v98
	v_lshlrev_b32_e32 v98, 16, v14
	v_and_b32_e32 v99, 0xffff0000, v14
	v_mul_f32_e32 v98, v106, v98
	v_mul_f32_e32 v99, v107, v99
	v_cvt_pk_bf16_f32 v98, v98, v99
	v_lshlrev_b32_e32 v99, 16, v15
	v_and_b32_e32 v104, 0xffff0000, v15
	v_mul_f32_e32 v99, v108, v99
	v_mul_f32_e32 v104, v109, v104
	v_add_u32_e32 v106, 64, v142
	v_cvt_pk_bf16_f32 v99, v99, v104
	ds_read2st64_b32 v[104:105], v106 offset0:145 offset1:146
	ds_read2st64_b32 v[106:107], v106 offset0:147 offset1:148
	v_or_b32_e32 v108, s6, v149
	v_ashrrev_i32_e32 v109, 31, v108
	s_waitcnt lgkmcnt(1)
	v_mov_b32_e32 v110, v104
	s_waitcnt lgkmcnt(0)
; __device__ __forceinline__ unsigned cvt_pk_bf16(float lo, float hi) { unsigned r; asm volatile("v_cvt_pk_bf16_f32 %0, %1, %2" : "=v"(r) : "v"(lo), "v"(hi)); return r; }
; __device__ __forceinline__ float bflo(unsigned w) { return __uint_as_float(w << 16); }
; __device__ __forceinline__ float bfhi(unsigned w) { return __uint_as_float(w & 0xffff0000u); }
; __device__ __forceinline__ void gla_mma(const Params& p, unsigned char* lds, int l, int item, int tid) {
;     ...
;         if (s >= 32) {
; #pragma unroll
;             for (int cb = 0; cb < 4; ++cb) { const float ss = (red[16 * cb + lr] + red[64 + 16 * cb + lr]) + (red[128 + 16 * cb + lr] + red[192 + 16 * cb + lr]);
;                 const float rs = rsqrtf(ss * (1.0f / 128.0f) + EPS); const size_t tk = (size_t)TOK(16 * cb + lr);
;                 const f32x4 o0 = accO[0][cb] * rs * ng[0], o1 = accO[1][cb] * rs * ng[1]; const u32x4 g4 = gw[cb];
;                 u32x4 w; w.x = cvt_pk_bf16(o0[0] * bflo(g4.x), o0[1] * bfhi(g4.x)); w.y = cvt_pk_bf16(o0[2] * bflo(g4.y), o0[3] * bfhi(g4.y)); w.z = cvt_pk_bf16(o1[0] * bflo(g4.z), o1[1] * bfhi(g4.z)); w.w = cvt_pk_bf16(o1[2] * bflo(g4.w), o1[3] * bfhi(g4.w));
;                 *(u32x4*)(MIX + tk * D + ocol) = w; }
	v_mov_b32_e32 v111, v106
	v_mov_b32_e32 v106, v105
	v_pk_add_f32 v[104:105], v[110:111], v[106:107]
	s_nop 0
	v_add_f32_e32 v104, v104, v105
	v_fmamk_f32 v104, v104, 0x3c000000, v208
	v_mul_f32_e32 v105, 0x4b800000, v104
	v_cmp_gt_f32_e32 vcc, s75, v104
	s_nop 1
	v_cndmask_b32_e32 v104, v104, v105, vcc
	v_rsq_f32_e32 v106, v104
	v_lshlrev_b64 v[104:105], 11, v[108:109]
	v_lshl_add_u64 v[104:105], v[138:139], 0, v[104:105]
	global_store_dwordx4 v[104:105], v[96:99], off nt
	s_nop 1
	v_mul_f32_e32 v96, 0x45800000, v106
	v_cndmask_b32_e32 v96, v106, v96, vcc
	v_pk_mul_f32 v[98:99], v[80:81], v[96:97] op_sel_hi:[1,0]
	v_pk_mul_f32 v[104:105], v[82:83], v[96:97] op_sel_hi:[1,0]
	v_pk_mul_f32 v[106:107], v[84:85], v[96:97] op_sel_hi:[1,0]
	v_pk_mul_f32 v[96:97], v[86:87], v[96:97] op_sel_hi:[1,0]
	v_pk_mul_f32 v[98:99], v[4:5], v[98:99]
	v_pk_mul_f32 v[108:109], v[2:3], v[96:97]
	v_lshlrev_b32_e32 v96, 16, v20
	v_and_b32_e32 v97, 0xffff0000, v20
	v_mul_f32_e32 v96, v98, v96
	v_mul_f32_e32 v97, v99, v97
	v_pk_mul_f32 v[104:105], v[6:7], v[104:105]
	v_cvt_pk_bf16_f32 v96, v96, v97
	v_lshlrev_b32_e32 v97, 16, v21
	v_and_b32_e32 v98, 0xffff0000, v21
	v_mul_f32_e32 v97, v104, v97
	v_mul_f32_e32 v98, v105, v98
	v_pk_mul_f32 v[106:107], v[0:1], v[106:107]
	v_cvt_pk_bf16_f32 v97, v97, v98
	v_lshlrev_b32_e32 v98, 16, v22
	v_and_b32_e32 v99, 0xffff0000, v22
	v_mul_f32_e32 v98, v106, v98
	v_mul_f32_e32 v99, v107, v99
	v_cvt_pk_bf16_f32 v98, v98, v99
	v_lshlrev_b32_e32 v99, 16, v23
	v_and_b32_e32 v104, 0xffff0000, v23
	v_mul_f32_e32 v99, v108, v99
	v_mul_f32_e32 v104, v109, v104
	v_add_u32_e32 v106, 0x80, v142
	v_cvt_pk_bf16_f32 v99, v99, v104
	ds_read2st64_b32 v[104:105], v106 offset0:145 offset1:146
	ds_read2st64_b32 v[106:107], v106 offset0:147 offset1:148
	s_waitcnt lgkmcnt(1)
	v_mov_b32_e32 v108, v104
	s_waitcnt lgkmcnt(0)
	v_mov_b32_e32 v109, v106
	v_mov_b32_e32 v106, v105
	v_pk_add_f32 v[104:105], v[108:109], v[106:107]
	s_nop 0
	v_add_f32_e32 v104, v104, v105
	v_fmamk_f32 v104, v104, 0x3c000000, v208
	v_mul_f32_e32 v105, 0x4b800000, v104
	v_cmp_gt_f32_e32 vcc, s75, v104
	s_nop 1
	v_cndmask_b32_e32 v104, v104, v105, vcc
	v_rsq_f32_e32 v106, v104
	v_lshlrev_b64 v[104:105], 11, v[140:141]
	v_lshl_add_u64 v[104:105], v[138:139], 0, v[104:105]
	global_store_dwordx4 v[104:105], v[96:99], off nt
	s_nop 1
	v_mul_f32_e32 v96, 0x45800000, v106
	v_cndmask_b32_e32 v96, v106, v96, vcc
	v_pk_mul_f32 v[98:99], v[88:89], v[96:97] op_sel_hi:[1,0]
	v_pk_mul_f32 v[104:105], v[90:91], v[96:97] op_sel_hi:[1,0]
	v_pk_mul_f32 v[106:107], v[92:93], v[96:97] op_sel_hi:[1,0]
	v_pk_mul_f32 v[96:97], v[94:95], v[96:97] op_sel_hi:[1,0]
	v_pk_mul_f32 v[98:99], v[4:5], v[98:99]
	v_pk_mul_f32 v[108:109], v[2:3], v[96:97]
	v_lshlrev_b32_e32 v96, 16, v36
	v_and_b32_e32 v97, 0xffff0000, v36
	v_mul_f32_e32 v96, v98, v96
	v_mul_f32_e32 v97, v99, v97
	v_pk_mul_f32 v[104:105], v[6:7], v[104:105]
	v_cvt_pk_bf16_f32 v96, v96, v97
	v_lshlrev_b32_e32 v97, 16, v37
	v_and_b32_e32 v98, 0xffff0000, v37
	v_mul_f32_e32 v97, v104, v97
	v_mul_f32_e32 v98, v105, v98
	v_pk_mul_f32 v[106:107], v[0:1], v[106:107]
	v_cvt_pk_bf16_f32 v97, v97, v98
	v_lshlrev_b32_e32 v98, 16, v38
	v_and_b32_e32 v99, 0xffff0000, v38
	v_mul_f32_e32 v98, v106, v98
	v_mul_f32_e32 v99, v107, v99
	v_cvt_pk_bf16_f32 v98, v98, v99
	v_lshlrev_b32_e32 v99, 16, v39
	v_and_b32_e32 v104, 0xffff0000, v39
	v_mul_f32_e32 v99, v108, v99
	v_mul_f32_e32 v104, v109, v104
	v_add_u32_e32 v106, 0xc0, v142
	v_cvt_pk_bf16_f32 v99, v99, v104
	ds_read2st64_b32 v[104:105], v106 offset0:145 offset1:146
	ds_read2st64_b32 v[106:107], v106 offset0:147 offset1:148
	v_or_b32_e32 v108, s6, v151
	v_ashrrev_i32_e32 v109, 31, v108
	s_waitcnt lgkmcnt(1)
	v_mov_b32_e32 v110, v104
	s_waitcnt lgkmcnt(0)
	v_mov_b32_e32 v111, v106
	v_mov_b32_e32 v106, v105
	v_pk_add_f32 v[104:105], v[110:111], v[106:107]
	s_nop 0
	v_add_f32_e32 v104, v104, v105
	v_fmamk_f32 v104, v104, 0x3c000000, v208
	v_mul_f32_e32 v105, 0x4b800000, v104
	v_cmp_gt_f32_e32 vcc, s75, v104
	s_nop 1
	v_cndmask_b32_e32 v104, v104, v105, vcc
	v_rsq_f32_e32 v106, v104
	v_lshlrev_b64 v[104:105], 11, v[108:109]
	v_lshl_add_u64 v[104:105], v[138:139], 0, v[104:105]
	global_store_dwordx4 v[104:105], v[96:99], off nt
	v_or_b32_e32 v104, s6, v162
	v_ashrrev_i32_e32 v105, 31, v104
	v_mul_f32_e32 v96, 0x45800000, v106
	v_cndmask_b32_e32 v96, v106, v96, vcc
	v_pk_mul_f32 v[98:99], v[100:101], v[96:97] op_sel_hi:[1,0]
	v_pk_mul_f32 v[106:107], v[102:103], v[96:97] op_sel_hi:[1,0]
	v_pk_mul_f32 v[108:109], v[116:117], v[96:97] op_sel_hi:[1,0]
	v_pk_mul_f32 v[96:97], v[118:119], v[96:97] op_sel_hi:[1,0]
	v_pk_mul_f32 v[98:99], v[4:5], v[98:99]
	v_pk_mul_f32 v[110:111], v[2:3], v[96:97]
	v_lshlrev_b32_e32 v96, 16, v56
	v_and_b32_e32 v97, 0xffff0000, v56
	v_mul_f32_e32 v96, v98, v96
	v_mul_f32_e32 v97, v99, v97
	v_pk_mul_f32 v[106:107], v[6:7], v[106:107]
	v_cvt_pk_bf16_f32 v96, v96, v97
	v_lshlrev_b32_e32 v97, 16, v57
	v_and_b32_e32 v98, 0xffff0000, v57
	v_mul_f32_e32 v97, v106, v97
	v_mul_f32_e32 v98, v107, v98
	v_pk_mul_f32 v[108:109], v[0:1], v[108:109]
	v_cvt_pk_bf16_f32 v97, v97, v98
	v_lshlrev_b32_e32 v98, 16, v58
	v_and_b32_e32 v99, 0xffff0000, v58
	v_mul_f32_e32 v98, v108, v98
	v_mul_f32_e32 v99, v109, v99
	v_cvt_pk_bf16_f32 v98, v98, v99
	v_lshlrev_b32_e32 v99, 16, v59
	v_lshlrev_b64 v[104:105], 11, v[104:105]
	v_mul_f32_e32 v99, v110, v99
	v_and_b32_e32 v106, 0xffff0000, v59
	v_lshl_add_u64 v[104:105], v[138:139], 0, v[104:105]
	v_mul_f32_e32 v106, v111, v106
	v_cvt_pk_bf16_f32 v99, v99, v106
	global_store_dwordx4 v[104:105], v[96:99], off nt
	s_branch .LBB0_260

; __device__ __forceinline__ void gla_load_qka(const GlaPrepCtx& c, int si, GlaRegs& R) {
;     const int dir = c.dir; const size_t t0 = (size_t)(c.b * SEQ + CHUNK(si) * 64); const bf16_t* zr = c.Z + (t0 + c.lrow) * ZW + c.h * 64 + c.lcs;
;     R.q0 = *(const u32x4*)(zr + ZQ); R.k0 = *(const u32x4*)(zr + ZK); R.q1 = *(const u32x4*)(zr + (size_t)32 * ZW + ZQ); R.k1 = *(const u32x4*)(zr + (size_t)32 * ZW + ZK);
;     if (c.tid < 128) R.a = *(const u32x4*)(c.DEC + (t0 + c.arow) * 32 + dir * 16 + c.acs);
; }
; __device__ __forceinline__ void gla_load_v(const GlaPrepCtx& c, int si, GlaRegs& R) {
;     const int dir = c.dir; const size_t t0 = (size_t)(c.b * SEQ + CHUNK(si) * 64); const bf16_t* vr = c.Z + (t0 + c.vrow) * ZW + ZV + c.h * 128 + c.vcs;
;     R.v0 = *(const u32x4*)vr; R.v1 = *(const u32x4*)(vr + (size_t)16 * ZW); R.v2 = *(const u32x4*)(vr + (size_t)32 * ZW); R.v3 = *(const u32x4*)(vr + (size_t)48 * ZW);
; }
; __device__ __forceinline__ void gla_store_qka(const GlaPrepCtx& c, const GlaRegs& R) {
;     const int dir = c.dir; const int r0_ = POS(c.lrow), r1_ = POS(c.lrow + 32);
;     *(u32x4*)(c.qraw + r0_ * 64 + ROT(r0_, c.lcs)) = R.q0; *(u32x4*)(c.kraw + r0_ * 64 + ROT(r0_, c.lcs)) = R.k0; *(u32x4*)(c.qraw + r1_ * 64 + ROT(r1_, c.lcs)) = R.q1; *(u32x4*)(c.kraw + r1_ * 64 + ROT(r1_, c.lcs)) = R.k1;
;     if (c.tid < 128) *(u32x4*)(c.araw + POS(c.arow) * 16 + c.acs) = R.a;
; __device__ __forceinline__ void gla_prep(const Params& p, unsigned char* lds, int l, int item, int tid) {
;     ...
;     gla_load_qka(c, 0, RA); gla_store_qka(c, RA);
;     gla_load_qka(c, 1, RB); gla_load_v(c, 0, RB);
.LBB0_285:
	s_or_b64 exec, exec, s[26:27]
	s_lshl_b32 s6, s14, 8
	v_readlane_b32 s7, v247, 41
	s_or_b32 s6, s6, s7
	v_add_u32_e32 v6, s6, v64
	v_readlane_b32 s6, v247, 44
	v_ashrrev_i32_e32 v96, 3, v106
	v_ashrrev_i32_e32 v7, 31, v6
	v_readlane_b32 s7, v247, 45
	v_readlane_b32 s10, v247, 48
	v_readlane_b32 s12, v247, 50
	v_lshl_add_u64 v[6:7], v[6:7], 2, s[6:7]
	v_ashrrev_i32_e32 v97, 31, v96
	v_readlane_b32 s11, v247, 49
	v_readlane_b32 s13, v247, 51
	v_lshlrev_b32_e32 v5, 3, v106
	global_load_dword v4, v[6:7], off
	v_lshl_add_u64 v[6:7], v[96:97], 0, s[10:11]
	v_mov_b64_e32 v[8:9], s[12:13]
	v_and_b32_e32 v10, 56, v5
	v_mad_u64_u32 v[8:9], s[6:7], v6, s1, v[8:9]
	v_mad_i32_i24 v9, v7, s1, v9
	v_lshlrev_b32_e32 v152, 1, v10
	v_lshl_add_u64 v[6:7], v[8:9], 0, v[152:153]
	global_load_dwordx4 v[8:11], v[6:7], off nt
	global_load_dwordx4 v[12:15], v[6:7], off offset:512 nt
	v_add_co_u32_e32 v6, vcc, 0x2c000, v6
	s_movk_i32 s6, 0x7f
	s_nop 0
	v_addc_co_u32_e32 v7, vcc, 0, v7, vcc
	global_load_dwordx4 v[20:23], v[6:7], off nt
	global_load_dwordx4 v[24:27], v[6:7], off offset:512 nt
	v_ashrrev_i32_e32 v98, 1, v106
	v_and_b32_e32 v6, 8, v5
	v_cmp_lt_i32_e64 s[44:45], s6, v106
	s_movk_i32 s6, 0x80
	v_cmp_gt_i32_e64 s[42:43], s6, v106
	v_ashrrev_i32_e32 v99, 31, v98
	v_lshlrev_b32_e32 v28, 1, v6
	s_and_saveexec_b64 s[26:27], s[42:43]
	s_cbranch_execz .LBB0_287
	v_lshl_add_u64 v[16:17], v[98:99], 0, s[10:11]
	v_readlane_b32 s6, v247, 55
	v_lshlrev_b64 v[16:17], 6, v[16:17]
	v_readlane_b32 s7, v247, 56
	v_mov_b32_e32 v29, v153
	s_nop 0
	v_lshl_add_u64 v[16:17], s[6:7], 0, v[16:17]
	v_lshl_add_u64 v[16:17], v[16:17], 0, v[28:29]
	global_load_dwordx4 v[16:19], v[16:17], off nt
.LBB0_287:
	s_or_b64 exec, exec, s[26:27]
	v_readlane_b32 s6, v247, 42
	v_sub_u32_e32 v7, 63, v96
	v_readlane_b32 s7, v247, 43
	v_sub_u32_e32 v29, 31, v96
	v_add_u32_e32 v30, 32, v96
	v_cndmask_b32_e64 v7, v7, v96, s[6:7]
	v_cndmask_b32_e64 v29, v29, v30, s[6:7]
	v_lshlrev_b32_e32 v30, 7, v7
	v_and_b32_e32 v7, 48, v7
	v_add_u32_e32 v7, v7, v5
	v_and_b32_e32 v7, 56, v7
	v_lshlrev_b32_e32 v7, 1, v7
	v_add3_u32 v109, 0, v30, v7
	v_lshlrev_b32_e32 v7, 7, v29
	v_and_b32_e32 v29, 48, v29
	v_add_u32_e32 v29, v29, v5
	v_and_b32_e32 v29, 56, v29
	v_lshlrev_b32_e32 v29, 1, v29
	v_add3_u32 v110, 0, v7, v29
	v_sub_u32_e32 v7, 63, v98
	v_cndmask_b32_e64 v65, v7, v98, s[6:7]
	s_waitcnt vmcnt(3)
	ds_write_b128 v109, v[8:11] offset:38144
	s_waitcnt vmcnt(2)
	ds_write_b128 v109, v[12:15] offset:46336
	s_waitcnt vmcnt(1)
	ds_write_b128 v110, v[20:23] offset:38144
	s_waitcnt vmcnt(0)
	ds_write_b128 v110, v[24:27] offset:46336
	s_and_saveexec_b64 s[26:27], s[42:43]
	v_lshlrev_b32_e32 v7, 5, v65
	v_add3_u32 v7, 0, v7, v28
	ds_write_b128 v7, v[16:19] offset:54528
	s_or_b64 exec, exec, s[26:27]
	v_readlane_b32 s6, v247, 58
	v_readlane_b32 s7, v247, 59
	v_mov_b64_e32 v[30:31], s[12:13]
	s_nop 0
	v_lshl_add_u64 v[28:29], v[96:97], 0, s[6:7]
	v_mad_u64_u32 v[30:31], s[6:7], v28, s1, v[30:31]
	v_mad_i32_i24 v31, v29, s1, v31
	v_lshl_add_u64 v[36:37], v[30:31], 0, v[152:153]
	v_add_co_u32_e32 v40, vcc, 0x2c000, v36
	global_load_dwordx4 v[28:31], v[36:37], off nt
	global_load_dwordx4 v[32:35], v[36:37], off offset:512 nt
	v_addc_co_u32_e32 v41, vcc, 0, v37, vcc
	global_load_dwordx4 v[36:39], v[40:41], off nt
	s_nop 0
	global_load_dwordx4 v[40:43], v[40:41], off offset:512 nt
	s_and_saveexec_b64 s[6:7], s[44:45]
	s_xor_b64 s[26:27], exec, s[6:7]
	v_mov_b32_e32 v99, v153
	s_or_saveexec_b64 s[26:27], s[26:27]
	s_xor_b64 exec, exec, s[26:27]
	s_cbranch_execz .LBB0_293
	v_readlane_b32 s6, v247, 58
	v_readlane_b32 s7, v247, 59
	v_lshlrev_b32_e32 v46, 1, v6
	v_mov_b32_e32 v47, v153
	v_lshl_add_u64 v[44:45], v[98:99], 0, s[6:7]
	v_readlane_b32 s6, v247, 55
	v_lshlrev_b64 v[44:45], 6, v[44:45]
	v_readlane_b32 s7, v247, 56
	s_nop 1
	v_lshl_add_u64 v[44:45], s[6:7], 0, v[44:45]
	v_lshl_add_u64 v[44:45], v[44:45], 0, v[46:47]
	global_load_dwordx4 v[44:47], v[44:45], off nt
; #define GLA_BAR() do { asm volatile("s_waitcnt lgkmcnt(0)" ::: "memory"); __builtin_amdgcn_s_barrier(); asm volatile("" ::: "memory"); } while (0)
; #define ST8_(pp, v) do { *(u32x2*)(pp) = (u32x2){(v).x, (v).y}; *(u32x2*)((pp) + 4) = (u32x2){(v).z, (v).w}; } while (0)
; __device__ __forceinline__ void gla_load_v(const GlaPrepCtx& c, int si, GlaRegs& R) {
;     const int dir = c.dir; const size_t t0 = (size_t)(c.b * SEQ + CHUNK(si) * 64); const bf16_t* vr = c.Z + (t0 + c.vrow) * ZW + ZV + c.h * 128 + c.vcs;
;     R.v0 = *(const u32x4*)vr; R.v1 = *(const u32x4*)(vr + (size_t)16 * ZW); R.v2 = *(const u32x4*)(vr + (size_t)32 * ZW); R.v3 = *(const u32x4*)(vr + (size_t)48 * ZW);
; }
; __device__ __forceinline__ void gla_store_qka(const GlaPrepCtx& c, const GlaRegs& R) {
;     const int dir = c.dir; const int r0_ = POS(c.lrow), r1_ = POS(c.lrow + 32);
;     *(u32x4*)(c.qraw + r0_ * 64 + ROT(r0_, c.lcs)) = R.q0; *(u32x4*)(c.kraw + r0_ * 64 + ROT(r0_, c.lcs)) = R.k0; *(u32x4*)(c.qraw + r1_ * 64 + ROT(r1_, c.lcs)) = R.q1; *(u32x4*)(c.kraw + r1_ * 64 + ROT(r1_, c.lcs)) = R.k1;
;     if (c.tid < 128) *(u32x4*)(c.araw + POS(c.arow) * 16 + c.acs) = R.a;
; }
; __device__ __forceinline__ void gla_store_v(const GlaPrepCtx& c, const GlaRegs& R) {
;     const int dir = c.dir;
;     ST8_(c.vraw + POS(c.vrow) * VP + c.vcs, R.v0); ST8_(c.vraw + POS(c.vrow + 16) * VP + c.vcs, R.v1); ST8_(c.vraw + POS(c.vrow + 32) * VP + c.vcs, R.v2); ST8_(c.vraw + POS(c.vrow + 48) * VP + c.vcs, R.v3);
; __device__ __forceinline__ void gla_prep(const Params& p, unsigned char* lds, int l, int item, int tid) {
;     ...
;     gla_load_qka(c, 1, RB); gla_load_v(c, 0, RB);
;     GLA_BAR();
;     for (int s = -1; s < 63; s += 2) { gla_prep_step(c, s, RA, RB); gla_prep_step(c, s + 1, RB, RA); }
.LBB0_293:
	s_or_b64 exec, exec, s[26:27]
	v_ashrrev_i32_e32 v100, 4, v106
	v_ashrrev_i32_e32 v101, 31, v100
	v_lshl_add_u64 v[48:49], v[100:101], 0, s[10:11]
	v_readlane_b32 s10, v246, 35
	v_readlane_b32 s11, v246, 36
	v_lshlrev_b32_e32 v5, 1, v5
	v_and_b32_e32 v66, 0xf0, v5
	v_mov_b64_e32 v[50:51], s[10:11]
	v_mad_u64_u32 v[50:51], s[6:7], v48, s1, v[50:51]
	v_mad_i32_i24 v51, v49, s1, v51
	v_mov_b32_e32 v67, v153
	v_lshl_add_u64 v[56:57], v[50:51], 0, v[66:67]
	s_mov_b32 s6, 0x16000
	v_add_co_u32_e32 v48, vcc, s6, v56
	s_mov_b32 s6, 0x2c000
	s_nop 0
	v_addc_co_u32_e32 v49, vcc, 0, v57, vcc
	v_add_co_u32_e32 v58, vcc, s6, v56
	s_mov_b32 s6, 0x42000
	s_nop 0
	v_addc_co_u32_e32 v59, vcc, 0, v57, vcc
	v_add_co_u32_e32 v60, vcc, s6, v56
	global_load_dwordx4 v[52:55], v[56:57], off offset:1024 nt
	s_nop 0
	global_load_dwordx4 v[48:51], v[48:49], off offset:1024 nt
	v_addc_co_u32_e32 v61, vcc, 0, v57, vcc
	global_load_dwordx4 v[56:59], v[58:59], off offset:1024 nt
	s_nop 0
	global_load_dwordx4 v[60:63], v[60:61], off offset:1024 nt
	s_lshl_b32 s8, s14, 7
	s_add_i32 s6, s8, s2
	s_ashr_i32 s7, s6, 31
	s_lshl_b64 s[6:7], s[6:7], 8
	s_add_u32 s26, s86, s6
	v_readlane_b32 s6, v247, 40
	s_addc_u32 s27, s87, s7
	s_add_i32 s6, s8, s6
	v_add_lshl_u32 v71, s4, v107, 4
	v_and_b32_e32 v72, 12, v111
	s_ashr_i32 s7, s6, 31
	v_and_or_b32 v71, v71, 48, v72
	v_lshlrev_b32_e32 v72, 5, v108
	s_lshl_b64 s[6:7], s[6:7], 8
	v_and_b32_e32 v72, 0x180, v72
	s_add_u32 s28, s86, s6
	v_lshlrev_b32_e32 v71, 1, v71
	v_lshl_or_b32 v72, v107, 11, v72
	s_movk_i32 s4, 0x90
	s_addc_u32 s29, s87, s7
	v_and_or_b32 v69, v111, 48, v112
	v_add3_u32 v111, 0, v71, v72
	v_mul_lo_u32 v71, v64, s4
	s_movk_i32 s4, 0xff74
	s_cmp_lt_u32 s5, 64
	v_mul_lo_u32 v64, v64, s4
	v_readlane_b32 s4, v247, 42
	v_readlane_b32 s5, v247, 43
	v_sub_u32_e32 v72, 47, v100
	v_add_u32_e32 v73, 16, v100
	v_lshl_add_u64 v[102:103], s[12:13], 0, v[152:153]
	v_lshlrev_b32_e32 v152, 1, v6
	v_readlane_b32 s6, v247, 55
	v_lshlrev_b32_e32 v65, 5, v65
	v_cndmask_b32_e64 v72, v72, v73, s[4:5]
	v_sub_u32_e32 v73, 31, v100
	v_add_u32_e32 v74, 32, v100
	v_readlane_b32 s7, v247, 56
	v_add3_u32 v113, 0, v65, v152
	v_sub_u32_e32 v65, 63, v100
	v_cndmask_b32_e64 v73, v73, v74, s[4:5]
	v_sub_u32_e32 v74, 15, v100
	v_add_u32_e32 v75, 48, v100
	s_waitcnt lgkmcnt(0)
	s_barrier
	v_lshl_add_u64 v[104:105], s[6:7], 0, v[152:153]
	v_cndmask_b32_e64 v65, v65, v100, s[4:5]
	s_movk_i32 s6, 0x108
	v_cndmask_b32_e64 v74, v74, v75, s[4:5]
	v_add_u32_e32 v68, 0, v66
	v_lshl_add_u32 v70, v107, 4, 0
	v_lshlrev_b32_e32 v69, 5, v69
	v_add_u32_e32 v71, 0, v71
	v_mul_lo_u32 v65, v65, s6
	v_mul_lo_u32 v72, v72, s6
	v_mul_lo_u32 v73, v73, s6
	v_mul_lo_u32 v74, v74, s6
	s_mov_b32 s4, 0xdd00
	s_cselect_b64 s[36:37], -1, 0
	v_mov_b32_e32 v5, v4
	v_mov_b32_e32 v6, v4
	v_mov_b32_e32 v7, v4
	v_cmp_eq_u32_e64 s[44:45], 0, v107
	v_cmp_lt_u32_e64 s[46:47], 1, v107
	v_lshl_add_u32 v112, v107, 5, v71
	v_cmp_eq_u32_e64 s[48:49], 0, v106
	v_lshl_add_u64 v[106:107], s[10:11], 0, v[66:67]
	s_mov_b32 s5, -1
	v_add_u32_e32 v114, v70, v69
	v_add_u32_e32 v115, v71, v64
	v_add3_u32 v116, v68, v65, s4
	v_add3_u32 v117, v68, v72, s4
	v_add3_u32 v118, v68, v73, s4
	v_add3_u32 v119, v68, v74, s4
	s_branch .LBB0_296

; __device__ __forceinline__ void gla_load_qka(const GlaPrepCtx& c, int si, GlaRegs& R) {
;     const int dir = c.dir; const size_t t0 = (size_t)(c.b * SEQ + CHUNK(si) * 64); const bf16_t* zr = c.Z + (t0 + c.lrow) * ZW + c.h * 64 + c.lcs;
;     R.q0 = *(const u32x4*)(zr + ZQ); R.k0 = *(const u32x4*)(zr + ZK); R.q1 = *(const u32x4*)(zr + (size_t)32 * ZW + ZQ); R.k1 = *(const u32x4*)(zr + (size_t)32 * ZW + ZK);
;     if (c.tid < 128) R.a = *(const u32x4*)(c.DEC + (t0 + c.arow) * 32 + dir * 16 + c.acs);
; __device__ __forceinline__ void gla_prep_step(const GlaPrepCtx& c, int s, GlaRegs& LD, GlaRegs& ST) {
;     ...
;     if (s + 3 < 64) gla_load_qka(c, s + 3, LD);
.LBB0_302:
	s_cmp_lt_i32 s5, 61
	s_cselect_b64 s[54:55], -1, 0
	s_cmp_gt_i32 s5, 60
	s_cselect_b64 s[38:39], -1, 0
	s_and_b64 vcc, exec, s[38:39]
	s_cbranch_vccnz .LBB0_306
	v_readlane_b32 s6, v247, 42
	s_add_i32 s4, s5, 3
	s_sub_i32 s8, 60, s5
	v_readlane_b32 s7, v247, 43
	s_and_b64 s[6:7], s[6:7], exec
	s_cselect_b32 s4, s4, s8
	s_lshl_b32 s4, s4, 6
	v_readlane_b32 s6, v247, 57
	s_add_i32 s64, s4, s6
	s_ashr_i32 s65, s64, 31
	v_lshl_add_u64 v[8:9], s[64:65], 0, v[96:97]
	v_mad_u64_u32 v[20:21], s[6:7], v8, s1, v[102:103]
	v_mad_i32_i24 v21, v9, s1, v21
	v_add_co_u32_e32 v24, vcc, 0x2c000, v20
	global_load_dwordx4 v[8:11], v[20:21], off nt
	global_load_dwordx4 v[12:15], v[20:21], off offset:512 nt
	v_addc_co_u32_e32 v25, vcc, 0, v21, vcc
	global_load_dwordx4 v[20:23], v[24:25], off nt
	s_nop 0
	global_load_dwordx4 v[24:27], v[24:25], off offset:512 nt
	s_and_saveexec_b64 s[70:71], s[42:43]
	s_cbranch_execz .LBB0_305
	v_lshl_add_u64 v[16:17], v[98:99], 0, s[64:65]
	v_lshlrev_b64 v[16:17], 6, v[16:17]
	v_lshl_add_u64 v[16:17], v[104:105], 0, v[16:17]
	global_load_dwordx4 v[16:19], v[16:17], off nt

; __device__ __forceinline__ void gla_load_v(const GlaPrepCtx& c, int si, GlaRegs& R) {
;     const int dir = c.dir; const size_t t0 = (size_t)(c.b * SEQ + CHUNK(si) * 64); const bf16_t* vr = c.Z + (t0 + c.vrow) * ZW + ZV + c.h * 128 + c.vcs;
;     R.v0 = *(const u32x4*)vr; R.v1 = *(const u32x4*)(vr + (size_t)16 * ZW); R.v2 = *(const u32x4*)(vr + (size_t)32 * ZW); R.v3 = *(const u32x4*)(vr + (size_t)48 * ZW);
; __device__ __forceinline__ void gla_prep_step(const GlaPrepCtx& c, int s, GlaRegs& LD, GlaRegs& ST) {
;     ...
;     if (s + 3 < 64) gla_load_qka(c, s + 3, LD);
;     if (s + 2 < 64) gla_load_v(c, s + 2, LD);
;     unsigned rq[8], rk[8], ro[8], rko[8]; float rdec = 0.f;
;     if (s < 63) {
;         float la[16];
; #pragma unroll
;         for (int cb = 0; cb < 4; ++cb) { const int pr = 16 * (lr >> 2) + 4 * cb + (lr & 3);
;             u32x4 aw = (u32x4){0u, 0u, 0u, 0u}; if (q4 < 2) aw = *(const u32x4*)(c.araw + pr * 16 + 8 * q4);
;             f32x4 d = (f32x4){c.bias, c.bias, c.bias, c.bias};
;             d = __builtin_amdgcn_mfma_f32_16x16x32_bf16(__builtin_bit_cast(bf16x8, aw), c.w2f, d, 0, 0, 0);
; #pragma unroll
;             for (int jj = 0; jj < 4; ++jj) la[4 * cb + jj] = logsig2(d[jj]); }
; #pragma unroll
;         for (int i = 1; i < 16; ++i) la[i] += la[i - 1];
;         const float tq = la[15]; float inc = tq;
;         { const float t1 = __shfl_up(inc, 16); if (q4 >= 1) inc += t1; const float t2 = __shfl_up(inc, 32); if (q4 >= 2) inc += t2; }
;         const float off = inc - tq;
;         const float tot = __shfl(inc, lr + 48);
;         const float bmid = __shfl(off + la[0], lr + 32);
;         const float emid = __builtin_amdgcn_exp2f(bmid), etm = __builtin_amdgcn_exp2f(tot - bmid);
;         rdec = __builtin_amdgcn_exp2f(tot);
.LBB0_306:
	v_readlane_b32 s6, v247, 42
	s_add_i32 s4, s5, 2
	s_sub_i32 s8, 61, s5
	v_readlane_b32 s7, v247, 43
	s_and_b64 s[6:7], s[6:7], exec
	s_cselect_b32 s6, s4, s8
	s_lshl_b32 s6, s6, 6
	v_readlane_b32 s7, v247, 57
	s_add_i32 s6, s6, s7
	s_ashr_i32 s7, s6, 31
	v_lshl_add_u64 v[64:65], s[6:7], 0, v[100:101]
	v_mad_u64_u32 v[72:73], s[6:7], v64, s1, v[106:107]
	s_mov_b32 s6, 0x16000
	v_mad_i32_i24 v73, v65, s1, v73
	v_add_co_u32_e32 v64, vcc, s6, v72
	v_mov_b32_e32 v84, 0
	s_nop 0
	v_addc_co_u32_e32 v65, vcc, 0, v73, vcc
	v_add_co_u32_e32 v68, vcc, 0x2c000, v72
	v_mov_b32_e32 v80, 0
	s_nop 0
	v_addc_co_u32_e32 v69, vcc, 0, v73, vcc
	v_add_co_u32_e32 v74, vcc, 0x42000, v72
	global_load_dwordx4 v[64:67], v[64:65], off offset:1024 nt
	s_nop 0
	global_load_dwordx4 v[68:71], v[68:69], off offset:1024 nt
	v_addc_co_u32_e32 v75, vcc, 0, v73, vcc
	global_load_dwordx4 v[76:79], v[72:73], off offset:1024 nt
	s_nop 0
	global_load_dwordx4 v[72:75], v[74:75], off offset:1024 nt
	v_mov_b32_e32 v81, 0
	v_mov_b32_e32 v82, 0
	v_mov_b32_e32 v83, 0
	s_and_saveexec_b64 s[64:65], s[40:41]
	ds_read_b128 v[80:83], v114 offset:54528
	s_or_b64 exec, exec, s[64:65]
	s_waitcnt lgkmcnt(0)
	v_mfma_f32_16x16x32_bf16 v[80:83], v[80:83], v[0:3], v[4:7]
	v_mov_b32_e32 v85, 0
	v_mov_b32_e32 v86, 0
	v_mov_b32_e32 v87, 0
	s_and_saveexec_b64 s[64:65], s[40:41]
	ds_read_b128 v[84:87], v114 offset:54656
	s_or_b64 exec, exec, s[64:65]
	s_waitcnt lgkmcnt(0)
	v_mfma_f32_16x16x32_bf16 v[88:91], v[84:87], v[0:3], v[4:7]
	v_mov_b32_e32 v84, 0
	v_mov_b32_e32 v92, 0
	v_mov_b32_e32 v93, 0
	v_mov_b32_e32 v94, 0
	v_mov_b32_e32 v95, 0
	s_and_saveexec_b64 s[64:65], s[40:41]
	ds_read_b128 v[92:95], v114 offset:54784
	s_or_b64 exec, exec, s[64:65]
	s_waitcnt lgkmcnt(0)
	v_mfma_f32_16x16x32_bf16 v[92:95], v[92:95], v[0:3], v[4:7]
	v_mov_b32_e32 v85, 0
	v_mov_b32_e32 v86, 0
	v_mov_b32_e32 v87, 0
	s_and_saveexec_b64 s[64:65], s[40:41]
	ds_read_b128 v[84:87], v114 offset:54912
	s_or_b64 exec, exec, s[64:65]
	v_mul_f32_e32 v80, 0xbfb8aa3b, v80
	v_exp_f32_e32 v80, v80
	v_mul_f32_e32 v81, 0xbfb8aa3b, v81
	v_exp_f32_e32 v81, v81
	v_mul_f32_e32 v88, 0xbfb8aa3b, v88
	v_add_f32_e32 v80, 1.0, v80
	v_log_f32_e32 v123, v80
	v_add_f32_e32 v80, 1.0, v81
	v_mul_f32_e32 v81, 0xbfb8aa3b, v82
	v_log_f32_e32 v80, v80
	v_exp_f32_e32 v81, v81
	v_mul_f32_e32 v82, 0xbfb8aa3b, v83
	v_exp_f32_e32 v82, v82
	v_exp_f32_e32 v88, v88
	v_mul_f32_e32 v89, 0xbfb8aa3b, v89
	v_exp_f32_e32 v89, v89
	v_mul_f32_e32 v90, 0xbfb8aa3b, v90
	v_exp_f32_e32 v90, v90
	v_mul_f32_e32 v91, 0xbfb8aa3b, v91
	v_mul_f32_e32 v124, 0xbd800000, v80
	v_add_f32_e32 v80, 1.0, v81
	v_mul_f32_e32 v92, 0xbfb8aa3b, v92
	v_exp_f32_e32 v91, v91
	v_log_f32_e32 v120, v80
	v_add_f32_e32 v121, 1.0, v82
	s_waitcnt lgkmcnt(0)
	v_mfma_f32_16x16x32_bf16 v[80:83], v[84:87], v[0:3], v[4:7]
	v_exp_f32_e32 v92, v92
	v_mul_f32_e32 v93, 0xbfb8aa3b, v93
	v_add_f32_e32 v88, 1.0, v88
	v_log_f32_e32 v84, v121
	v_exp_f32_e32 v93, v93
	v_mul_f32_e32 v94, 0xbfb8aa3b, v94
	v_log_f32_e32 v88, v88
	v_add_f32_e32 v89, 1.0, v89
	v_exp_f32_e32 v94, v94
	v_mul_f32_e32 v95, 0xbfb8aa3b, v95
	v_log_f32_e32 v89, v89
	v_add_f32_e32 v90, 1.0, v90
	v_fmac_f32_e32 v124, 0xbd800000, v123
	v_exp_f32_e32 v95, v95
	v_log_f32_e32 v90, v90
	v_add_f32_e32 v91, 1.0, v91
	v_mul_f32_e32 v80, 0xbfb8aa3b, v80
	v_fmamk_f32 v125, v120, 0xbd800000, v124
	v_add_f32_e32 v92, 1.0, v92
	v_log_f32_e32 v91, v91
	v_exp_f32_e32 v80, v80
	v_mul_f32_e32 v81, 0xbfb8aa3b, v81
	v_fmamk_f32 v126, v84, 0xbd800000, v125
	v_add_f32_e32 v93, 1.0, v93
	v_log_f32_e32 v92, v92
	v_exp_f32_e32 v81, v81
	v_mul_f32_e32 v82, 0xbfb8aa3b, v82
	v_fmamk_f32 v127, v88, 0xbd800000, v126
	v_log_f32_e32 v93, v93
	v_add_f32_e32 v94, 1.0, v94
	v_exp_f32_e32 v82, v82
	v_fmamk_f32 v132, v89, 0xbd800000, v127
	v_log_f32_e32 v94, v94
	v_add_f32_e32 v95, 1.0, v95
	v_fmamk_f32 v133, v90, 0xbd800000, v132
	v_log_f32_e32 v95, v95
	v_add_f32_e32 v80, 1.0, v80
	v_mul_f32_e32 v83, 0xbfb8aa3b, v83
	v_fmamk_f32 v136, v91, 0xbd800000, v133
	v_log_f32_e32 v80, v80
	v_add_f32_e32 v81, 1.0, v81
	v_exp_f32_e32 v83, v83
	v_fmamk_f32 v137, v92, 0xbd800000, v136
	v_log_f32_e32 v81, v81
	v_add_f32_e32 v82, 1.0, v82
	v_fmamk_f32 v138, v93, 0xbd800000, v137
	v_log_f32_e32 v82, v82
	v_fmamk_f32 v139, v94, 0xbd800000, v138
	v_fmamk_f32 v141, v95, 0xbd800000, v139
	v_add_f32_e32 v83, 1.0, v83
	v_fmamk_f32 v142, v80, 0xbd800000, v141
	v_log_f32_e32 v83, v83
	v_fmamk_f32 v81, v81, 0xbd800000, v142
	v_fmamk_f32 v143, v82, 0xbd800000, v81
	v_add_u32_e32 v80, -16, v209
	v_and_b32_e32 v82, 64, v209
	v_cmp_lt_i32_e32 vcc, v80, v82
	v_fmamk_f32 v144, v83, 0xbd800000, v143
	v_subrev_u32_e32 v83, 32, v209
	v_cndmask_b32_e32 v80, v80, v209, vcc
	v_lshlrev_b32_e32 v120, 2, v80
	ds_bpermute_b32 v80, v120, v144
	v_cmp_lt_i32_e32 vcc, v83, v82
	v_or_b32_e32 v82, v82, v108
	v_lshlrev_b32_e32 v122, 2, v82
	v_cndmask_b32_e32 v83, v83, v209, vcc
	s_waitcnt lgkmcnt(0)
	v_add_f32_e32 v80, v144, v80
	v_cndmask_b32_e64 v80, v80, v144, s[44:45]
	v_lshlrev_b32_e32 v121, 2, v83
	ds_bpermute_b32 v83, v121, v80
	s_waitcnt lgkmcnt(0)
	v_add_f32_e32 v83, v80, v83
	v_cndmask_b32_e64 v80, v80, v83, s[46:47]
	v_sub_f32_e32 v145, v80, v144
	v_fmamk_f32 v90, v123, 0xbd800000, v145
	ds_bpermute_b32 v123, v122, v90 offset:128
	ds_bpermute_b32 v80, v122, v80 offset:192
	v_add_f32_e32 v91, v124, v145
	v_add_f32_e32 v81, v81, v145
	s_waitcnt lgkmcnt(1)
	v_sub_f32_e32 v91, v91, v123
	v_sub_f32_e32 v90, v90, v123
	v_exp_f32_e32 v93, v91
	s_waitcnt lgkmcnt(0)
; #define LAS __attribute__((address_space(3)))
; __device__ __forceinline__ unsigned cvt_pk_bf16(float lo, float hi) { unsigned r; asm volatile("v_cvt_pk_bf16_f32 %0, %1, %2" : "=v"(r) : "v"(lo), "v"(hi)); return r; }
; __device__ __forceinline__ float bf2f(unsigned short b) { return __uint_as_float(((unsigned)b) << 16); }
; #define GLA_BAR() do { asm volatile("s_waitcnt lgkmcnt(0)" ::: "memory"); __builtin_amdgcn_s_barrier(); asm volatile("" ::: "memory"); } while (0)
; __device__ __forceinline__ void gla_prep_step(const GlaPrepCtx& c, int s, GlaRegs& LD, GlaRegs& ST) {
;     ...
;         typedef short s4v __attribute__((ext_vector_type(4)));
;         s4v qt[4], kt[4];
;         { const int trow = 16 * q4 + (lr >> 2), tcol = ((16 * wid + 16 * q4) & 63) + 4 * (lr & 3);
; #pragma unroll
;           for (int t = 0; t < 4; ++t) { qt[t] = __builtin_amdgcn_ds_read_tr16_b64_v4i16((LAS s4v*)(c.qraw + (trow + 4 * t) * 64 + tcol)); kt[t] = __builtin_amdgcn_ds_read_tr16_b64_v4i16((LAS s4v*)(c.kraw + (trow + 4 * t) * 64 + tcol)); } }
; #pragma unroll
;         for (int i = 0; i < 16; i += 2) {
;             const float x0 = off + la[i] - bmid, x1 = off + la[i + 1] - bmid;
;             const float e10 = __builtin_amdgcn_exp2f(x0), e20 = __builtin_amdgcn_exp2f(-x0), e11 = __builtin_amdgcn_exp2f(x1), e21 = __builtin_amdgcn_exp2f(-x1);
;             const float q0 = bf2f((unsigned short)qt[i >> 2][i & 3]) * e10, q1 = bf2f((unsigned short)qt[i >> 2][(i & 3) + 1]) * e11;
;             const float k0 = bf2f((unsigned short)kt[i >> 2][i & 3]) * e20, k1 = bf2f((unsigned short)kt[i >> 2][(i & 3) + 1]) * e21;
;             rq[i >> 1] = cvt_pk_bf16(q0, q1); rk[i >> 1] = cvt_pk_bf16(k0, k1); ro[i >> 1] = cvt_pk_bf16(q0 * emid, q1 * emid); rko[i >> 1] = cvt_pk_bf16(k0 * etm, k1 * etm);
;         }
;     }
;     GLA_BAR();
	v_sub_f32_e32 v82, v80, v123
	v_exp_f32_e32 v92, v90
	v_exp_f32_e64 v90, -v90
	v_exp_f32_e32 v146, v82
	ds_read_b64_tr_b16 v[82:83], v111 offset:38144
	ds_read_b64_tr_b16 v[84:85], v111 offset:38656
	ds_read_b64_tr_b16 v[94:95], v111 offset:39168
	ds_read_b64_tr_b16 v[130:131], v111 offset:39680
	ds_read_b64_tr_b16 v[86:87], v111 offset:46336
	ds_read_b64_tr_b16 v[88:89], v111 offset:46848
	ds_read_b64_tr_b16 v[128:129], v111 offset:47360
	ds_read_b64_tr_b16 v[134:135], v111 offset:47872
	v_exp_f32_e32 v147, v123
	v_exp_f32_e64 v91, -v91
	s_waitcnt lgkmcnt(7)
	v_lshlrev_b32_e32 v124, 16, v82
	v_and_b32_e32 v82, 0xffff0000, v82
	v_mul_f32_e32 v93, v93, v82
	s_waitcnt lgkmcnt(3)
	v_lshlrev_b32_e32 v82, 16, v86
	v_mul_f32_e32 v92, v92, v124
	v_mul_f32_e32 v124, v90, v82
	v_and_b32_e32 v82, 0xffff0000, v86
	v_mul_f32_e32 v91, v91, v82
	v_cvt_pk_bf16_f32 v82, v92, v93
	v_mul_f32_e32 v90, v147, v92
	v_mul_f32_e32 v92, v147, v93
	v_cvt_pk_bf16_f32 v86, v124, v91
	v_cvt_pk_bf16_f32 v90, v90, v92
	v_mul_f32_e32 v92, v146, v124
	v_mul_f32_e32 v91, v146, v91
	v_cvt_pk_bf16_f32 v124, v92, v91
	v_add_f32_e32 v92, v126, v145
	v_add_f32_e32 v91, v125, v145
	v_sub_f32_e32 v92, v92, v123
	v_sub_f32_e32 v91, v91, v123
	v_exp_f32_e32 v125, v92
	v_exp_f32_e32 v93, v91
	v_exp_f32_e64 v91, -v91
	v_exp_f32_e64 v92, -v92
	v_lshlrev_b32_e32 v126, 16, v83
	v_and_b32_e32 v83, 0xffff0000, v83
	v_mul_f32_e32 v125, v125, v83
	v_lshlrev_b32_e32 v83, 16, v87
	v_mul_f32_e32 v93, v93, v126
	v_mul_f32_e32 v126, v91, v83
	v_and_b32_e32 v83, 0xffff0000, v87
	v_mul_f32_e32 v92, v92, v83
	v_cvt_pk_bf16_f32 v83, v93, v125
	v_mul_f32_e32 v91, v147, v93
	v_mul_f32_e32 v93, v147, v125
	v_cvt_pk_bf16_f32 v87, v126, v92
	v_cvt_pk_bf16_f32 v91, v91, v93
	v_mul_f32_e32 v93, v146, v126
	v_mul_f32_e32 v92, v146, v92
	v_cvt_pk_bf16_f32 v125, v93, v92
	v_add_f32_e32 v93, v132, v145
	v_add_f32_e32 v92, v127, v145
	v_sub_f32_e32 v93, v93, v123
	v_sub_f32_e32 v92, v92, v123
	v_exp_f32_e32 v127, v93
	v_exp_f32_e32 v126, v92
	v_exp_f32_e64 v92, -v92
	v_exp_f32_e64 v93, -v93
	v_lshlrev_b32_e32 v132, 16, v84
	v_and_b32_e32 v84, 0xffff0000, v84
	v_mul_f32_e32 v127, v127, v84
	s_waitcnt lgkmcnt(2)
	v_lshlrev_b32_e32 v84, 16, v88
	v_mul_f32_e32 v126, v126, v132
	v_mul_f32_e32 v132, v92, v84
	v_and_b32_e32 v84, 0xffff0000, v88
	v_mul_f32_e32 v93, v93, v84
	v_cvt_pk_bf16_f32 v84, v126, v127
	v_mul_f32_e32 v92, v147, v126
	v_mul_f32_e32 v126, v147, v127
	v_cvt_pk_bf16_f32 v88, v132, v93
	v_cvt_pk_bf16_f32 v92, v92, v126
	v_mul_f32_e32 v126, v146, v132
	v_mul_f32_e32 v93, v146, v93
	v_add_f32_e32 v127, v136, v145
	v_cvt_pk_bf16_f32 v126, v126, v93
	v_add_f32_e32 v93, v133, v145
	v_sub_f32_e32 v127, v127, v123
	v_sub_f32_e32 v93, v93, v123
	v_exp_f32_e32 v133, v127
	v_exp_f32_e32 v132, v93
	v_exp_f32_e64 v93, -v93
	v_exp_f32_e64 v127, -v127
	v_lshlrev_b32_e32 v136, 16, v85
	v_and_b32_e32 v85, 0xffff0000, v85
	v_mul_f32_e32 v133, v133, v85
	v_lshlrev_b32_e32 v85, 16, v89
	v_mul_f32_e32 v132, v132, v136
	v_mul_f32_e32 v136, v93, v85
	v_and_b32_e32 v85, 0xffff0000, v89
	v_mul_f32_e32 v127, v127, v85
	v_cvt_pk_bf16_f32 v85, v132, v133
	v_mul_f32_e32 v93, v147, v132
	v_mul_f32_e32 v132, v147, v133
	v_cvt_pk_bf16_f32 v89, v136, v127
	v_cvt_pk_bf16_f32 v93, v93, v132
	v_mul_f32_e32 v132, v146, v136
	v_mul_f32_e32 v127, v146, v127
	v_add_f32_e32 v133, v138, v145
	v_cvt_pk_bf16_f32 v127, v132, v127
	v_add_f32_e32 v132, v137, v145
	v_sub_f32_e32 v133, v133, v123
	v_sub_f32_e32 v132, v132, v123
	v_exp_f32_e32 v137, v133
	v_exp_f32_e32 v136, v132
	v_exp_f32_e64 v133, -v133
	v_exp_f32_e64 v132, -v132
	v_lshlrev_b32_e32 v138, 16, v94
	v_and_b32_e32 v94, 0xffff0000, v94
	v_mul_f32_e32 v94, v137, v94
	s_waitcnt lgkmcnt(1)
	v_lshlrev_b32_e32 v137, 16, v128
	v_and_b32_e32 v128, 0xffff0000, v128
	v_mul_f32_e32 v136, v136, v138
	v_mul_f32_e32 v133, v133, v128
	v_mul_f32_e32 v137, v132, v137
	v_cvt_pk_bf16_f32 v128, v136, v94
	v_cvt_pk_bf16_f32 v132, v137, v133
	v_mul_f32_e32 v136, v147, v136
	v_mul_f32_e32 v94, v147, v94
	v_mul_f32_e32 v133, v146, v133
	v_cvt_pk_bf16_f32 v136, v136, v94
	v_mul_f32_e32 v94, v146, v137
	v_cvt_pk_bf16_f32 v140, v94, v133
	v_add_f32_e32 v133, v141, v145
	v_add_f32_e32 v94, v139, v145
	v_sub_f32_e32 v133, v133, v123
	v_sub_f32_e32 v94, v94, v123
	v_exp_f32_e32 v138, v133
	v_exp_f32_e32 v137, v94
	v_exp_f32_e64 v94, -v94
	v_exp_f32_e64 v133, -v133
	v_lshlrev_b32_e32 v139, 16, v95
	v_and_b32_e32 v95, 0xffff0000, v95
	v_mul_f32_e32 v95, v138, v95
	v_lshlrev_b32_e32 v138, 16, v129
	v_mul_f32_e32 v137, v137, v139
	v_mul_f32_e32 v94, v94, v138
	v_and_b32_e32 v129, 0xffff0000, v129
	v_mul_f32_e32 v138, v133, v129
	v_cvt_pk_bf16_f32 v129, v137, v95
	v_cvt_pk_bf16_f32 v133, v94, v138
	v_mul_f32_e32 v137, v147, v137
	v_mul_f32_e32 v95, v147, v95
	v_mul_f32_e32 v94, v146, v94
	v_cvt_pk_bf16_f32 v137, v137, v95
	v_mul_f32_e32 v95, v146, v138
	v_cvt_pk_bf16_f32 v141, v94, v95
	v_add_f32_e32 v94, v142, v145
	v_sub_f32_e32 v81, v81, v123
	v_sub_f32_e32 v94, v94, v123
	v_exp_f32_e32 v138, v81
	v_exp_f32_e32 v95, v94
	v_exp_f32_e64 v94, -v94
	v_exp_f32_e64 v81, -v81
	v_lshlrev_b32_e32 v139, 16, v130
	v_and_b32_e32 v130, 0xffff0000, v130
	v_mul_f32_e32 v138, v138, v130
	s_waitcnt lgkmcnt(0)
	v_lshlrev_b32_e32 v130, 16, v134
	v_mul_f32_e32 v94, v94, v130
	v_and_b32_e32 v130, 0xffff0000, v134
	v_mul_f32_e32 v95, v95, v139
	v_mul_f32_e32 v81, v81, v130
	v_cvt_pk_bf16_f32 v130, v95, v138
	v_cvt_pk_bf16_f32 v134, v94, v81
	v_mul_f32_e32 v138, v147, v138
	v_mul_f32_e32 v94, v146, v94
	v_mul_f32_e32 v95, v147, v95
	v_cvt_pk_bf16_f32 v138, v95, v138
	v_mul_f32_e32 v81, v146, v81
	v_cvt_pk_bf16_f32 v142, v94, v81
	v_add_f32_e32 v94, v144, v145
	v_add_f32_e32 v81, v143, v145
	v_sub_f32_e32 v94, v94, v123
	v_sub_f32_e32 v81, v81, v123
	v_exp_f32_e32 v123, v94
	v_exp_f32_e32 v95, v81
	v_exp_f32_e64 v81, -v81
	v_exp_f32_e64 v94, -v94
	v_lshlrev_b32_e32 v139, 16, v131
	v_and_b32_e32 v131, 0xffff0000, v131
	v_mul_f32_e32 v123, v123, v131
	v_lshlrev_b32_e32 v131, 16, v135
	v_mul_f32_e32 v81, v81, v131
	v_and_b32_e32 v131, 0xffff0000, v135
	v_mul_f32_e32 v95, v95, v139
	v_mul_f32_e32 v94, v94, v131
	v_cvt_pk_bf16_f32 v131, v95, v123
	v_cvt_pk_bf16_f32 v135, v81, v94
	v_mul_f32_e32 v95, v147, v95
	v_mul_f32_e32 v123, v147, v123
	v_cvt_pk_bf16_f32 v139, v95, v123
	v_mul_f32_e32 v81, v146, v81
	v_mul_f32_e32 v94, v146, v94
	v_cvt_pk_bf16_f32 v143, v81, v94
	s_waitcnt lgkmcnt(0)
	s_barrier
; #define GLA_BAR() do { asm volatile("s_waitcnt lgkmcnt(0)" ::: "memory"); __builtin_amdgcn_s_barrier(); asm volatile("" ::: "memory"); } while (0)
; __device__ __forceinline__ void gla_prep_step(const GlaPrepCtx& c, int s, GlaRegs& LD, GlaRegs& ST) {
;     ...
;     GLA_BAR();
;     if (s < 63) {
;         *(u32x4*)(c.qin + ch * GP + 16 * q4) = (u32x4){rq[0], rq[1], rq[2], rq[3]}; *(u32x4*)(c.qin + ch * GP + 16 * q4 + 8) = (u32x4){rq[4], rq[5], rq[6], rq[7]};
;         *(u32x4*)(c.kin + ch * GP + 16 * q4) = (u32x4){rk[0], rk[1], rk[2], rk[3]}; *(u32x4*)(c.kin + ch * GP + 16 * q4 + 8) = (u32x4){rk[4], rk[5], rk[6], rk[7]};
;         *(u32x4*)(c.qout + ch * GP + 16 * q4) = (u32x4){ro[0], ro[1], ro[2], ro[3]}; *(u32x4*)(c.qout + ch * GP + 16 * q4 + 8) = (u32x4){ro[4], ro[5], ro[6], ro[7]};
;         *(u32x4*)(c.koutT + ch * GP + 16 * q4) = (u32x4){rko[0], rko[1], rko[2], rko[3]}; *(u32x4*)(c.koutT + ch * GP + 16 * q4 + 8) = (u32x4){rko[4], rko[5], rko[6], rko[7]};
;         if (q4 == 0) c.decs[ch] = rdec;
;     }
;     if (s + 2 < 64) gla_store_qka(c, ST);
;     if (s + 1 < 64) gla_store_v(c, ST);
;     if (s == 31) {
;         asm volatile("s_waitcnt vmcnt(0)" ::: "memory"); __syncthreads();
;         if (tid == 0) { __builtin_amdgcn_fence(__ATOMIC_RELEASE, "agent"); asm volatile("s_waitcnt vmcnt(0)" ::: "memory"); __hip_atomic_store(c.myflag, 1u, __ATOMIC_RELAXED, __HIP_MEMORY_SCOPE_AGENT); }
	ds_write_b128 v112, v[82:85]
	ds_write_b128 v112, v[128:131] offset:16
	ds_write_b128 v112, v[86:89] offset:9216
	ds_write_b128 v112, v[132:135] offset:9232
	ds_write_b128 v112, v[90:93] offset:18432
	ds_write_b128 v112, v[136:139] offset:18448
	ds_write_b128 v112, v[124:127] offset:27648
	ds_write_b128 v112, v[140:143] offset:27664
	s_and_saveexec_b64 s[64:65], s[44:45]
	v_exp_f32_e32 v80, v80
	ds_write_b32 v115, v80 offset:36864
	s_or_b64 exec, exec, s[64:65]
	s_waitcnt vmcnt(11)
	ds_write_b128 v109, v[28:31] offset:38144
	s_waitcnt vmcnt(10)
	ds_write_b128 v109, v[32:35] offset:46336
	s_waitcnt vmcnt(9)
	ds_write_b128 v110, v[36:39] offset:38144
	s_waitcnt vmcnt(8)
	ds_write_b128 v110, v[40:43] offset:46336
	s_and_saveexec_b64 s[64:65], s[42:43]
	ds_write_b128 v113, v[44:47] offset:54528
	s_or_b64 exec, exec, s[64:65]
	s_cmp_lg_u32 s5, 31
	s_waitcnt vmcnt(7)
	ds_write2_b64 v116, v[52:53], v[54:55] offset1:1
	s_waitcnt vmcnt(6)
	ds_write2_b64 v117, v[48:49], v[50:51] offset1:1
	s_waitcnt vmcnt(5)
	ds_write2_b64 v118, v[56:57], v[58:59] offset1:1
	s_waitcnt vmcnt(4)
	ds_write2_b64 v119, v[60:61], v[62:63] offset1:1
	s_cbranch_scc1 .LBB0_322
	s_waitcnt vmcnt(0)
	s_waitcnt lgkmcnt(0)
	s_barrier
	s_and_saveexec_b64 s[64:65], s[48:49]
	s_cbranch_execz .LBB0_321
	buffer_wbl2 sc1
	s_waitcnt vmcnt(0)
	s_waitcnt vmcnt(0)
	global_store_dword v153, v207, s[26:27] sc1

; __device__ __forceinline__ void gla_load_v(const GlaPrepCtx& c, int si, GlaRegs& R) {
;     const int dir = c.dir; const size_t t0 = (size_t)(c.b * SEQ + CHUNK(si) * 64); const bf16_t* vr = c.Z + (t0 + c.vrow) * ZW + ZV + c.h * 128 + c.vcs;
;     R.v0 = *(const u32x4*)vr; R.v1 = *(const u32x4*)(vr + (size_t)16 * ZW); R.v2 = *(const u32x4*)(vr + (size_t)32 * ZW); R.v3 = *(const u32x4*)(vr + (size_t)48 * ZW);
.LBB0_325:
	v_readlane_b32 s8, v247, 42
	s_add_i32 s7, s5, 3
	s_sub_i32 s5, 60, s5
	v_readlane_b32 s9, v247, 43
	s_and_b64 s[8:9], s[8:9], exec
	s_cselect_b32 s5, s7, s5
	s_lshl_b32 s5, s5, 6
	v_readlane_b32 s7, v247, 57
	s_add_i32 s8, s5, s7
	s_ashr_i32 s9, s8, 31
	v_lshl_add_u64 v[48:49], s[8:9], 0, v[100:101]
	v_mad_u64_u32 v[52:53], s[8:9], v48, s1, v[106:107]
	v_mad_i32_i24 v53, v49, s1, v53
	v_add_co_u32_e32 v48, vcc, 0x16000, v52
	s_nop 1
	v_addc_co_u32_e32 v49, vcc, 0, v53, vcc
	v_add_co_u32_e32 v54, vcc, 0x2c000, v52
	s_nop 1
	v_addc_co_u32_e32 v55, vcc, 0, v53, vcc
	v_add_co_u32_e32 v60, vcc, 0x42000, v52
	global_load_dwordx4 v[48:51], v[48:49], off offset:1024 nt
	s_nop 0
	global_load_dwordx4 v[56:59], v[54:55], off offset:1024 nt
	v_addc_co_u32_e32 v61, vcc, 0, v53, vcc
	global_load_dwordx4 v[52:55], v[52:53], off offset:1024 nt
	s_nop 0
	global_load_dwordx4 v[60:63], v[60:61], off offset:1024 nt

; __device__ __forceinline__ void gla_load_qka(const GlaPrepCtx& c, int si, GlaRegs& R) {
;     const int dir = c.dir; const size_t t0 = (size_t)(c.b * SEQ + CHUNK(si) * 64); const bf16_t* zr = c.Z + (t0 + c.lrow) * ZW + c.h * 64 + c.lcs;
;     R.q0 = *(const u32x4*)(zr + ZQ); R.k0 = *(const u32x4*)(zr + ZK); R.q1 = *(const u32x4*)(zr + (size_t)32 * ZW + ZQ); R.k1 = *(const u32x4*)(zr + (size_t)32 * ZW + ZK);
;     if (c.tid < 128) R.a = *(const u32x4*)(c.DEC + (t0 + c.arow) * 32 + dir * 16 + c.acs);
.LBB0_348:
	v_readlane_b32 s8, v247, 42
	s_add_i32 s7, s5, 4
	s_sub_i32 s10, 59, s5
	v_readlane_b32 s9, v247, 43
	s_and_b64 s[8:9], s[8:9], exec
	s_cselect_b32 s7, s7, s10
	s_lshl_b32 s7, s7, 6
	v_readlane_b32 s8, v247, 57
	s_add_i32 s50, s7, s8
	s_ashr_i32 s51, s50, 31
	v_lshl_add_u64 v[28:29], s[50:51], 0, v[96:97]
	v_mad_u64_u32 v[36:37], s[8:9], v28, s1, v[102:103]
	v_mad_i32_i24 v37, v29, s1, v37
	v_add_co_u32_e32 v40, vcc, 0x2c000, v36
	global_load_dwordx4 v[28:31], v[36:37], off nt
	global_load_dwordx4 v[32:35], v[36:37], off offset:512 nt
	v_addc_co_u32_e32 v41, vcc, 0, v37, vcc
	global_load_dwordx4 v[36:39], v[40:41], off nt
	s_nop 0
	global_load_dwordx4 v[40:43], v[40:41], off offset:512 nt
	s_and_saveexec_b64 s[64:65], s[42:43]
	s_cbranch_execz .LBB0_350
	v_lshl_add_u64 v[44:45], v[98:99], 0, s[50:51]
	v_lshlrev_b64 v[44:45], 6, v[44:45]
	v_lshl_add_u64 v[44:45], v[104:105], 0, v[44:45]
	global_load_dwordx4 v[44:47], v[44:45], off nt
